# v48: v46 + cross-row lane^16/lane^32 all-reduces via v_permlane16_swap/v_permlane32_swap instead of ds_bpermute in passB rf/rb, sum-of-squares and final-norm epilogue
# speedup vs baseline: 1.0051x; 1.0051x over previous
; #define LAS __attribute__((address_space(3)))
; __device__ void passB_unit(const Params& p, LAS unsigned char* lds, int u, bool do_store = true) {
;     ...
;     {
;         f32x4 sacc[4][2];
; #pragma unroll
;         for (int mt = 0; mt < 4; ++mt)
; #pragma unroll
;             for (int nt = 0; nt < 2; ++nt) sacc[mt][nt] = (f32x4){0.f, 0.f, 0.f, 0.f};
; #pragma unroll
;         for (int ks = 0; ks < 8; ++ks) { bf16x8 qf[4];
; #pragma unroll
;             for (int mt = 0; mt < 4; ++mt) qf[mt] = *(const LAS bf16x8*)(Qs + (wt2 * 64 + mt * 16 + fr) * 264 + ks * 32 + fq * 8);
; #pragma unroll
;             for (int mt = 0; mt < 4; ++mt)
; #pragma unroll
;                 for (int nt = 0; nt < 2; ++nt) sacc[mt][nt] = __builtin_amdgcn_mfma_f32_16x16x32_bf16(kfa[ks][nt], qf[mt], sacc[mt][nt], 0, 0, 0); }
.LBB0_549:
	s_or_b64 exec, exec, s[4:5]
	v_lshl_or_b32 v211, v62, 6, v201
	s_movk_i32 s4, 0x210
	v_and_b32_e32 v116, 48, v196
	v_mul_lo_u32 v210, v211, s4
	v_add_u32_e32 v91, 0, v116
	v_add_u32_e32 v253, 0x2100, v210
	v_add_u32_e32 v252, 0x4200, v210
	v_add_u32_e32 v227, 0x6300, v210
	v_add_u32_e32 v217, v91, v210
	v_add_u32_e32 v114, v91, v253
	v_add_u32_e32 v115, v91, v252
	v_add_u32_e32 v91, v91, v227
	s_waitcnt lgkmcnt(0)
	s_barrier
	ds_read_b128 v[60:63], v217
	ds_read_b128 v[68:71], v217 offset:64
	ds_read_b128 v[76:79], v114
	ds_read_b128 v[80:83], v114 offset:64
	ds_read_b128 v[94:97], v115
	ds_read_b128 v[98:101], v115 offset:64
	ds_read_b128 v[106:109], v91
	ds_read_b128 v[110:113], v91 offset:64
	s_waitcnt vmcnt(15) lgkmcnt(7)
	v_mfma_f32_16x16x32_bf16 v[72:75], v[52:55], v[60:63], 0
	s_cmp_lt_i32 s50, 32
	s_cselect_b32 s57, s69, s13
	s_cselect_b32 s58, s68, s12
	s_waitcnt vmcnt(13)
	v_mfma_f32_16x16x32_bf16 v[60:63], v[56:59], v[60:63], 0
	s_lshl_b32 s4, s50, 4
	s_and_b32 s59, s4, 0x1e0
	s_or_b32 s4, s59, s52
	s_waitcnt lgkmcnt(5)
	v_mfma_f32_16x16x32_bf16 v[84:87], v[52:55], v[76:79], 0
	s_lshl_b32 s4, s4, 17
	s_add_u32 s4, s58, s4
	s_addc_u32 s5, s57, 0
	v_mfma_f32_16x16x32_bf16 v[76:79], v[56:59], v[76:79], 0
	v_lshlrev_b32_e32 v89, 13, v223
	s_waitcnt lgkmcnt(3)
	v_mfma_f32_16x16x32_bf16 v[102:105], v[52:55], v[94:97], 0
	v_mfma_f32_16x16x32_bf16 v[94:97], v[56:59], v[94:97], 0
	s_waitcnt lgkmcnt(1)
	v_mfma_f32_16x16x32_bf16 v[52:55], v[52:55], v[106:109], 0
	v_mfma_f32_16x16x32_bf16 v[56:59], v[56:59], v[106:109], 0
	v_mfma_f32_16x16x32_bf16 v[72:75], v[44:47], v[68:71], v[72:75]
	s_waitcnt vmcnt(12)
	v_mfma_f32_16x16x32_bf16 v[60:63], v[48:51], v[68:71], v[60:63]
	v_mfma_f32_16x16x32_bf16 v[68:71], v[44:47], v[80:83], v[84:87]
	v_mfma_f32_16x16x32_bf16 v[76:79], v[48:51], v[80:83], v[76:79]
	v_mfma_f32_16x16x32_bf16 v[80:83], v[44:47], v[98:101], v[102:105]
	v_mfma_f32_16x16x32_bf16 v[84:87], v[48:51], v[98:101], v[94:97]
	s_waitcnt lgkmcnt(0)
	v_mfma_f32_16x16x32_bf16 v[44:47], v[44:47], v[110:113], v[52:55]
	v_mfma_f32_16x16x32_bf16 v[48:51], v[48:51], v[110:113], v[56:59]
	s_nop 1
	ds_read_b128 v[52:55], v217 offset:128
	ds_read_b128 v[56:59], v217 offset:192
	s_waitcnt vmcnt(11) lgkmcnt(1)
	v_mfma_f32_16x16x32_bf16 v[72:75], v[36:39], v[52:55], v[72:75]
	s_waitcnt vmcnt(9)
	v_mfma_f32_16x16x32_bf16 v[52:55], v[40:43], v[52:55], v[60:63]
	s_nop 2
	ds_read_b128 v[60:63], v114 offset:128
	ds_read_b128 v[94:97], v114 offset:192
	s_waitcnt lgkmcnt(1)
	v_mfma_f32_16x16x32_bf16 v[68:71], v[36:39], v[60:63], v[68:71]
	v_mfma_f32_16x16x32_bf16 v[60:63], v[40:43], v[60:63], v[76:79]
	s_nop 2
	ds_read_b128 v[76:79], v115 offset:128
	ds_read_b128 v[98:101], v115 offset:192
	s_waitcnt lgkmcnt(1)
	v_mfma_f32_16x16x32_bf16 v[80:83], v[36:39], v[76:79], v[80:83]
	v_mfma_f32_16x16x32_bf16 v[76:79], v[40:43], v[76:79], v[84:87]
	s_nop 2
	ds_read_b128 v[84:87], v91 offset:128
	ds_read_b128 v[102:105], v91 offset:192
	s_waitcnt lgkmcnt(1)
	v_mfma_f32_16x16x32_bf16 v[36:39], v[36:39], v[84:87], v[44:47]
	v_mfma_f32_16x16x32_bf16 v[40:43], v[40:43], v[84:87], v[48:51]
	v_mfma_f32_16x16x32_bf16 v[44:47], v[28:31], v[56:59], v[72:75]
	s_waitcnt vmcnt(8)
	v_mfma_f32_16x16x32_bf16 v[48:51], v[32:35], v[56:59], v[52:55]
	v_mfma_f32_16x16x32_bf16 v[52:55], v[28:31], v[94:97], v[68:71]
	v_mfma_f32_16x16x32_bf16 v[56:59], v[32:35], v[94:97], v[60:63]
	v_mfma_f32_16x16x32_bf16 v[60:63], v[28:31], v[98:101], v[80:83]
	v_mfma_f32_16x16x32_bf16 v[68:71], v[32:35], v[98:101], v[76:79]
	s_waitcnt lgkmcnt(0)
	v_mfma_f32_16x16x32_bf16 v[28:31], v[28:31], v[102:105], v[36:39]
	v_mfma_f32_16x16x32_bf16 v[32:35], v[32:35], v[102:105], v[40:43]
	s_nop 1
	ds_read_b128 v[36:39], v217 offset:256
	ds_read_b128 v[40:43], v217 offset:320
	s_waitcnt vmcnt(7) lgkmcnt(1)
	v_mfma_f32_16x16x32_bf16 v[44:47], v[20:23], v[36:39], v[44:47]
	s_waitcnt vmcnt(5)
	v_mfma_f32_16x16x32_bf16 v[36:39], v[24:27], v[36:39], v[48:51]
	s_nop 2
	ds_read_b128 v[48:51], v114 offset:256
	ds_read_b128 v[72:75], v114 offset:320
	s_waitcnt lgkmcnt(1)
	v_mfma_f32_16x16x32_bf16 v[52:55], v[20:23], v[48:51], v[52:55]
	v_mfma_f32_16x16x32_bf16 v[48:51], v[24:27], v[48:51], v[56:59]
	s_nop 2
	ds_read_b128 v[56:59], v115 offset:256
	ds_read_b128 v[76:79], v115 offset:320
	s_waitcnt lgkmcnt(1)
	v_mfma_f32_16x16x32_bf16 v[60:63], v[20:23], v[56:59], v[60:63]
	v_mfma_f32_16x16x32_bf16 v[56:59], v[24:27], v[56:59], v[68:71]
	s_nop 2
	ds_read_b128 v[68:71], v91 offset:256
	ds_read_b128 v[80:83], v91 offset:320
	s_waitcnt lgkmcnt(1)
	v_mfma_f32_16x16x32_bf16 v[20:23], v[20:23], v[68:71], v[28:31]
	v_mfma_f32_16x16x32_bf16 v[24:27], v[24:27], v[68:71], v[32:35]
	v_mfma_f32_16x16x32_bf16 v[28:31], v[12:15], v[40:43], v[44:47]
	s_waitcnt vmcnt(4)
	v_mfma_f32_16x16x32_bf16 v[32:35], v[16:19], v[40:43], v[36:39]
	v_mfma_f32_16x16x32_bf16 v[36:39], v[12:15], v[72:75], v[52:55]
	v_mfma_f32_16x16x32_bf16 v[40:43], v[16:19], v[72:75], v[48:51]
	v_mfma_f32_16x16x32_bf16 v[44:47], v[12:15], v[76:79], v[60:63]
	v_mfma_f32_16x16x32_bf16 v[48:51], v[16:19], v[76:79], v[56:59]
	s_waitcnt lgkmcnt(0)
	v_mfma_f32_16x16x32_bf16 v[12:15], v[12:15], v[80:83], v[20:23]
	v_mfma_f32_16x16x32_bf16 v[16:19], v[16:19], v[80:83], v[24:27]
	s_nop 1
	ds_read_b128 v[20:23], v217 offset:384
	ds_read_b128 v[24:27], v217 offset:448
	ds_read_b128 v[60:63], v114 offset:448
	ds_read_b128 v[52:55], v115 offset:384
	ds_read_b128 v[68:71], v115 offset:448
	s_waitcnt vmcnt(3) lgkmcnt(4)
	v_mfma_f32_16x16x32_bf16 v[28:31], v[8:11], v[20:23], v[28:31]
	ds_read_b128 v[98:101], v91 offset:448
	s_waitcnt vmcnt(1)
; #define LAS __attribute__((address_space(3)))
; __device__ __forceinline__ unsigned cvt_pk_bf16(float lo, float hi) { unsigned r; asm volatile("v_cvt_pk_bf16_f32 %0, %1, %2" : "=v"(r) : "v"(lo), "v"(hi)); return r; }
; __device__ void passB_unit(const Params& p, LAS unsigned char* lds, int u, bool do_store = true) {
;     ...
;         for (int ks = 0; ks < 8; ++ks) { bf16x8 qf[4];
; #pragma unroll
;             for (int mt = 0; mt < 4; ++mt) qf[mt] = *(const LAS bf16x8*)(Qs + (wt2 * 64 + mt * 16 + fr) * 264 + ks * 32 + fq * 8);
; #pragma unroll
;             for (int mt = 0; mt < 4; ++mt)
; #pragma unroll
;                 for (int nt = 0; nt < 2; ++nt) sacc[mt][nt] = __builtin_amdgcn_mfma_f32_16x16x32_bf16(kfa[ks][nt], qf[mt], sacc[mt][nt], 0, 0, 0); }
;         PB_ISSUE(0); PB_ISSUE(1);
;         __builtin_amdgcn_sched_barrier(0);
; #pragma unroll
;         for (int mt = 0; mt < 4; ++mt) { const int t = wt2 * 64 + mt * 16 + fr; const float Mf = MA[t], Mb = MA[128 + t]; float rf = 0.f, rb = 0.f;
; #pragma unroll
;             for (int nt = 0; nt < 2; ++nt) { const int s0 = w4 * 32 + nt * 16 + fq * 4; float pf[4], pb[4];
; #pragma unroll
;                 for (int r = 0; r < 4; ++r) { const int s = s0 + r; const float val = sacc[mt][nt][r];
;                     const float ef = __expf(fminf(aA[s] - Mf, 0.f)), eb = __expf(fminf(aA[128 + s] - Mb, 0.f));
;                     pf[r] = (s <= t) ? val * ef : 0.f; pb[r] = (s >= t) ? val * eb : 0.f; rf += pf[r]; rb += pb[r]; }
;                 u32x2 wf, wb; wf.x = cvt_pk_bf16(pf[0], pf[1]); wf.y = cvt_pk_bf16(pf[2], pf[3]); wb.x = cvt_pk_bf16(pb[0], pb[1]); wb.y = cvt_pk_bf16(pb[2], pb[3]);
;                 *(LAS u32x2*)(Pd + t * 136 + s0) = wf; *(LAS u32x2*)(Pd + 128 * 136 + t * 136 + s0) = wb; }
	v_mfma_f32_16x16x32_bf16 v[20:23], v[4:7], v[20:23], v[32:35]
	s_nop 2
	ds_read_b128 v[32:35], v114 offset:384
	s_waitcnt lgkmcnt(0)
	v_mfma_f32_16x16x32_bf16 v[36:39], v[8:11], v[32:35], v[36:39]
	v_mfma_f32_16x16x32_bf16 v[32:35], v[4:7], v[32:35], v[40:43]
	s_nop 2
	ds_read_b128 v[40:43], v91 offset:384
	v_mfma_f32_16x16x32_bf16 v[72:75], v[8:11], v[52:55], v[44:47]
	s_waitcnt lgkmcnt(0)
	v_mfma_f32_16x16x32_bf16 v[12:15], v[8:11], v[40:43], v[12:15]
	v_mov_b32_e32 v9, 0
	v_lshlrev_b32_e32 v8, 15, v223
	v_lshl_add_u64 v[10:11], s[4:5], 0, v[8:9]
	v_mov_b32_e32 v91, v9
	v_lshl_add_u64 v[140:141], v[10:11], 0, v[90:91]
	s_movk_i32 s4, 0x2000
	v_mfma_f32_16x16x32_bf16 v[94:97], v[4:7], v[52:55], v[48:51]
	v_mfma_f32_16x16x32_bf16 v[102:105], v[4:7], v[40:43], v[16:19]
	v_add_co_u32_e32 v4, vcc, s4, v140
	s_movk_i32 s4, 0x3000
	s_nop 0
	v_addc_co_u32_e32 v5, vcc, 0, v141, vcc
	v_add_co_u32_e32 v114, vcc, s4, v140
	s_movk_i32 s4, 0x1000
	s_nop 0
	v_addc_co_u32_e32 v115, vcc, 0, v141, vcc
	v_add_co_u32_e32 v6, vcc, s4, v140
	v_mfma_f32_16x16x32_bf16 v[106:109], v[0:3], v[24:27], v[28:31]
	s_nop 0
	v_addc_co_u32_e32 v7, vcc, 0, v141, vcc
	global_load_dwordx4 v[56:59], v[140:141], off nt
	global_load_dwordx4 v[48:51], v[140:141], off offset:1024 nt
	global_load_dwordx4 v[52:55], v[4:5], off offset:1024 nt
	global_load_dwordx4 v[40:43], v[4:5], off offset:2048 nt
	s_waitcnt vmcnt(4)
	v_mfma_f32_16x16x32_bf16 v[110:113], v[64:67], v[24:27], v[20:23]
	v_mfma_f32_16x16x32_bf16 v[84:87], v[0:3], v[60:63], v[36:39]
	v_mfma_f32_16x16x32_bf16 v[80:83], v[64:67], v[60:63], v[32:35]
	global_load_dwordx4 v[44:47], v[140:141], off offset:2048 nt
	s_nop 1
	global_load_dwordx4 v[32:35], v[140:141], off offset:3072 nt
	global_load_dwordx4 v[36:39], v[4:5], off offset:3072 nt
	global_load_dwordx4 v[24:27], v[6:7], off nt
	global_load_dwordx4 v[28:31], v[114:115], off nt
	global_load_dwordx4 v[16:19], v[114:115], off offset:1024 nt
	global_load_dwordx4 v[20:23], v[6:7], off offset:1024 nt
	global_load_dwordx4 v[8:11], v[6:7], off offset:2048 nt
	v_mfma_f32_16x16x32_bf16 v[76:79], v[0:3], v[68:71], v[72:75]
	v_mfma_f32_16x16x32_bf16 v[72:75], v[64:67], v[68:71], v[94:97]
	v_mfma_f32_16x16x32_bf16 v[68:71], v[0:3], v[98:101], v[12:15]
	global_load_dwordx4 v[60:63], v[114:115], off offset:-4096 nt
	s_nop 0
	global_load_dwordx4 v[4:7], v[6:7], off offset:3072 nt
	s_nop 0
	global_load_dwordx4 v[12:15], v[114:115], off offset:2048 nt
	global_load_dwordx4 v[0:3], v[114:115], off offset:3072 nt
	v_mfma_f32_16x16x32_bf16 v[64:67], v[64:67], v[98:101], v[102:105]
	v_lshlrev_b32_e32 v212, 2, v93
	v_lshl_or_b32 v91, v223, 5, v212
	v_lshl_add_u32 v93, v211, 2, 0
	s_add_i32 s51, 0, 0x22000
	v_add_u32_e32 v93, 0x22400, v93
	v_lshl_add_u32 v96, v91, 2, s51
	ds_read2st64_b32 v[114:115], v93 offset1:2
	ds_read_b128 v[100:103], v96
	ds_read_b128 v[118:121], v96 offset:512
	s_movk_i32 s6, 0x88
	v_cmp_gt_i32_e32 vcc, v91, v211
	v_mul_lo_u32 v104, v211, s6
	s_waitcnt lgkmcnt(1)
	v_sub_f32_e32 v94, v100, v114
	v_min_f32_e32 v94, 0, v94
	s_waitcnt lgkmcnt(0)
	v_sub_f32_e32 v95, v118, v115
	v_mul_f32_e32 v94, 0x3fb8aa3b, v94
	v_min_f32_e32 v95, 0, v95
	v_sub_f32_e32 v99, v119, v115
	v_exp_f32_e32 v94, v94
	v_mul_f32_e32 v95, 0x3fb8aa3b, v95
	v_min_f32_e32 v99, 0, v99
	v_exp_f32_e32 v95, v95
	v_mul_f32_e32 v99, 0x3fb8aa3b, v99
	v_exp_f32_e32 v99, v99
	v_mul_f32_e32 v94, v106, v94
	v_cndmask_b32_e64 v97, v94, 0, vcc
	v_mul_f32_e32 v94, v106, v95
	v_cmp_lt_i32_e64 s[6:7], v91, v211
	v_sub_f32_e32 v98, v101, v114
	v_or_b32_e32 v100, 1, v91
	v_cndmask_b32_e64 v105, v94, 0, s[6:7]
	v_min_f32_e32 v98, 0, v98
	v_mul_f32_e32 v99, v107, v99
	v_cmp_ge_i32_e64 s[10:11], v100, v211
	v_add_f32_e32 v95, 0, v105
	v_mul_f32_e32 v98, 0x3fb8aa3b, v98
	v_cndmask_b32_e64 v101, 0, v99, s[10:11]
	v_exp_f32_e32 v98, v98
	v_add_f32_e32 v118, v95, v101
	v_sub_f32_e32 v95, v102, v114
	v_min_f32_e32 v95, 0, v95
	v_mul_f32_e32 v95, 0x3fb8aa3b, v95
	v_exp_f32_e32 v95, v95
	v_sub_f32_e32 v102, v120, v115
	v_mul_f32_e32 v98, v107, v98
	v_min_f32_e32 v102, 0, v102
	v_add_f32_e32 v94, 0, v97
	v_cndmask_b32_e64 v98, 0, v98, s[6:7]
	v_mul_f32_e32 v102, 0x3fb8aa3b, v102
	v_add_f32_e32 v99, v94, v98
	v_or_b32_e32 v94, 2, v91
	v_exp_f32_e32 v102, v102
	v_mul_f32_e32 v95, v108, v95
	v_cmp_le_i32_e64 s[10:11], v94, v211
	v_lshlrev_b32_e32 v93, 1, v104
	s_add_i32 s46, 0, 0x10800
	v_cndmask_b32_e64 v106, 0, v95, s[10:11]
	v_add_f32_e32 v120, v99, v106
	v_sub_f32_e32 v99, v103, v114
	v_mul_f32_e32 v95, v108, v102
	v_min_f32_e32 v99, 0, v99
	v_sub_f32_e32 v102, v121, v115
	v_mul_f32_e32 v99, 0x3fb8aa3b, v99
	v_min_f32_e32 v102, 0, v102
	v_exp_f32_e32 v99, v99
	v_mul_f32_e32 v102, 0x3fb8aa3b, v102
	v_exp_f32_e32 v102, v102
	v_cmp_ge_i32_e64 s[10:11], v94, v211
	v_mul_f32_e32 v99, v109, v99
	s_add_i32 s48, 0, 0x19000
	v_cndmask_b32_e64 v119, 0, v95, s[10:11]
	v_or_b32_e32 v95, 3, v91
	v_cmp_le_i32_e64 s[10:11], v95, v211
	v_cvt_pk_bf16_f32 v98, v97, v98
	v_add_f32_e32 v97, v118, v119
	v_mbcnt_hi_u32_b32 v204, -1, v158
	v_cndmask_b32_e64 v103, 0, v99, s[10:11]
	v_mul_f32_e32 v99, v109, v102
	v_lshlrev_b32_e32 v102, 1, v91
	v_cmp_ge_i32_e64 s[10:11], v95, v211
	v_add3_u32 v122, s46, v93, v102
	v_add3_u32 v123, s48, v93, v102
	v_or_b32_e32 v93, 16, v91
	v_cndmask_b32_e64 v121, 0, v99, s[10:11]
	v_cvt_pk_bf16_f32 v99, v106, v103
	v_cvt_pk_bf16_f32 v106, v105, v101
	v_cvt_pk_bf16_f32 v107, v119, v121
	ds_write_b64 v122, v[98:99]
	ds_write_b64 v123, v[106:107]
	v_lshl_add_u32 v101, v93, 2, s51
	ds_read_b128 v[106:109], v101
	v_add_f32_e32 v98, v120, v103
	v_add_f32_e32 v97, v97, v121
	ds_read_b128 v[118:121], v101 offset:512
	v_cmp_le_i32_e64 s[10:11], v93, v211
	s_waitcnt lgkmcnt(1)
; #define LAS __attribute__((address_space(3)))
; __device__ __forceinline__ unsigned cvt_pk_bf16(float lo, float hi) { unsigned r; asm volatile("v_cvt_pk_bf16_f32 %0, %1, %2" : "=v"(r) : "v"(lo), "v"(hi)); return r; }
; __device__ void passB_unit(const Params& p, LAS unsigned char* lds, int u, bool do_store = true) {
;     ...
;         for (int mt = 0; mt < 4; ++mt) { const int t = wt2 * 64 + mt * 16 + fr; const float Mf = MA[t], Mb = MA[128 + t]; float rf = 0.f, rb = 0.f;
; #pragma unroll
;             for (int nt = 0; nt < 2; ++nt) { const int s0 = w4 * 32 + nt * 16 + fq * 4; float pf[4], pb[4];
; #pragma unroll
;                 for (int r = 0; r < 4; ++r) { const int s = s0 + r; const float val = sacc[mt][nt][r];
;                     const float ef = __expf(fminf(aA[s] - Mf, 0.f)), eb = __expf(fminf(aA[128 + s] - Mb, 0.f));
;                     pf[r] = (s <= t) ? val * ef : 0.f; pb[r] = (s >= t) ? val * eb : 0.f; rf += pf[r]; rb += pb[r]; }
;                 u32x2 wf, wb; wf.x = cvt_pk_bf16(pf[0], pf[1]); wf.y = cvt_pk_bf16(pf[2], pf[3]); wb.x = cvt_pk_bf16(pb[0], pb[1]); wb.y = cvt_pk_bf16(pb[2], pb[3]);
;                 *(LAS u32x2*)(Pd + t * 136 + s0) = wf; *(LAS u32x2*)(Pd + 128 * 136 + t * 136 + s0) = wb; }
;             rf += __shfl_xor(rf, 16); rf += __shfl_xor(rf, 32); rb += __shfl_xor(rb, 16); rb += __shfl_xor(rb, 32);
;             if (fq == 0) { rsP[w4 * 128 + t] = rf; rsP[512 + w4 * 128 + t] = rb; } }
	v_sub_f32_e32 v99, v106, v114
	v_sub_f32_e32 v106, v107, v114
	v_min_f32_e32 v106, 0, v106
	s_waitcnt lgkmcnt(0)
	v_sub_f32_e32 v107, v119, v115
	v_min_f32_e32 v107, 0, v107
	v_min_f32_e32 v99, 0, v99
	v_sub_f32_e32 v103, v118, v115
	v_mul_f32_e32 v106, 0x3fb8aa3b, v106
	v_mul_f32_e32 v107, 0x3fb8aa3b, v107
	v_mul_f32_e32 v99, 0x3fb8aa3b, v99
	v_min_f32_e32 v103, 0, v103
	v_exp_f32_e32 v106, v106
	v_exp_f32_e32 v107, v107
	v_exp_f32_e32 v99, v99
	v_mul_f32_e32 v103, 0x3fb8aa3b, v103
	v_exp_f32_e32 v103, v103
	v_mul_f32_e32 v106, v111, v106
	v_mul_f32_e32 v107, v111, v107
	v_sub_f32_e32 v108, v108, v114
	v_sub_f32_e32 v111, v120, v115
	v_mul_f32_e32 v99, v110, v99
	v_min_f32_e32 v108, 0, v108
	v_min_f32_e32 v111, 0, v111
	v_cndmask_b32_e64 v105, 0, v99, s[10:11]
	v_mul_f32_e32 v99, v110, v103
	v_cmp_ge_i32_e64 s[10:11], v93, v211
	v_mul_f32_e32 v108, 0x3fb8aa3b, v108
	v_mul_f32_e32 v111, 0x3fb8aa3b, v111
	v_cndmask_b32_e64 v103, 0, v99, s[10:11]
	v_exp_f32_e32 v108, v108
	v_exp_f32_e32 v111, v111
	v_add_f32_e32 v99, v97, v103
	v_or_b32_e32 v97, 17, v91
	v_cmp_le_i32_e64 s[10:11], v97, v211
	v_sub_f32_e32 v109, v109, v114
	v_add_f32_e32 v98, v98, v105
	v_cndmask_b32_e64 v106, 0, v106, s[10:11]
	v_min_f32_e32 v109, 0, v109
	v_cmp_ge_i32_e64 s[10:11], v97, v211
	v_add_f32_e32 v110, v98, v106
	v_or_b32_e32 v98, 18, v91
	v_mul_f32_e32 v108, v112, v108
	v_mul_f32_e32 v111, v112, v111
	v_mul_f32_e32 v109, 0x3fb8aa3b, v109
	v_sub_f32_e32 v112, v121, v115
	v_cndmask_b32_e64 v107, 0, v107, s[10:11]
	v_cmp_le_i32_e64 s[10:11], v98, v211
	v_exp_f32_e32 v109, v109
	v_min_f32_e32 v112, 0, v112
	v_cndmask_b32_e64 v108, 0, v108, s[10:11]
	v_cmp_ge_i32_e64 s[10:11], v98, v211
	v_mul_f32_e32 v112, 0x3fb8aa3b, v112
	v_add_f32_e32 v99, v99, v107
	v_cndmask_b32_e64 v118, 0, v111, s[10:11]
	v_exp_f32_e32 v112, v112
	v_add_f32_e32 v111, v99, v118
	v_or_b32_e32 v99, 19, v91
	v_mul_f32_e32 v109, v113, v109
	v_cmp_le_i32_e64 s[10:11], v99, v211
	v_add_f32_e32 v110, v110, v108
	v_and_b32_e32 v205, 64, v204
	v_cndmask_b32_e64 v109, 0, v109, s[10:11]
	v_mul_f32_e32 v112, v113, v112
	v_cmp_ge_i32_e64 s[10:11], v99, v211
	v_add_f32_e32 v114, v110, v109
	v_xor_b32_e32 v110, 16, v204
	v_add_u32_e32 v115, 64, v205
	v_cndmask_b32_e64 v113, 0, v112, s[10:11]
	v_cmp_lt_i32_e64 s[10:11], v110, v115
	v_add_f32_e32 v120, v111, v113
	v_lshlrev_b32_e32 v216, 9, v223
	v_cndmask_b32_e64 v110, v204, v110, s[10:11]
	v_lshlrev_b32_e32 v225, 2, v110
	v_cvt_pk_bf16_f32 v110, v105, v106
	v_cvt_pk_bf16_f32 v111, v108, v109
	v_cvt_pk_bf16_f32 v112, v103, v107
	v_xor_b32_e32 v103, 32, v204
	v_cmp_lt_i32_e64 s[10:11], v103, v115
	s_waitcnt lgkmcnt(0)
	v_mov_b32_e32 v119, v114
	v_mov_b32_e32 v105, v114
	s_nop 1
	v_permlane16_swap_b32_e32 v119, v105
	v_add_f32_e32 v105, v105, v119
	s_add_i32 s47, 0, 0x23c00
	v_cndmask_b32_e64 v103, v204, v103, s[10:11]
	v_lshlrev_b32_e32 v226, 2, v103
	s_waitcnt lgkmcnt(0)
	v_mov_b32_e32 v107, v120
	v_mov_b32_e32 v119, v120
	s_nop 1
	v_permlane16_swap_b32_e32 v107, v119
	v_add_f32_e32 v107, v107, v119
	v_mov_b32_e32 v106, v105
	s_nop 1
	v_permlane32_swap_b32_e32 v106, v105
	v_mov_b32_e32 v108, v107
	s_nop 1
	v_permlane32_swap_b32_e32 v108, v107
	v_add_u32_e32 v117, s47, v216
	v_cmp_gt_u32_e64 s[4:5], 16, v197
	v_lshl_add_u32 v103, v211, 2, v117
	v_cvt_pk_bf16_f32 v113, v118, v113
	ds_write_b64 v122, v[110:111] offset:32
	ds_write_b64 v123, v[112:113] offset:32
	s_and_saveexec_b64 s[10:11], s[4:5]
	s_cbranch_execz .LBB0_551
	s_waitcnt lgkmcnt(2)
	v_add_f32_e32 v107, v107, v108
	v_add_f32_e32 v105, v105, v106
	ds_write2st64_b32 v103, v105, v107 offset1:8
.LBB0_551:
	s_or_b64 exec, exec, s[10:11]
	v_or_b32_e32 v213, 16, v211
	v_lshl_add_u32 v105, v213, 2, 0
	v_add_u32_e32 v105, 0x22400, v105
	s_waitcnt lgkmcnt(2)
	ds_read_b128 v[106:109], v96
	ds_read2st64_b32 v[114:115], v105 offset1:2
	ds_read_b128 v[110:113], v96 offset:512
	v_cmp_le_i32_e64 s[10:11], v91, v213
	v_add_u32_e32 v104, 0x880, v104
	v_lshlrev_b32_e32 v105, 1, v104
	s_waitcnt lgkmcnt(1)
	v_sub_f32_e32 v106, v106, v114
	v_min_f32_e32 v106, 0, v106
	s_waitcnt lgkmcnt(0)
	v_sub_f32_e32 v110, v110, v115
	v_sub_f32_e32 v107, v107, v114
	v_mul_f32_e32 v106, 0x3fb8aa3b, v106
	v_min_f32_e32 v110, 0, v110
	v_min_f32_e32 v107, 0, v107
	v_exp_f32_e32 v106, v106
	v_mul_f32_e32 v110, 0x3fb8aa3b, v110
	v_mul_f32_e32 v107, 0x3fb8aa3b, v107
	v_sub_f32_e32 v111, v111, v115
	v_exp_f32_e32 v110, v110
	v_exp_f32_e32 v107, v107
	v_min_f32_e32 v111, 0, v111
	v_mul_f32_e32 v111, 0x3fb8aa3b, v111
	v_exp_f32_e32 v111, v111
	v_mul_f32_e32 v106, v84, v106
	v_cndmask_b32_e64 v106, 0, v106, s[10:11]
	v_mul_f32_e32 v84, v84, v110
	v_cmp_lt_i32_e64 s[10:11], v91, v213
	v_mul_f32_e32 v107, v85, v107
	v_mul_f32_e32 v85, v85, v111
	v_cndmask_b32_e64 v110, v84, 0, s[10:11]
	v_add_f32_e32 v84, 0, v106
	v_cndmask_b32_e64 v107, 0, v107, s[10:11]
	v_cmp_ge_i32_e64 s[10:11], v100, v213
	v_add_f32_e32 v118, v84, v107
	v_sub_f32_e32 v84, v108, v114
	v_cndmask_b32_e64 v111, 0, v85, s[10:11]
	v_min_f32_e32 v84, 0, v84
	v_sub_f32_e32 v85, v112, v115
	v_mul_f32_e32 v84, 0x3fb8aa3b, v84
	v_min_f32_e32 v85, 0, v85
	v_exp_f32_e32 v84, v84
	v_mul_f32_e32 v85, 0x3fb8aa3b, v85
	v_exp_f32_e32 v85, v85
	v_cmp_le_i32_e64 s[10:11], v94, v213
	v_mul_f32_e32 v84, v86, v84
	v_add_f32_e32 v117, 0, v110
	v_cndmask_b32_e64 v108, 0, v84, s[10:11]
	v_mul_f32_e32 v84, v86, v85
	v_cmp_ge_i32_e64 s[10:11], v94, v213
	v_sub_f32_e32 v85, v113, v115
	v_min_f32_e32 v85, 0, v85
	v_cndmask_b32_e64 v112, 0, v84, s[10:11]
	v_sub_f32_e32 v84, v109, v114
	v_min_f32_e32 v84, 0, v84
	v_mul_f32_e32 v84, 0x3fb8aa3b, v84
	v_exp_f32_e32 v84, v84
	v_mul_f32_e32 v85, 0x3fb8aa3b, v85
	v_exp_f32_e32 v85, v85
	v_cmp_le_i32_e64 s[10:11], v95, v213
	v_mul_f32_e32 v84, v87, v84
	v_add_f32_e32 v117, v117, v111
	v_cndmask_b32_e64 v109, 0, v84, s[10:11]
	v_mul_f32_e32 v84, v87, v85
	v_cmp_ge_i32_e64 s[10:11], v95, v213
	s_nop 1
	v_cndmask_b32_e64 v113, 0, v84, s[10:11]
	v_cvt_pk_bf16_f32 v84, v106, v107
	v_cvt_pk_bf16_f32 v85, v108, v109
	v_cvt_pk_bf16_f32 v86, v110, v111
	v_add3_u32 v110, s46, v105, v102
	v_add3_u32 v105, s48, v105, v102
	v_cvt_pk_bf16_f32 v87, v112, v113
	ds_write_b64 v110, v[84:85]
	ds_write_b64 v105, v[86:87]
	ds_read_b128 v[84:87], v101
	v_add_f32_e32 v106, v118, v108
	v_add_f32_e32 v111, v117, v112
	v_add_f32_e32 v112, v106, v109
	ds_read_b128 v[106:109], v101 offset:512
	s_waitcnt lgkmcnt(1)
; #define LAS __attribute__((address_space(3)))
; __device__ __forceinline__ unsigned cvt_pk_bf16(float lo, float hi) { unsigned r; asm volatile("v_cvt_pk_bf16_f32 %0, %1, %2" : "=v"(r) : "v"(lo), "v"(hi)); return r; }
; __device__ void passB_unit(const Params& p, LAS unsigned char* lds, int u, bool do_store = true) {
;     ...
;         for (int mt = 0; mt < 4; ++mt) { const int t = wt2 * 64 + mt * 16 + fr; const float Mf = MA[t], Mb = MA[128 + t]; float rf = 0.f, rb = 0.f;
; #pragma unroll
;             for (int nt = 0; nt < 2; ++nt) { const int s0 = w4 * 32 + nt * 16 + fq * 4; float pf[4], pb[4];
; #pragma unroll
;                 for (int r = 0; r < 4; ++r) { const int s = s0 + r; const float val = sacc[mt][nt][r];
;                     const float ef = __expf(fminf(aA[s] - Mf, 0.f)), eb = __expf(fminf(aA[128 + s] - Mb, 0.f));
;                     pf[r] = (s <= t) ? val * ef : 0.f; pb[r] = (s >= t) ? val * eb : 0.f; rf += pf[r]; rb += pb[r]; }
;                 u32x2 wf, wb; wf.x = cvt_pk_bf16(pf[0], pf[1]); wf.y = cvt_pk_bf16(pf[2], pf[3]); wb.x = cvt_pk_bf16(pb[0], pb[1]); wb.y = cvt_pk_bf16(pb[2], pb[3]);
;                 *(LAS u32x2*)(Pd + t * 136 + s0) = wf; *(LAS u32x2*)(Pd + 128 * 136 + t * 136 + s0) = wb; }
;             rf += __shfl_xor(rf, 16); rf += __shfl_xor(rf, 32); rb += __shfl_xor(rb, 16); rb += __shfl_xor(rb, 32);
;             if (fq == 0) { rsP[w4 * 128 + t] = rf; rsP[512 + w4 * 128 + t] = rb; } }
	v_sub_f32_e32 v84, v84, v114
	v_min_f32_e32 v84, 0, v84
	v_sub_f32_e32 v85, v85, v114
	v_mul_f32_e32 v84, 0x3fb8aa3b, v84
	v_min_f32_e32 v85, 0, v85
	s_waitcnt lgkmcnt(0)
	v_sub_f32_e32 v107, v107, v115
	v_exp_f32_e32 v84, v84
	v_mul_f32_e32 v85, 0x3fb8aa3b, v85
	v_min_f32_e32 v107, 0, v107
	v_sub_f32_e32 v86, v86, v114
	v_exp_f32_e32 v85, v85
	v_mul_f32_e32 v107, 0x3fb8aa3b, v107
	v_min_f32_e32 v86, 0, v86
	v_sub_f32_e32 v108, v108, v115
	v_exp_f32_e32 v107, v107
	v_mul_f32_e32 v86, 0x3fb8aa3b, v86
	v_min_f32_e32 v108, 0, v108
	v_exp_f32_e32 v86, v86
	v_mul_f32_e32 v108, 0x3fb8aa3b, v108
	v_mul_f32_e32 v84, v80, v84
	v_exp_f32_e32 v108, v108
	v_cndmask_b32_e64 v84, v84, 0, vcc
	v_mul_f32_e32 v85, v81, v85
	v_cmp_le_i32_e32 vcc, v97, v213
	v_mul_f32_e32 v81, v81, v107
	v_sub_f32_e32 v106, v106, v115
	v_cndmask_b32_e32 v85, 0, v85, vcc
	v_cmp_ge_i32_e32 vcc, v97, v213
	v_mul_f32_e32 v86, v82, v86
	v_min_f32_e32 v106, 0, v106
	v_cndmask_b32_e32 v107, 0, v81, vcc
	v_cmp_le_i32_e32 vcc, v98, v213
	v_mul_f32_e32 v82, v82, v108
	v_mul_f32_e32 v106, 0x3fb8aa3b, v106
	v_cndmask_b32_e32 v86, 0, v86, vcc
	v_cmp_ge_i32_e32 vcc, v98, v213
	v_exp_f32_e32 v106, v106
	v_add_f32_e32 v111, v111, v113
	v_cndmask_b32_e32 v108, 0, v82, vcc
	v_sub_f32_e32 v82, v87, v114
	v_min_f32_e32 v82, 0, v82
	v_sub_f32_e32 v87, v109, v115
	v_mul_f32_e32 v82, 0x3fb8aa3b, v82
	v_min_f32_e32 v87, 0, v87
	v_exp_f32_e32 v82, v82
	v_mul_f32_e32 v87, 0x3fb8aa3b, v87
	v_exp_f32_e32 v87, v87
	v_mul_f32_e32 v80, v80, v106
	v_cndmask_b32_e64 v106, v80, 0, s[6:7]
	v_add_f32_e32 v80, v112, v84
	v_add_f32_e32 v111, v111, v106
	v_mul_f32_e32 v82, v83, v82
	v_cmp_le_i32_e32 vcc, v99, v213
	v_add_f32_e32 v80, v80, v85
	v_add_f32_e32 v81, v111, v107
	v_cndmask_b32_e32 v82, 0, v82, vcc
	v_mul_f32_e32 v83, v83, v87
	v_cmp_ge_i32_e32 vcc, v99, v213
	v_add_f32_e32 v80, v80, v86
	v_add_f32_e32 v81, v81, v108
	v_cndmask_b32_e32 v87, 0, v83, vcc
	v_add_f32_e32 v80, v80, v82
	v_add_f32_e32 v109, v81, v87
	v_cvt_pk_bf16_f32 v84, v84, v85
	v_cvt_pk_bf16_f32 v85, v86, v82
	v_cvt_pk_bf16_f32 v86, v106, v107
	s_waitcnt lgkmcnt(0)
	v_mov_b32_e32 v83, v80
	s_nop 1
	v_permlane16_swap_b32_e32 v83, v80
	v_add_f32_e32 v80, v80, v83
	s_waitcnt lgkmcnt(0)
	v_mov_b32_e32 v111, v109
	v_mov_b32_e32 v82, v109
	s_nop 1
	v_permlane16_swap_b32_e32 v111, v82
	v_add_f32_e32 v82, v82, v111
	v_mov_b32_e32 v81, v80
	s_nop 1
	v_permlane32_swap_b32_e32 v81, v80
	v_mov_b32_e32 v83, v82
	s_nop 1
	v_permlane32_swap_b32_e32 v83, v82
	v_cvt_pk_bf16_f32 v87, v108, v87
	ds_write_b64 v110, v[84:85] offset:32
	ds_write_b64 v105, v[86:87] offset:32
	s_and_saveexec_b64 s[6:7], s[4:5]
	s_cbranch_execz .LBB0_553
	s_waitcnt lgkmcnt(2)
	v_add_f32_e32 v82, v82, v83
	v_add_f32_e32 v80, v80, v81
	v_add_u32_e32 v81, 64, v103
	ds_write2st64_b32 v81, v80, v82 offset1:8
.LBB0_553:
	s_or_b64 exec, exec, s[6:7]
	v_or_b32_e32 v214, 32, v211
	v_lshl_add_u32 v80, v214, 2, 0
	v_add_u32_e32 v80, 0x22400, v80
	s_waitcnt lgkmcnt(2)
	ds_read_b128 v[82:85], v96
	ds_read2st64_b32 v[86:87], v80 offset1:2
	v_add_u32_e32 v80, 0x880, v104
	ds_read_b128 v[104:107], v96 offset:512
	v_cmp_le_i32_e32 vcc, v91, v214
	v_lshlrev_b32_e32 v81, 1, v80
	s_waitcnt lgkmcnt(1)
	v_sub_f32_e32 v82, v82, v86
	v_min_f32_e32 v82, 0, v82
	s_waitcnt lgkmcnt(0)
	v_sub_f32_e32 v104, v104, v87
	v_sub_f32_e32 v83, v83, v86
	v_mul_f32_e32 v82, 0x3fb8aa3b, v82
	v_min_f32_e32 v104, 0, v104
	v_min_f32_e32 v83, 0, v83
	v_sub_f32_e32 v105, v105, v87
	v_exp_f32_e32 v82, v82
	v_mul_f32_e32 v104, 0x3fb8aa3b, v104
	v_mul_f32_e32 v83, 0x3fb8aa3b, v83
	v_min_f32_e32 v105, 0, v105
	v_exp_f32_e32 v104, v104
	v_exp_f32_e32 v83, v83
	v_mul_f32_e32 v105, 0x3fb8aa3b, v105
	v_exp_f32_e32 v105, v105
	v_mul_f32_e32 v82, v76, v82
	v_cndmask_b32_e32 v82, 0, v82, vcc
	v_mul_f32_e32 v76, v76, v104
	v_cmp_lt_i32_e32 vcc, v91, v214
	v_mul_f32_e32 v83, v77, v83
	v_mul_f32_e32 v77, v77, v105
	v_cndmask_b32_e64 v104, v76, 0, vcc
	v_cndmask_b32_e32 v83, 0, v83, vcc
	v_cmp_ge_i32_e32 vcc, v100, v214
	v_add_f32_e32 v76, 0, v82
	v_add_f32_e32 v76, v76, v83
	v_cndmask_b32_e32 v105, 0, v77, vcc
	v_sub_f32_e32 v77, v84, v86
	v_min_f32_e32 v77, 0, v77
	v_mul_f32_e32 v77, 0x3fb8aa3b, v77
	v_sub_f32_e32 v84, v106, v87
	v_exp_f32_e32 v77, v77
	v_min_f32_e32 v84, 0, v84
	v_mul_f32_e32 v84, 0x3fb8aa3b, v84
	v_exp_f32_e32 v84, v84
	v_mul_f32_e32 v77, v78, v77
	v_cmp_le_i32_e32 vcc, v94, v214
	v_add_f32_e32 v108, 0, v104
	v_mul_f32_e32 v78, v78, v84
	v_cndmask_b32_e32 v77, 0, v77, vcc
	v_cmp_ge_i32_e32 vcc, v94, v214
	v_add_f32_e32 v106, v76, v77
	v_sub_f32_e32 v76, v85, v86
	v_cndmask_b32_e32 v84, 0, v78, vcc
	v_min_f32_e32 v76, 0, v76
	v_sub_f32_e32 v78, v107, v87
	v_mul_f32_e32 v76, 0x3fb8aa3b, v76
	v_min_f32_e32 v78, 0, v78
	v_exp_f32_e32 v76, v76
	v_mul_f32_e32 v78, 0x3fb8aa3b, v78
	v_exp_f32_e32 v78, v78
	v_cmp_le_i32_e32 vcc, v95, v214
	v_mul_f32_e32 v76, v79, v76
	v_add_f32_e32 v108, v108, v105
	v_cndmask_b32_e32 v85, 0, v76, vcc
	v_mul_f32_e32 v76, v79, v78
	v_cmp_ge_i32_e32 vcc, v95, v214
	s_nop 1
	v_cndmask_b32_e32 v107, 0, v76, vcc
	v_cvt_pk_bf16_f32 v76, v82, v83
	v_cvt_pk_bf16_f32 v77, v77, v85
	v_cvt_pk_bf16_f32 v78, v104, v105
	v_add3_u32 v104, s46, v81, v102
	v_add3_u32 v81, s48, v81, v102
	v_cvt_pk_bf16_f32 v79, v84, v107
	ds_write_b64 v104, v[76:77]
	ds_write_b64 v81, v[78:79]
	ds_read_b128 v[76:79], v101
	v_add_f32_e32 v82, v108, v84
	v_add_f32_e32 v105, v106, v85
	v_add_f32_e32 v106, v82, v107
	ds_read_b128 v[82:85], v101 offset:512
	s_waitcnt lgkmcnt(1)
	v_sub_f32_e32 v76, v76, v86
	v_min_f32_e32 v76, 0, v76
	v_mul_f32_e32 v76, 0x3fb8aa3b, v76
	v_sub_f32_e32 v77, v77, v86
	s_waitcnt lgkmcnt(0)
; #define LAS __attribute__((address_space(3)))
; __device__ __forceinline__ unsigned cvt_pk_bf16(float lo, float hi) { unsigned r; asm volatile("v_cvt_pk_bf16_f32 %0, %1, %2" : "=v"(r) : "v"(lo), "v"(hi)); return r; }
; __device__ void passB_unit(const Params& p, LAS unsigned char* lds, int u, bool do_store = true) {
;     ...
;         for (int mt = 0; mt < 4; ++mt) { const int t = wt2 * 64 + mt * 16 + fr; const float Mf = MA[t], Mb = MA[128 + t]; float rf = 0.f, rb = 0.f;
; #pragma unroll
;             for (int nt = 0; nt < 2; ++nt) { const int s0 = w4 * 32 + nt * 16 + fq * 4; float pf[4], pb[4];
; #pragma unroll
;                 for (int r = 0; r < 4; ++r) { const int s = s0 + r; const float val = sacc[mt][nt][r];
;                     const float ef = __expf(fminf(aA[s] - Mf, 0.f)), eb = __expf(fminf(aA[128 + s] - Mb, 0.f));
;                     pf[r] = (s <= t) ? val * ef : 0.f; pb[r] = (s >= t) ? val * eb : 0.f; rf += pf[r]; rb += pb[r]; }
;                 u32x2 wf, wb; wf.x = cvt_pk_bf16(pf[0], pf[1]); wf.y = cvt_pk_bf16(pf[2], pf[3]); wb.x = cvt_pk_bf16(pb[0], pb[1]); wb.y = cvt_pk_bf16(pb[2], pb[3]);
;                 *(LAS u32x2*)(Pd + t * 136 + s0) = wf; *(LAS u32x2*)(Pd + 128 * 136 + t * 136 + s0) = wb; }
;             rf += __shfl_xor(rf, 16); rf += __shfl_xor(rf, 32); rb += __shfl_xor(rb, 16); rb += __shfl_xor(rb, 32);
;             if (fq == 0) { rsP[w4 * 128 + t] = rf; rsP[512 + w4 * 128 + t] = rb; } }
	v_sub_f32_e32 v82, v82, v87
	v_min_f32_e32 v82, 0, v82
	v_exp_f32_e32 v76, v76
	v_mul_f32_e32 v82, 0x3fb8aa3b, v82
	v_min_f32_e32 v77, 0, v77
	v_sub_f32_e32 v83, v83, v87
	v_exp_f32_e32 v82, v82
	v_mul_f32_e32 v77, 0x3fb8aa3b, v77
	v_min_f32_e32 v83, 0, v83
	v_sub_f32_e32 v78, v78, v86
	v_exp_f32_e32 v77, v77
	v_mul_f32_e32 v83, 0x3fb8aa3b, v83
	v_min_f32_e32 v78, 0, v78
	v_sub_f32_e32 v84, v84, v87
	v_exp_f32_e32 v83, v83
	v_mul_f32_e32 v78, 0x3fb8aa3b, v78
	v_min_f32_e32 v84, 0, v84
	v_mul_f32_e32 v76, v72, v76
	v_cmp_le_i32_e32 vcc, v93, v214
	v_exp_f32_e32 v78, v78
	v_mul_f32_e32 v84, 0x3fb8aa3b, v84
	v_cndmask_b32_e32 v76, 0, v76, vcc
	v_mul_f32_e32 v72, v72, v82
	v_cmp_ge_i32_e32 vcc, v93, v214
	v_exp_f32_e32 v84, v84
	v_mul_f32_e32 v77, v73, v77
	v_cndmask_b32_e32 v82, 0, v72, vcc
	v_cmp_le_i32_e32 vcc, v97, v214
	v_mul_f32_e32 v73, v73, v83
	v_mul_f32_e32 v78, v74, v78
	v_cndmask_b32_e32 v77, 0, v77, vcc
	v_cmp_ge_i32_e32 vcc, v97, v214
	v_mul_f32_e32 v74, v74, v84
	v_add_f32_e32 v72, v105, v76
	v_cndmask_b32_e32 v83, 0, v73, vcc
	v_cmp_le_i32_e32 vcc, v98, v214
	v_add_f32_e32 v105, v106, v82
	v_add_f32_e32 v72, v72, v77
	v_cndmask_b32_e32 v78, 0, v78, vcc
	v_cmp_ge_i32_e32 vcc, v98, v214
	v_add_f32_e32 v73, v105, v83
	v_add_f32_e32 v72, v72, v78
	v_cndmask_b32_e32 v84, 0, v74, vcc
	v_sub_f32_e32 v74, v79, v86
	v_min_f32_e32 v74, 0, v74
	v_sub_f32_e32 v79, v85, v87
	v_mul_f32_e32 v74, 0x3fb8aa3b, v74
	v_min_f32_e32 v79, 0, v79
	v_exp_f32_e32 v74, v74
	v_mul_f32_e32 v79, 0x3fb8aa3b, v79
	v_exp_f32_e32 v79, v79
	v_cmp_le_i32_e32 vcc, v99, v214
	v_mul_f32_e32 v74, v75, v74
	v_add_f32_e32 v73, v73, v84
	v_cndmask_b32_e32 v74, 0, v74, vcc
	v_mul_f32_e32 v75, v75, v79
	v_cmp_ge_i32_e32 vcc, v99, v214
	v_add_f32_e32 v72, v72, v74
	v_cvt_pk_bf16_f32 v76, v76, v77
	v_cvt_pk_bf16_f32 v77, v78, v74
	v_cvt_pk_bf16_f32 v78, v82, v83
	s_nop 0
	v_cndmask_b32_e32 v79, 0, v75, vcc
	v_add_f32_e32 v85, v73, v79
	v_cvt_pk_bf16_f32 v79, v84, v79
	ds_write_b64 v104, v[76:77] offset:32
	ds_write_b64 v81, v[78:79] offset:32
	s_waitcnt lgkmcnt(2)
	v_mov_b32_e32 v75, v72
	s_nop 1
	v_permlane16_swap_b32_e32 v75, v72
	v_add_f32_e32 v72, v72, v75
	s_waitcnt lgkmcnt(2)
	v_mov_b32_e32 v86, v85
	v_mov_b32_e32 v74, v85
	s_nop 1
	v_permlane16_swap_b32_e32 v86, v74
	v_add_f32_e32 v74, v74, v86
	v_mov_b32_e32 v73, v72
	s_nop 1
	v_permlane32_swap_b32_e32 v73, v72
	v_mov_b32_e32 v75, v74
	s_nop 1
	v_permlane32_swap_b32_e32 v75, v74
	s_and_saveexec_b64 s[6:7], s[4:5]
	s_cbranch_execz .LBB0_555
	s_waitcnt lgkmcnt(0)
	v_add_f32_e32 v74, v74, v75
	v_add_f32_e32 v72, v72, v73
	v_add_u32_e32 v73, 0x80, v103
	ds_write2st64_b32 v73, v72, v74 offset1:8
; #define LAS __attribute__((address_space(3)))
; __device__ __forceinline__ unsigned cvt_pk_bf16(float lo, float hi) { unsigned r; asm volatile("v_cvt_pk_bf16_f32 %0, %1, %2" : "=v"(r) : "v"(lo), "v"(hi)); return r; }
; __device__ void passB_unit(const Params& p, LAS unsigned char* lds, int u, bool do_store = true) {
;     ...
;         for (int mt = 0; mt < 4; ++mt) { const int t = wt2 * 64 + mt * 16 + fr; const float Mf = MA[t], Mb = MA[128 + t]; float rf = 0.f, rb = 0.f;
; #pragma unroll
;             for (int nt = 0; nt < 2; ++nt) { const int s0 = w4 * 32 + nt * 16 + fq * 4; float pf[4], pb[4];
; #pragma unroll
;                 for (int r = 0; r < 4; ++r) { const int s = s0 + r; const float val = sacc[mt][nt][r];
;                     const float ef = __expf(fminf(aA[s] - Mf, 0.f)), eb = __expf(fminf(aA[128 + s] - Mb, 0.f));
;                     pf[r] = (s <= t) ? val * ef : 0.f; pb[r] = (s >= t) ? val * eb : 0.f; rf += pf[r]; rb += pb[r]; }
;                 u32x2 wf, wb; wf.x = cvt_pk_bf16(pf[0], pf[1]); wf.y = cvt_pk_bf16(pf[2], pf[3]); wb.x = cvt_pk_bf16(pb[0], pb[1]); wb.y = cvt_pk_bf16(pb[2], pb[3]);
;                 *(LAS u32x2*)(Pd + t * 136 + s0) = wf; *(LAS u32x2*)(Pd + 128 * 136 + t * 136 + s0) = wb; }
;             rf += __shfl_xor(rf, 16); rf += __shfl_xor(rf, 32); rb += __shfl_xor(rb, 16); rb += __shfl_xor(rb, 32);
;             if (fq == 0) { rsP[w4 * 128 + t] = rf; rsP[512 + w4 * 128 + t] = rb; } }
.LBB0_555:
	s_or_b64 exec, exec, s[6:7]
	v_or_b32_e32 v215, 48, v211
	v_lshl_add_u32 v72, v215, 2, 0
	v_add_u32_e32 v76, 0x22400, v72
	s_waitcnt lgkmcnt(0)
	ds_read_b128 v[72:75], v96
	ds_read2st64_b32 v[82:83], v76 offset1:2
	ds_read_b128 v[76:79], v96 offset:512
	v_cmp_le_i32_e32 vcc, v91, v215
	v_mov_b32_e32 v81, 0x1100
	v_lshl_add_u32 v80, v80, 1, v81
	s_waitcnt lgkmcnt(1)
	v_sub_f32_e32 v72, v72, v82
	v_min_f32_e32 v72, 0, v72
	s_waitcnt lgkmcnt(0)
	v_sub_f32_e32 v76, v76, v83
	v_sub_f32_e32 v73, v73, v82
	v_mul_f32_e32 v72, 0x3fb8aa3b, v72
	v_min_f32_e32 v76, 0, v76
	v_min_f32_e32 v73, 0, v73
	v_sub_f32_e32 v77, v77, v83
	v_exp_f32_e32 v72, v72
	v_mul_f32_e32 v76, 0x3fb8aa3b, v76
	v_mul_f32_e32 v73, 0x3fb8aa3b, v73
	v_min_f32_e32 v77, 0, v77
	v_exp_f32_e32 v76, v76
	v_exp_f32_e32 v73, v73
	v_mul_f32_e32 v77, 0x3fb8aa3b, v77
	v_exp_f32_e32 v77, v77
	v_mul_f32_e32 v72, v68, v72
	v_cndmask_b32_e32 v72, 0, v72, vcc
	v_mul_f32_e32 v68, v68, v76
	v_cmp_lt_i32_e32 vcc, v91, v215
	v_mul_f32_e32 v73, v69, v73
	v_mul_f32_e32 v69, v69, v77
	v_cndmask_b32_e64 v76, v68, 0, vcc
	v_cndmask_b32_e32 v73, 0, v73, vcc
	v_cmp_ge_i32_e32 vcc, v100, v215
	v_add_f32_e32 v68, 0, v72
	v_add_f32_e32 v68, v68, v73
	v_cndmask_b32_e32 v77, 0, v69, vcc
	v_sub_f32_e32 v69, v74, v82
	v_min_f32_e32 v69, 0, v69
	v_mul_f32_e32 v69, 0x3fb8aa3b, v69
	v_sub_f32_e32 v74, v78, v83
	v_exp_f32_e32 v69, v69
	v_min_f32_e32 v74, 0, v74
	v_mul_f32_e32 v74, 0x3fb8aa3b, v74
	v_exp_f32_e32 v74, v74
	v_mul_f32_e32 v69, v70, v69
	v_cmp_le_i32_e32 vcc, v94, v215
	v_add_f32_e32 v81, 0, v76
	v_mul_f32_e32 v70, v70, v74
	v_cndmask_b32_e32 v69, 0, v69, vcc
	v_cmp_ge_i32_e32 vcc, v94, v215
	v_add_f32_e32 v78, v68, v69
	v_sub_f32_e32 v68, v75, v82
	v_cndmask_b32_e32 v74, 0, v70, vcc
	v_min_f32_e32 v68, 0, v68
	v_sub_f32_e32 v70, v79, v83
	v_mul_f32_e32 v68, 0x3fb8aa3b, v68
	v_min_f32_e32 v70, 0, v70
	v_exp_f32_e32 v68, v68
	v_mul_f32_e32 v70, 0x3fb8aa3b, v70
	v_exp_f32_e32 v70, v70
	v_cmp_le_i32_e32 vcc, v95, v215
	v_mul_f32_e32 v68, v71, v68
	v_add_f32_e32 v81, v81, v77
	v_cndmask_b32_e32 v75, 0, v68, vcc
	v_mul_f32_e32 v68, v71, v70
	v_cmp_ge_i32_e32 vcc, v95, v215
	v_add_f32_e32 v78, v78, v75
	s_nop 0
	v_cndmask_b32_e32 v79, 0, v68, vcc
	v_cvt_pk_bf16_f32 v68, v72, v73
	v_cvt_pk_bf16_f32 v69, v69, v75
	v_cvt_pk_bf16_f32 v70, v76, v77
	v_add3_u32 v76, s46, v80, v102
	v_add3_u32 v77, s48, v80, v102
	v_cvt_pk_bf16_f32 v71, v74, v79
	ds_write_b64 v76, v[68:69]
	ds_write_b64 v77, v[70:71]
	ds_read_b128 v[68:71], v101
	v_add_f32_e32 v72, v81, v74
	v_add_f32_e32 v79, v72, v79
	ds_read_b128 v[72:75], v101 offset:512
	v_cmp_le_i32_e32 vcc, v93, v215
	s_waitcnt lgkmcnt(1)
	v_sub_f32_e32 v68, v68, v82
	v_min_f32_e32 v68, 0, v68
	v_mul_f32_e32 v68, 0x3fb8aa3b, v68
	s_waitcnt lgkmcnt(0)
	v_sub_f32_e32 v72, v72, v83
	v_min_f32_e32 v72, 0, v72
	v_sub_f32_e32 v69, v69, v82
	v_exp_f32_e32 v68, v68
	v_mul_f32_e32 v72, 0x3fb8aa3b, v72
	v_min_f32_e32 v69, 0, v69
	v_sub_f32_e32 v73, v73, v83
	v_exp_f32_e32 v72, v72
	v_mul_f32_e32 v69, 0x3fb8aa3b, v69
	v_min_f32_e32 v73, 0, v73
	v_sub_f32_e32 v70, v70, v82
	v_exp_f32_e32 v69, v69
	v_mul_f32_e32 v73, 0x3fb8aa3b, v73
	v_min_f32_e32 v70, 0, v70
	v_sub_f32_e32 v74, v74, v83
	v_exp_f32_e32 v73, v73
	v_mul_f32_e32 v70, 0x3fb8aa3b, v70
	v_min_f32_e32 v74, 0, v74
	v_mul_f32_e32 v68, v64, v68
	v_exp_f32_e32 v70, v70
	v_mul_f32_e32 v74, 0x3fb8aa3b, v74
	v_cndmask_b32_e32 v68, 0, v68, vcc
	v_mul_f32_e32 v64, v64, v72
	v_cmp_ge_i32_e32 vcc, v93, v215
	v_exp_f32_e32 v74, v74
	v_mul_f32_e32 v69, v65, v69
	v_cndmask_b32_e32 v72, 0, v64, vcc
	v_cmp_le_i32_e32 vcc, v97, v215
	v_mul_f32_e32 v65, v65, v73
	v_mul_f32_e32 v70, v66, v70
	v_cndmask_b32_e32 v69, 0, v69, vcc
	v_cmp_ge_i32_e32 vcc, v97, v215
	v_mul_f32_e32 v66, v66, v74
	v_add_f32_e32 v64, v78, v68
	v_cndmask_b32_e32 v73, 0, v65, vcc
	v_cmp_le_i32_e32 vcc, v98, v215
	v_add_f32_e32 v78, v79, v72
	v_add_f32_e32 v64, v64, v69
	v_cndmask_b32_e32 v70, 0, v70, vcc
	v_cmp_ge_i32_e32 vcc, v98, v215
	v_add_f32_e32 v65, v78, v73
	v_add_f32_e32 v64, v64, v70
	v_cndmask_b32_e32 v74, 0, v66, vcc
	v_sub_f32_e32 v66, v71, v82
	v_min_f32_e32 v66, 0, v66
	v_sub_f32_e32 v71, v75, v83
	v_mul_f32_e32 v66, 0x3fb8aa3b, v66
	v_min_f32_e32 v71, 0, v71
	v_exp_f32_e32 v66, v66
	v_mul_f32_e32 v71, 0x3fb8aa3b, v71
	v_exp_f32_e32 v71, v71
	v_cmp_le_i32_e32 vcc, v99, v215
	v_mul_f32_e32 v66, v67, v66
	v_add_f32_e32 v65, v65, v74
	v_cndmask_b32_e32 v66, 0, v66, vcc
	v_mul_f32_e32 v67, v67, v71
	v_cmp_ge_i32_e32 vcc, v99, v215
	v_add_f32_e32 v64, v64, v66
	v_cvt_pk_bf16_f32 v68, v68, v69
	v_cvt_pk_bf16_f32 v69, v70, v66
	v_cvt_pk_bf16_f32 v70, v72, v73
	s_nop 0
	v_cndmask_b32_e32 v71, 0, v67, vcc
	v_add_f32_e32 v75, v65, v71
	v_cvt_pk_bf16_f32 v71, v74, v71
	ds_write_b64 v76, v[68:69] offset:32
	ds_write_b64 v77, v[70:71] offset:32
	s_waitcnt lgkmcnt(2)
	v_mov_b32_e32 v67, v64
	s_nop 1
	v_permlane16_swap_b32_e32 v67, v64
	v_add_f32_e32 v64, v64, v67
	s_waitcnt lgkmcnt(2)
	v_mov_b32_e32 v78, v75
	v_mov_b32_e32 v66, v75
	s_nop 1
	v_permlane16_swap_b32_e32 v78, v66
	v_add_f32_e32 v66, v66, v78
	v_mov_b32_e32 v65, v64
	s_nop 1
	v_permlane32_swap_b32_e32 v65, v64
	v_mov_b32_e32 v67, v66
	s_nop 1
	v_permlane32_swap_b32_e32 v67, v66
	s_and_saveexec_b64 s[6:7], s[4:5]
	s_cbranch_execz .LBB0_557
	s_waitcnt lgkmcnt(0)
	v_add_f32_e32 v66, v66, v67
	v_add_f32_e32 v64, v64, v65
	v_add_u32_e32 v65, 0xc0, v103
	ds_write2st64_b32 v65, v64, v66 offset1:8

; #define LAS __attribute__((address_space(3)))
; __device__ void passB_unit(const Params& p, LAS unsigned char* lds, int u, bool do_store = true) {
;     ...
;     f32x4 hsum[4][4], acc[4][2];
; #pragma unroll
;     for (int q = 0; q < 12; ++q) {
;         const int nh = q / 6, d = (q % 6) / 3, kind = q % 3;
;         if (q + 2 < 12) PB_ISSUE(q + 2);
;         __builtin_amdgcn_sched_barrier(0);
;         if (kind == 0) {
; #pragma unroll
;             for (int mt = 0; mt < 4; ++mt)
; #pragma unroll
;                 for (int n2 = 0; n2 < 2; ++n2) { acc[mt][n2] = (f32x4){0.f, 0.f, 0.f, 0.f}; if (d == 0) hsum[mt][nh * 2 + n2] = (f32x4){0.f, 0.f, 0.f, 0.f}; }
;         }
;         if (kind < 2) {
; #pragma unroll
;             for (int ks = 0; ks < 4; ++ks) { bf16x8 qf[4];
; #pragma unroll
;                 for (int mt = 0; mt < 4; ++mt) qf[mt] = *(const LAS bf16x8*)(Qs + (wt2 * 64 + mt * 16 + fr) * 264 + (kind * 4 + ks) * 32 + fq * 8);
; #pragma unroll
;                 for (int mt = 0; mt < 4; ++mt)
; #pragma unroll
;                     for (int n2 = 0; n2 < 2; ++n2) acc[mt][n2] = __builtin_amdgcn_mfma_f32_16x16x32_bf16(F[q % 3][ks][n2], qf[mt], acc[mt][n2], 0, 0, 0); }
.LBB0_559:
	s_or_b64 exec, exec, s[6:7]
	s_ashr_i32 s43, s42, 31
	s_lshl_b64 s[0:1], s[42:43], 18
	v_readlane_b32 s6, v254, 31
	s_add_u32 s0, s6, s0
	v_readlane_b32 s6, v254, 32
	s_addc_u32 s1, s6, s1
	s_lshl_b32 s74, s34, 15
	v_or_b32_e32 v64, s74, v89
	v_lshlrev_b32_e32 v92, 1, v64
	v_mov_b32_e32 v93, 0
	v_lshl_add_u64 v[64:65], s[0:1], 0, v[92:93]
	v_mov_b32_e32 v91, v93
	v_lshl_add_u64 v[144:145], v[64:65], 0, v[90:91]
	s_movk_i32 s1, 0x1000
	v_add_co_u32_e32 v142, vcc, s1, v144
	s_movk_i32 s0, 0x2000
	s_nop 0
	v_addc_co_u32_e32 v143, vcc, 0, v145, vcc
	v_add_co_u32_e32 v188, vcc, s0, v144
	s_waitcnt lgkmcnt(0)
	s_barrier
	v_addc_co_u32_e32 v189, vcc, 0, v145, vcc
	global_load_dwordx4 v[96:99], v[144:145], off
	global_load_dwordx4 v[80:83], v[144:145], off offset:1024
	global_load_dwordx4 v[84:87], v[142:143], off offset:1024
	global_load_dwordx4 v[72:75], v[142:143], off offset:2048
	global_load_dwordx4 v[76:79], v[144:145], off offset:2048
	global_load_dwordx4 v[68:71], v[144:145], off offset:3072
	global_load_dwordx4 v[112:115], v[188:189], off offset:-4096
	global_load_dwordx4 v[64:67], v[142:143], off offset:3072
	s_or_b32 s6, s50, 1
	s_cmp_lt_i32 s6, 32
	s_cselect_b32 s75, s69, s13
	s_cselect_b32 s76, s68, s12
	s_lshl_b32 s6, s6, 4
	s_and_b32 s77, s6, 0x1f0
	s_or_b32 s6, s77, s52
	s_lshl_b32 s6, s6, 17
	s_add_u32 s6, s76, s6
	s_addc_u32 s7, s75, 0
	v_lshlrev_b32_e32 v92, 1, v88
	v_lshl_add_u64 v[88:89], s[6:7], 0, v[92:93]
	v_and_b32_e32 v218, 0xffffff00, v196
	s_add_i32 s78, 0, 0x22800
	v_lshlrev_b32_e32 v219, 2, v201
	s_add_i32 s79, 0, 0x25400
	v_lshl_add_u64 v[156:157], v[88:89], 0, v[90:91]
	v_add3_u32 v221, s78, v218, v219
	v_add3_u32 v220, s79, v218, v219
	ds_read_b128 v[88:91], v217
	ds_read_b128 v[92:95], v217 offset:64
	ds_read_b128 v[104:107], v217 offset:8448
	ds_read_b128 v[108:111], v217 offset:8512
	ds_read_b128 v[122:125], v217 offset:16896
	ds_read_b128 v[126:129], v217 offset:16960
	ds_read_b128 v[134:137], v217 offset:25344
	ds_read_b128 v[146:149], v217 offset:25408
	s_waitcnt vmcnt(23) lgkmcnt(7)
	v_mfma_f32_16x16x32_bf16 v[100:103], v[56:59], v[88:91], 0
	s_waitcnt vmcnt(11)
	v_mfma_f32_16x16x32_bf16 v[88:91], v[60:63], v[88:91], 0
	s_waitcnt lgkmcnt(5)
	v_mfma_f32_16x16x32_bf16 v[118:121], v[56:59], v[104:107], 0
	v_mfma_f32_16x16x32_bf16 v[104:107], v[60:63], v[104:107], 0
	s_waitcnt lgkmcnt(3)
	v_mfma_f32_16x16x32_bf16 v[130:133], v[56:59], v[122:125], 0
	v_mfma_f32_16x16x32_bf16 v[122:125], v[60:63], v[122:125], 0
	s_waitcnt lgkmcnt(1)
	v_mfma_f32_16x16x32_bf16 v[56:59], v[56:59], v[134:137], 0
	v_mfma_f32_16x16x32_bf16 v[60:63], v[60:63], v[134:137], 0
	v_mfma_f32_16x16x32_bf16 v[100:103], v[48:51], v[92:95], v[100:103]
	v_mfma_f32_16x16x32_bf16 v[88:91], v[52:55], v[92:95], v[88:91]
	v_mfma_f32_16x16x32_bf16 v[92:95], v[48:51], v[108:111], v[118:121]
	v_mfma_f32_16x16x32_bf16 v[104:107], v[52:55], v[108:111], v[104:107]
	v_mfma_f32_16x16x32_bf16 v[108:111], v[48:51], v[126:129], v[130:133]
	v_mfma_f32_16x16x32_bf16 v[118:121], v[52:55], v[126:129], v[122:125]
	s_waitcnt lgkmcnt(0)
	v_mfma_f32_16x16x32_bf16 v[48:51], v[48:51], v[146:149], v[56:59]
	v_mfma_f32_16x16x32_bf16 v[52:55], v[52:55], v[146:149], v[60:63]
	s_nop 1
	ds_read_b128 v[56:59], v217 offset:128
	ds_read_b128 v[60:63], v217 offset:192
	s_waitcnt lgkmcnt(1)
	v_mfma_f32_16x16x32_bf16 v[100:103], v[44:47], v[56:59], v[100:103]
	v_mfma_f32_16x16x32_bf16 v[56:59], v[40:43], v[56:59], v[88:91]
	s_nop 2
	ds_read_b128 v[88:91], v217 offset:8576
	ds_read_b128 v[122:125], v217 offset:8640
	s_waitcnt lgkmcnt(1)
	v_mfma_f32_16x16x32_bf16 v[92:95], v[44:47], v[88:91], v[92:95]
	v_mfma_f32_16x16x32_bf16 v[88:91], v[40:43], v[88:91], v[104:107]
	s_nop 2
	ds_read_b128 v[104:107], v217 offset:17024
	ds_read_b128 v[126:129], v217 offset:17088
	s_waitcnt lgkmcnt(1)
	v_mfma_f32_16x16x32_bf16 v[108:111], v[44:47], v[104:107], v[108:111]
	v_mfma_f32_16x16x32_bf16 v[104:107], v[40:43], v[104:107], v[118:121]
	s_nop 2
	ds_read_b128 v[118:121], v217 offset:25472
	ds_read_b128 v[132:135], v217 offset:25536
	s_waitcnt lgkmcnt(1)
	v_mfma_f32_16x16x32_bf16 v[44:47], v[44:47], v[118:121], v[48:51]
	v_mfma_f32_16x16x32_bf16 v[52:55], v[40:43], v[118:121], v[52:55]
	v_add_co_u32_e32 v118, vcc, s0, v156
	s_movk_i32 s0, 0x3000
	s_nop 0
	v_addc_co_u32_e32 v119, vcc, 0, v157, vcc
	v_add_co_u32_e32 v154, vcc, s0, v156
	v_mfma_f32_16x16x32_bf16 v[100:103], v[32:35], v[60:63], v[100:103]
	s_nop 0
	v_addc_co_u32_e32 v155, vcc, 0, v157, vcc
	v_mfma_f32_16x16x32_bf16 v[56:59], v[36:39], v[60:63], v[56:59]
	v_mfma_f32_16x16x32_bf16 v[92:95], v[32:35], v[122:125], v[92:95]
	v_mfma_f32_16x16x32_bf16 v[88:91], v[36:39], v[122:125], v[88:91]
	v_mfma_f32_16x16x32_bf16 v[146:149], v[32:35], v[126:129], v[108:111]
	v_mfma_f32_16x16x32_bf16 v[104:107], v[36:39], v[126:129], v[104:107]
	global_load_dwordx4 v[128:131], v[156:157], off nt
	s_nop 0
	global_load_dwordx4 v[108:111], v[156:157], off offset:1024 nt
	global_load_dwordx4 v[120:123], v[118:119], off offset:1024 nt
	global_load_dwordx4 v[48:51], v[118:119], off offset:2048 nt
	s_waitcnt lgkmcnt(0)
	v_mfma_f32_16x16x32_bf16 v[44:47], v[32:35], v[132:135], v[44:47]
	global_load_dwordx4 v[60:63], v[156:157], off offset:2048 nt
	global_load_dwordx4 v[40:43], v[156:157], off offset:3072 nt
	global_load_dwordx4 v[136:139], v[154:155], off offset:-4096 nt
	global_load_dwordx4 v[32:35], v[118:119], off offset:3072 nt
	v_mfma_f32_16x16x32_bf16 v[36:39], v[36:39], v[132:135], v[52:55]
	s_nop 2
	ds_read_b128 v[52:55], v217 offset:256
	ds_read_b128 v[124:127], v217 offset:320
	s_waitcnt lgkmcnt(1)
; #define LAS __attribute__((address_space(3)))
; __device__ void passB_unit(const Params& p, LAS unsigned char* lds, int u, bool do_store = true) {
;     ...
;     for (int q = 0; q < 12; ++q) {
;         const int nh = q / 6, d = (q % 6) / 3, kind = q % 3;
;         if (q + 2 < 12) PB_ISSUE(q + 2);
;         __builtin_amdgcn_sched_barrier(0);
;         if (kind == 0) {
; #pragma unroll
;             for (int mt = 0; mt < 4; ++mt)
; #pragma unroll
;                 for (int n2 = 0; n2 < 2; ++n2) { acc[mt][n2] = (f32x4){0.f, 0.f, 0.f, 0.f}; if (d == 0) hsum[mt][nh * 2 + n2] = (f32x4){0.f, 0.f, 0.f, 0.f}; }
;         }
;         if (kind < 2) {
; #pragma unroll
;             for (int ks = 0; ks < 4; ++ks) { bf16x8 qf[4];
; #pragma unroll
;                 for (int mt = 0; mt < 4; ++mt) qf[mt] = *(const LAS bf16x8*)(Qs + (wt2 * 64 + mt * 16 + fr) * 264 + (kind * 4 + ks) * 32 + fq * 8);
; #pragma unroll
;                 for (int mt = 0; mt < 4; ++mt)
; #pragma unroll
;                     for (int n2 = 0; n2 < 2; ++n2) acc[mt][n2] = __builtin_amdgcn_mfma_f32_16x16x32_bf16(F[q % 3][ks][n2], qf[mt], acc[mt][n2], 0, 0, 0); }
;         } else {
;             const LAS bf16_t* Pp = Pd + d * 128 * 136;
; #pragma unroll
;             for (int mt = 0; mt < 4; ++mt) { const float wv = winA[d * 128 + wt2 * 64 + mt * 16 + fr];
; #pragma unroll
;                 for (int n2 = 0; n2 < 2; ++n2) acc[mt][n2] *= wv; }
; #pragma unroll
;             for (int ks = 0; ks < 4; ++ks) { bf16x8 pf[4];
; #pragma unroll
;                 for (int mt = 0; mt < 4; ++mt) pf[mt] = *(const LAS bf16x8*)(Pp + (wt2 * 64 + mt * 16 + fr) * 136 + ks * 32 + fq * 8);
; #pragma unroll
;                 for (int mt = 0; mt < 4; ++mt)
; #pragma unroll
;                     for (int n2 = 0; n2 < 2; ++n2) acc[mt][n2] = __builtin_amdgcn_mfma_f32_16x16x32_bf16(F[q % 3][ks][n2], pf[mt], acc[mt][n2], 0, 0, 0); }
; #pragma unroll
;             for (int mt = 0; mt < 4; ++mt) { const float iv = invA[d * 128 + wt2 * 64 + mt * 16 + fr];
; #pragma unroll
;                 for (int n2 = 0; n2 < 2; ++n2) hsum[mt][nh * 2 + n2] += acc[mt][n2] * iv; }
	v_mfma_f32_16x16x32_bf16 v[100:103], v[24:27], v[52:55], v[100:103]
	v_mfma_f32_16x16x32_bf16 v[52:55], v[28:31], v[52:55], v[56:59]
	s_nop 2
	ds_read_b128 v[56:59], v217 offset:8704
	ds_read_b128 v[132:135], v217 offset:8768
	s_waitcnt lgkmcnt(1)
	v_mfma_f32_16x16x32_bf16 v[92:95], v[24:27], v[56:59], v[92:95]
	v_mfma_f32_16x16x32_bf16 v[56:59], v[28:31], v[56:59], v[88:91]
	s_nop 2
	ds_read_b128 v[88:91], v217 offset:17152
	ds_read_b128 v[150:153], v217 offset:17216
	s_waitcnt lgkmcnt(1)
	v_mfma_f32_16x16x32_bf16 v[146:149], v[24:27], v[88:91], v[146:149]
	v_mfma_f32_16x16x32_bf16 v[88:91], v[28:31], v[88:91], v[104:107]
	s_nop 2
	ds_read_b128 v[104:107], v217 offset:25600
	ds_read_b128 v[158:161], v217 offset:25664
	s_waitcnt lgkmcnt(1)
	v_mfma_f32_16x16x32_bf16 v[24:27], v[24:27], v[104:107], v[44:47]
	v_mfma_f32_16x16x32_bf16 v[28:31], v[28:31], v[104:107], v[36:39]
	v_mfma_f32_16x16x32_bf16 v[36:39], v[20:23], v[124:127], v[100:103]
	v_mfma_f32_16x16x32_bf16 v[44:47], v[16:19], v[124:127], v[52:55]
	v_mfma_f32_16x16x32_bf16 v[52:55], v[20:23], v[132:135], v[92:95]
	v_mfma_f32_16x16x32_bf16 v[56:59], v[16:19], v[132:135], v[56:59]
	v_mfma_f32_16x16x32_bf16 v[92:95], v[20:23], v[150:153], v[146:149]
	v_mfma_f32_16x16x32_bf16 v[88:91], v[16:19], v[150:153], v[88:91]
	s_waitcnt lgkmcnt(0)
	v_mfma_f32_16x16x32_bf16 v[20:23], v[20:23], v[158:161], v[24:27]
	v_mfma_f32_16x16x32_bf16 v[16:19], v[16:19], v[158:161], v[28:31]
	s_nop 1
	ds_read_b128 v[24:27], v217 offset:384
	ds_read_b128 v[28:31], v217 offset:448
	s_waitcnt lgkmcnt(1)
	v_mfma_f32_16x16x32_bf16 v[36:39], v[8:11], v[24:27], v[36:39]
	s_waitcnt vmcnt(17)
	v_mfma_f32_16x16x32_bf16 v[24:27], v[12:15], v[24:27], v[44:47]
	s_nop 2
	ds_read_b128 v[44:47], v217 offset:8832
	ds_read_b128 v[100:103], v217 offset:8896
	s_waitcnt lgkmcnt(1)
	v_mfma_f32_16x16x32_bf16 v[52:55], v[8:11], v[44:47], v[52:55]
	v_mfma_f32_16x16x32_bf16 v[44:47], v[12:15], v[44:47], v[56:59]
	s_nop 2
	ds_read_b128 v[56:59], v217 offset:17280
	ds_read_b128 v[104:107], v217 offset:17344
	s_waitcnt lgkmcnt(1)
	v_mfma_f32_16x16x32_bf16 v[92:95], v[8:11], v[56:59], v[92:95]
	v_mfma_f32_16x16x32_bf16 v[56:59], v[12:15], v[56:59], v[88:91]
	s_nop 2
	ds_read_b128 v[88:91], v217 offset:25728
	ds_read_b128 v[124:127], v217 offset:25792
	s_waitcnt lgkmcnt(1)
	v_mfma_f32_16x16x32_bf16 v[12:15], v[12:15], v[88:91], v[16:19]
	v_mfma_f32_16x16x32_bf16 v[16:19], v[4:7], v[28:31], v[36:39]
	s_nop 2
	v_add_co_u32_e32 v36, vcc, s1, v156
	v_mfma_f32_16x16x32_bf16 v[8:11], v[8:11], v[88:91], v[20:23]
	s_nop 0
	v_addc_co_u32_e32 v37, vcc, 0, v157, vcc
	s_waitcnt vmcnt(16)
	v_mfma_f32_16x16x32_bf16 v[20:23], v[0:3], v[28:31], v[24:27]
	v_mfma_f32_16x16x32_bf16 v[24:27], v[4:7], v[100:103], v[52:55]
	v_mfma_f32_16x16x32_bf16 v[28:31], v[0:3], v[100:103], v[44:47]
	v_mfma_f32_16x16x32_bf16 v[132:135], v[4:7], v[104:107], v[92:95]
	v_mfma_f32_16x16x32_bf16 v[146:149], v[0:3], v[104:107], v[56:59]
	global_load_dwordx4 v[100:103], v[36:37], off nt
	global_load_dwordx4 v[88:91], v[36:37], off offset:1024 nt
	global_load_dwordx4 v[104:107], v[154:155], off nt
	global_load_dwordx4 v[92:95], v[154:155], off offset:1024 nt
	global_load_dwordx4 v[52:55], v[36:37], off offset:2048 nt
	global_load_dwordx4 v[44:47], v[36:37], off offset:3072 nt
	global_load_dwordx4 v[56:59], v[154:155], off offset:2048 nt
	s_nop 0
	global_load_dwordx4 v[36:39], v[154:155], off offset:3072 nt
	s_waitcnt lgkmcnt(0)
	v_mfma_f32_16x16x32_bf16 v[4:7], v[4:7], v[124:127], v[8:11]
	v_mfma_f32_16x16x32_bf16 v[0:3], v[0:3], v[124:127], v[12:15]
	ds_read2_b32 v[118:119], v221 offset1:16
	s_movk_i32 s1, 0x110
	v_mul_lo_u32 v8, v211, s1
	v_add3_u32 v222, s46, v116, v8
	ds_read_b128 v[12:15], v222
	s_waitcnt lgkmcnt(1)
	v_pk_mul_f32 v[10:11], v[18:19], v[118:119] op_sel_hi:[1,0]
	v_pk_mul_f32 v[8:9], v[16:17], v[118:119] op_sel_hi:[1,0]
	v_pk_mul_f32 v[18:19], v[22:23], v[118:119] op_sel_hi:[1,0]
	v_pk_mul_f32 v[16:17], v[20:21], v[118:119] op_sel_hi:[1,0]
	v_mov_b32_e32 v150, v119
	ds_read_b128 v[116:119], v222 offset:4352
	ds_read_b128 v[124:127], v222 offset:4416
	ds_read2_b32 v[154:155], v221 offset0:32 offset1:48
	ds_read_b128 v[20:23], v222 offset:64
	s_waitcnt vmcnt(23) lgkmcnt(4)
	v_mfma_f32_16x16x32_bf16 v[8:11], v[96:99], v[12:15], v[8:11]
	v_mul_f32_e64 v26, v26, v150
	v_mul_f32_e64 v27, v27, v150
	v_pk_mul_f32 v[24:25], v[24:25], v[150:151] op_sel_hi:[1,0]
	s_waitcnt vmcnt(17)
	v_mfma_f32_16x16x32_bf16 v[12:15], v[112:115], v[12:15], v[16:19]
	s_nop 2
	v_mul_f32_e64 v18, v30, v150
	v_mul_f32_e64 v19, v31, v150
	v_pk_mul_f32 v[16:17], v[28:29], v[150:151] op_sel_hi:[1,0]
	ds_read_b128 v[150:153], v222 offset:8704
	s_waitcnt lgkmcnt(4)
	v_mfma_f32_16x16x32_bf16 v[24:27], v[96:99], v[116:119], v[24:27]
	s_waitcnt lgkmcnt(2)
	v_pk_mul_f32 v[30:31], v[134:135], v[154:155] op_sel_hi:[1,0]
	v_pk_mul_f32 v[28:29], v[132:133], v[154:155] op_sel_hi:[1,0]
	ds_read_b128 v[132:135], v222 offset:8768
	v_mfma_f32_16x16x32_bf16 v[16:19], v[112:115], v[116:119], v[16:19]
	v_mul_f32_e64 v118, v148, v154
	v_mul_f32_e64 v119, v149, v154
	v_pk_mul_f32 v[116:117], v[146:147], v[154:155] op_sel_hi:[1,0]
	ds_read_b128 v[146:149], v222 offset:13056
	v_mov_b32_e32 v154, v155
	s_waitcnt lgkmcnt(2)
	v_mfma_f32_16x16x32_bf16 v[28:31], v[96:99], v[150:153], v[28:31]
	v_mul_f32_e64 v6, v6, v154
	v_mul_f32_e64 v7, v7, v154
	v_pk_mul_f32 v[4:5], v[4:5], v[154:155] op_sel_hi:[1,0]
	v_pk_mul_f32 v[2:3], v[2:3], v[154:155] op_sel_hi:[1,0]
	v_mfma_f32_16x16x32_bf16 v[116:119], v[112:115], v[150:153], v[116:119]
	ds_read_b128 v[150:153], v222 offset:13120
	v_pk_mul_f32 v[0:1], v[0:1], v[154:155] op_sel_hi:[1,0]
	s_waitcnt lgkmcnt(1)
; #define LAS __attribute__((address_space(3)))
; __device__ void passB_unit(const Params& p, LAS unsigned char* lds, int u, bool do_store = true) {
;     ...
;     for (int q = 0; q < 12; ++q) {
;         const int nh = q / 6, d = (q % 6) / 3, kind = q % 3;
;         if (q + 2 < 12) PB_ISSUE(q + 2);
;         __builtin_amdgcn_sched_barrier(0);
;         if (kind == 0) {
; #pragma unroll
;             for (int mt = 0; mt < 4; ++mt)
; #pragma unroll
;                 for (int n2 = 0; n2 < 2; ++n2) { acc[mt][n2] = (f32x4){0.f, 0.f, 0.f, 0.f}; if (d == 0) hsum[mt][nh * 2 + n2] = (f32x4){0.f, 0.f, 0.f, 0.f}; }
;         }
;         if (kind < 2) {
; #pragma unroll
;             for (int ks = 0; ks < 4; ++ks) { bf16x8 qf[4];
; #pragma unroll
;                 for (int mt = 0; mt < 4; ++mt) qf[mt] = *(const LAS bf16x8*)(Qs + (wt2 * 64 + mt * 16 + fr) * 264 + (kind * 4 + ks) * 32 + fq * 8);
; #pragma unroll
;                 for (int mt = 0; mt < 4; ++mt)
; #pragma unroll
;                     for (int n2 = 0; n2 < 2; ++n2) acc[mt][n2] = __builtin_amdgcn_mfma_f32_16x16x32_bf16(F[q % 3][ks][n2], qf[mt], acc[mt][n2], 0, 0, 0); }
;         } else {
;             const LAS bf16_t* Pp = Pd + d * 128 * 136;
; #pragma unroll
;             for (int mt = 0; mt < 4; ++mt) { const float wv = winA[d * 128 + wt2 * 64 + mt * 16 + fr];
; #pragma unroll
;                 for (int n2 = 0; n2 < 2; ++n2) acc[mt][n2] *= wv; }
; #pragma unroll
;             for (int ks = 0; ks < 4; ++ks) { bf16x8 pf[4];
; #pragma unroll
;                 for (int mt = 0; mt < 4; ++mt) pf[mt] = *(const LAS bf16x8*)(Pp + (wt2 * 64 + mt * 16 + fr) * 136 + ks * 32 + fq * 8);
; #pragma unroll
;                 for (int mt = 0; mt < 4; ++mt)
; #pragma unroll
;                     for (int n2 = 0; n2 < 2; ++n2) acc[mt][n2] = __builtin_amdgcn_mfma_f32_16x16x32_bf16(F[q % 3][ks][n2], pf[mt], acc[mt][n2], 0, 0, 0); }
; #pragma unroll
;             for (int mt = 0; mt < 4; ++mt) { const float iv = invA[d * 128 + wt2 * 64 + mt * 16 + fr];
; #pragma unroll
;                 for (int n2 = 0; n2 < 2; ++n2) hsum[mt][nh * 2 + n2] += acc[mt][n2] * iv; }
	v_mfma_f32_16x16x32_bf16 v[4:7], v[96:99], v[146:149], v[4:7]
	v_mfma_f32_16x16x32_bf16 v[0:3], v[112:115], v[146:149], v[0:3]
	v_mfma_f32_16x16x32_bf16 v[8:11], v[80:83], v[20:23], v[8:11]
	v_mfma_f32_16x16x32_bf16 v[12:15], v[84:87], v[20:23], v[12:15]
	v_mfma_f32_16x16x32_bf16 v[20:23], v[80:83], v[124:127], v[24:27]
	v_mfma_f32_16x16x32_bf16 v[16:19], v[84:87], v[124:127], v[16:19]
	v_mfma_f32_16x16x32_bf16 v[24:27], v[80:83], v[132:135], v[28:31]
	v_mfma_f32_16x16x32_bf16 v[28:31], v[84:87], v[132:135], v[116:119]
	s_waitcnt lgkmcnt(0)
	v_mfma_f32_16x16x32_bf16 v[4:7], v[80:83], v[150:153], v[4:7]
	v_mfma_f32_16x16x32_bf16 v[0:3], v[84:87], v[150:153], v[0:3]
	ds_read_b128 v[80:83], v222 offset:128
	ds_read_b128 v[84:87], v222 offset:192
	s_waitcnt lgkmcnt(1)
	v_mfma_f32_16x16x32_bf16 v[8:11], v[76:79], v[80:83], v[8:11]
	v_mfma_f32_16x16x32_bf16 v[12:15], v[72:75], v[80:83], v[12:15]
	ds_read_b128 v[80:83], v222 offset:4480
	ds_read_b128 v[96:99], v222 offset:4544
	s_waitcnt lgkmcnt(1)
	v_mfma_f32_16x16x32_bf16 v[20:23], v[76:79], v[80:83], v[20:23]
	v_mfma_f32_16x16x32_bf16 v[16:19], v[72:75], v[80:83], v[16:19]
	ds_read_b128 v[80:83], v222 offset:8832
	ds_read_b128 v[146:149], v222 offset:8896
	s_waitcnt lgkmcnt(1)
	v_mfma_f32_16x16x32_bf16 v[24:27], v[76:79], v[80:83], v[24:27]
	v_mfma_f32_16x16x32_bf16 v[150:153], v[72:75], v[80:83], v[28:31]
	s_nop 2
	ds_read_b128 v[28:31], v222 offset:13184
	ds_read_b128 v[164:167], v222 offset:13248
	global_load_dwordx4 v[124:127], v[188:189], off offset:-4096
	global_load_dwordx4 v[132:135], v[144:145], off
	global_load_dwordx4 v[112:115], v[144:145], off offset:1024
	s_waitcnt lgkmcnt(1)
	v_mfma_f32_16x16x32_bf16 v[4:7], v[76:79], v[28:31], v[4:7]
	v_mfma_f32_16x16x32_bf16 v[72:75], v[72:75], v[28:31], v[0:3]
	v_mfma_f32_16x16x32_bf16 v[160:163], v[68:71], v[84:87], v[8:11]
	v_mfma_f32_16x16x32_bf16 v[8:11], v[68:71], v[146:149], v[24:27]
	global_load_dwordx4 v[116:119], v[142:143], off offset:1024
	global_load_dwordx4 v[76:79], v[142:143], off offset:2048
	global_load_dwordx4 v[80:83], v[144:145], off offset:2048
	global_load_dwordx4 v[28:31], v[144:145], off offset:3072
	global_load_dwordx4 v[24:27], v[142:143], off offset:3072
	ds_read2_b32 v[178:179], v220 offset1:16
	ds_read2_b32 v[176:177], v220 offset0:32 offset1:48
	s_waitcnt vmcnt(24)
	v_mfma_f32_16x16x32_bf16 v[84:87], v[64:67], v[84:87], v[12:15]
	s_waitcnt lgkmcnt(1)
	v_pk_fma_f32 v[158:159], v[162:163], v[178:179], 0 op_sel_hi:[1,0,0]
	v_mfma_f32_16x16x32_bf16 v[20:23], v[68:71], v[96:99], v[20:23]
	v_fma_f32 v160, v160, v178, 0
	v_fma_f32 v161, v161, v178, 0
	s_nop 2
	v_pk_fma_f32 v[162:163], v[86:87], v[178:179], 0 op_sel_hi:[1,0,0]
	v_pk_fma_f32 v[168:169], v[84:85], v[178:179], 0 op_sel_hi:[1,0,0]
	v_mfma_f32_16x16x32_bf16 v[16:19], v[64:67], v[96:99], v[16:19]
	v_mfma_f32_16x16x32_bf16 v[12:15], v[64:67], v[146:149], v[150:153]
	v_mfma_f32_16x16x32_bf16 v[0:3], v[68:71], v[164:167], v[4:7]
	v_mfma_f32_16x16x32_bf16 v[4:7], v[64:67], v[164:167], v[72:75]
	ds_read_b128 v[64:67], v217
	ds_read_b128 v[68:71], v217 offset:64
	ds_read_b128 v[84:87], v217 offset:8448
	ds_read_b128 v[96:99], v217 offset:8512
	ds_read_b128 v[150:153], v217 offset:16896
	ds_read_b128 v[164:167], v217 offset:16960
	ds_read_b128 v[180:183], v217 offset:25344
	ds_read_b128 v[184:187], v217 offset:25408
	s_waitcnt vmcnt(23) lgkmcnt(7)
	v_mfma_f32_16x16x32_bf16 v[72:75], v[128:131], v[64:67], 0
	s_movk_i32 s1, 0x4000
	s_movk_i32 s6, 0x5000
	s_movk_i32 s7, 0x6000
	s_waitcnt vmcnt(17)
	v_mfma_f32_16x16x32_bf16 v[64:67], v[136:139], v[64:67], 0
	s_movk_i32 s10, 0x7000
	s_waitcnt lgkmcnt(5)
	v_mfma_f32_16x16x32_bf16 v[146:149], v[128:131], v[84:87], 0
	v_mfma_f32_16x16x32_bf16 v[84:87], v[136:139], v[84:87], 0
	s_waitcnt lgkmcnt(3)
	v_mfma_f32_16x16x32_bf16 v[170:173], v[128:131], v[150:153], 0
	v_mfma_f32_16x16x32_bf16 v[150:153], v[136:139], v[150:153], 0
	s_waitcnt lgkmcnt(1)
	v_mfma_f32_16x16x32_bf16 v[128:131], v[128:131], v[180:183], 0
	v_mfma_f32_16x16x32_bf16 v[136:139], v[136:139], v[180:183], 0
	v_mfma_f32_16x16x32_bf16 v[72:75], v[108:111], v[68:71], v[72:75]
	v_mfma_f32_16x16x32_bf16 v[64:67], v[120:123], v[68:71], v[64:67]
	v_mfma_f32_16x16x32_bf16 v[68:71], v[108:111], v[96:99], v[146:149]
	v_mfma_f32_16x16x32_bf16 v[84:87], v[120:123], v[96:99], v[84:87]
	v_mfma_f32_16x16x32_bf16 v[96:99], v[108:111], v[164:167], v[170:173]
	v_mfma_f32_16x16x32_bf16 v[146:149], v[120:123], v[164:167], v[150:153]
	s_waitcnt lgkmcnt(0)
	v_mfma_f32_16x16x32_bf16 v[108:111], v[108:111], v[184:187], v[128:131]
	v_mfma_f32_16x16x32_bf16 v[120:123], v[120:123], v[184:187], v[136:139]
	s_nop 1
	ds_read_b128 v[128:131], v217 offset:128
	ds_read_b128 v[136:139], v217 offset:192
	s_waitcnt lgkmcnt(1)
	v_mfma_f32_16x16x32_bf16 v[72:75], v[60:63], v[128:131], v[72:75]
	v_mfma_f32_16x16x32_bf16 v[64:67], v[48:51], v[128:131], v[64:67]
	ds_read_b128 v[128:131], v217 offset:8576
	ds_read_b128 v[150:153], v217 offset:8640
	s_waitcnt lgkmcnt(1)
	v_mfma_f32_16x16x32_bf16 v[68:71], v[60:63], v[128:131], v[68:71]
	v_mfma_f32_16x16x32_bf16 v[84:87], v[48:51], v[128:131], v[84:87]
	ds_read_b128 v[128:131], v217 offset:17024
	ds_read_b128 v[164:167], v217 offset:17088
	s_waitcnt lgkmcnt(1)
	v_mfma_f32_16x16x32_bf16 v[96:99], v[60:63], v[128:131], v[96:99]
	v_mfma_f32_16x16x32_bf16 v[128:131], v[48:51], v[128:131], v[146:149]
	s_nop 2
	ds_read_b128 v[146:149], v217 offset:25472
	ds_read_b128 v[170:173], v217 offset:25536
	s_waitcnt lgkmcnt(1)
; #define LAS __attribute__((address_space(3)))
; __device__ void passB_unit(const Params& p, LAS unsigned char* lds, int u, bool do_store = true) {
;     ...
;     for (int q = 0; q < 12; ++q) {
;         const int nh = q / 6, d = (q % 6) / 3, kind = q % 3;
;         if (q + 2 < 12) PB_ISSUE(q + 2);
;         __builtin_amdgcn_sched_barrier(0);
;         if (kind == 0) {
; #pragma unroll
;             for (int mt = 0; mt < 4; ++mt)
; #pragma unroll
;                 for (int n2 = 0; n2 < 2; ++n2) { acc[mt][n2] = (f32x4){0.f, 0.f, 0.f, 0.f}; if (d == 0) hsum[mt][nh * 2 + n2] = (f32x4){0.f, 0.f, 0.f, 0.f}; }
;         }
;         if (kind < 2) {
; #pragma unroll
;             for (int ks = 0; ks < 4; ++ks) { bf16x8 qf[4];
; #pragma unroll
;                 for (int mt = 0; mt < 4; ++mt) qf[mt] = *(const LAS bf16x8*)(Qs + (wt2 * 64 + mt * 16 + fr) * 264 + (kind * 4 + ks) * 32 + fq * 8);
; #pragma unroll
;                 for (int mt = 0; mt < 4; ++mt)
; #pragma unroll
;                     for (int n2 = 0; n2 < 2; ++n2) acc[mt][n2] = __builtin_amdgcn_mfma_f32_16x16x32_bf16(F[q % 3][ks][n2], qf[mt], acc[mt][n2], 0, 0, 0); }
;         } else {
;             const LAS bf16_t* Pp = Pd + d * 128 * 136;
; #pragma unroll
;             for (int mt = 0; mt < 4; ++mt) { const float wv = winA[d * 128 + wt2 * 64 + mt * 16 + fr];
; #pragma unroll
;                 for (int n2 = 0; n2 < 2; ++n2) acc[mt][n2] *= wv; }
; #pragma unroll
;             for (int ks = 0; ks < 4; ++ks) { bf16x8 pf[4];
; #pragma unroll
;                 for (int mt = 0; mt < 4; ++mt) pf[mt] = *(const LAS bf16x8*)(Pp + (wt2 * 64 + mt * 16 + fr) * 136 + ks * 32 + fq * 8);
; #pragma unroll
;                 for (int mt = 0; mt < 4; ++mt)
; #pragma unroll
;                     for (int n2 = 0; n2 < 2; ++n2) acc[mt][n2] = __builtin_amdgcn_mfma_f32_16x16x32_bf16(F[q % 3][ks][n2], pf[mt], acc[mt][n2], 0, 0, 0); }
; #pragma unroll
;             for (int mt = 0; mt < 4; ++mt) { const float iv = invA[d * 128 + wt2 * 64 + mt * 16 + fr];
; #pragma unroll
;                 for (int n2 = 0; n2 < 2; ++n2) hsum[mt][nh * 2 + n2] += acc[mt][n2] * iv; }
	v_mfma_f32_16x16x32_bf16 v[60:63], v[60:63], v[146:149], v[108:111]
	v_mfma_f32_16x16x32_bf16 v[108:111], v[48:51], v[146:149], v[120:123]
	v_add_co_u32_e32 v48, vcc, s1, v140
	s_nop 1
	v_addc_co_u32_e32 v49, vcc, 0, v141, vcc
	v_add_co_u32_e32 v146, vcc, s6, v140
	v_mfma_f32_16x16x32_bf16 v[72:75], v[40:43], v[136:139], v[72:75]
	s_nop 0
	v_addc_co_u32_e32 v147, vcc, 0, v141, vcc
	v_add_co_u32_e32 v50, vcc, s7, v140
	s_waitcnt vmcnt(16)
	v_mfma_f32_16x16x32_bf16 v[64:67], v[32:35], v[136:139], v[64:67]
	v_addc_co_u32_e32 v51, vcc, 0, v141, vcc
	v_add_co_u32_e32 v174, vcc, s10, v140
	v_mfma_f32_16x16x32_bf16 v[68:71], v[40:43], v[150:153], v[68:71]
	s_nop 0
	v_addc_co_u32_e32 v175, vcc, 0, v141, vcc
	v_mfma_f32_16x16x32_bf16 v[152:155], v[32:35], v[150:153], v[84:87]
	global_load_dwordx4 v[140:143], v[146:147], off offset:-4096 nt
	global_load_dwordx4 v[148:151], v[174:175], off offset:-4096 nt
	global_load_dwordx4 v[120:123], v[48:49], off offset:1024 nt
	global_load_dwordx4 v[84:87], v[48:49], off offset:2048 nt
	v_mfma_f32_16x16x32_bf16 v[180:183], v[40:43], v[164:167], v[96:99]
	s_waitcnt lgkmcnt(0)
	v_mfma_f32_16x16x32_bf16 v[40:43], v[40:43], v[170:173], v[60:63]
	global_load_dwordx4 v[136:139], v[50:51], off offset:1024 nt
	s_nop 1
	global_load_dwordx4 v[60:63], v[48:49], off offset:3072 nt
	global_load_dwordx4 v[96:99], v[50:51], off offset:2048 nt
	s_nop 0
	global_load_dwordx4 v[48:51], v[50:51], off offset:3072 nt
	v_mfma_f32_16x16x32_bf16 v[128:131], v[32:35], v[164:167], v[128:131]
	v_mfma_f32_16x16x32_bf16 v[32:35], v[32:35], v[170:173], v[108:111]
	s_nop 2
	ds_read_b128 v[108:111], v217 offset:256
	ds_read_b128 v[164:167], v217 offset:320
	s_waitcnt vmcnt(23) lgkmcnt(1)
	v_mfma_f32_16x16x32_bf16 v[72:75], v[100:103], v[108:111], v[72:75]
	s_waitcnt vmcnt(21)
	v_mfma_f32_16x16x32_bf16 v[64:67], v[104:107], v[108:111], v[64:67]
	ds_read_b128 v[108:111], v217 offset:8704
	ds_read_b128 v[170:173], v217 offset:8768
	s_waitcnt lgkmcnt(1)
	v_mfma_f32_16x16x32_bf16 v[68:71], v[100:103], v[108:111], v[68:71]
	v_mfma_f32_16x16x32_bf16 v[108:111], v[104:107], v[108:111], v[152:155]
	s_nop 2
	ds_read_b128 v[152:155], v217 offset:17152
	ds_read_b128 v[184:187], v217 offset:17216
	s_waitcnt lgkmcnt(1)
	v_mfma_f32_16x16x32_bf16 v[180:183], v[100:103], v[152:155], v[180:183]
	v_mfma_f32_16x16x32_bf16 v[128:131], v[104:107], v[152:155], v[128:131]
	ds_read_b128 v[152:155], v217 offset:25600
	ds_read_b128 v[190:193], v217 offset:25664
	s_waitcnt lgkmcnt(1)
	v_mfma_f32_16x16x32_bf16 v[40:43], v[100:103], v[152:155], v[40:43]
	v_mfma_f32_16x16x32_bf16 v[32:35], v[104:107], v[152:155], v[32:35]
	v_mfma_f32_16x16x32_bf16 v[72:75], v[88:91], v[164:167], v[72:75]
	s_waitcnt vmcnt(20)
	v_mfma_f32_16x16x32_bf16 v[64:67], v[92:95], v[164:167], v[64:67]
	v_mfma_f32_16x16x32_bf16 v[68:71], v[88:91], v[170:173], v[68:71]
	v_mfma_f32_16x16x32_bf16 v[100:103], v[92:95], v[170:173], v[108:111]
	v_mfma_f32_16x16x32_bf16 v[104:107], v[88:91], v[184:187], v[180:183]
	v_mfma_f32_16x16x32_bf16 v[108:111], v[92:95], v[184:187], v[128:131]
	s_waitcnt lgkmcnt(0)
	v_mfma_f32_16x16x32_bf16 v[40:43], v[88:91], v[190:193], v[40:43]
	v_mfma_f32_16x16x32_bf16 v[32:35], v[92:95], v[190:193], v[32:35]
	ds_read_b128 v[88:91], v217 offset:384
	ds_read_b128 v[92:95], v217 offset:448
	s_waitcnt vmcnt(19) lgkmcnt(1)
	v_mfma_f32_16x16x32_bf16 v[72:75], v[52:55], v[88:91], v[72:75]
	s_waitcnt vmcnt(17)
	v_mfma_f32_16x16x32_bf16 v[64:67], v[56:59], v[88:91], v[64:67]
	ds_read_b128 v[88:91], v217 offset:8832
	ds_read_b128 v[128:131], v217 offset:8896
	s_waitcnt lgkmcnt(1)
	v_mfma_f32_16x16x32_bf16 v[68:71], v[52:55], v[88:91], v[68:71]
	v_mfma_f32_16x16x32_bf16 v[88:91], v[56:59], v[88:91], v[100:103]
	s_nop 2
	ds_read_b128 v[100:103], v217 offset:17280
	ds_read_b128 v[152:155], v217 offset:17344
	s_waitcnt lgkmcnt(1)
	v_mfma_f32_16x16x32_bf16 v[104:107], v[52:55], v[100:103], v[104:107]
	v_mfma_f32_16x16x32_bf16 v[100:103], v[56:59], v[100:103], v[108:111]
	s_nop 2
	ds_read_b128 v[108:111], v217 offset:25728
	ds_read_b128 v[164:167], v217 offset:25792
	s_waitcnt lgkmcnt(1)
	v_mfma_f32_16x16x32_bf16 v[40:43], v[52:55], v[108:111], v[40:43]
	v_mfma_f32_16x16x32_bf16 v[32:35], v[56:59], v[108:111], v[32:35]
	v_mfma_f32_16x16x32_bf16 v[52:55], v[44:47], v[92:95], v[72:75]
	s_waitcnt vmcnt(16)
	v_mfma_f32_16x16x32_bf16 v[92:95], v[36:39], v[92:95], v[64:67]
	v_mfma_f32_16x16x32_bf16 v[170:173], v[44:47], v[128:131], v[68:71]
	v_mfma_f32_16x16x32_bf16 v[128:131], v[36:39], v[128:131], v[88:91]
	v_mfma_f32_16x16x32_bf16 v[180:183], v[44:47], v[152:155], v[104:107]
	v_mfma_f32_16x16x32_bf16 v[152:155], v[36:39], v[152:155], v[100:103]
	s_nop 1
	global_load_dwordx4 v[104:107], v[146:147], off nt
	global_load_dwordx4 v[88:91], v[146:147], off offset:1024 nt
	global_load_dwordx4 v[108:111], v[174:175], off nt
	global_load_dwordx4 v[100:103], v[174:175], off offset:1024 nt
	global_load_dwordx4 v[68:71], v[146:147], off offset:2048 nt
	global_load_dwordx4 v[64:67], v[146:147], off offset:3072 nt
	global_load_dwordx4 v[72:75], v[174:175], off offset:2048 nt
	global_load_dwordx4 v[56:59], v[174:175], off offset:3072 nt
	s_waitcnt lgkmcnt(0)
	v_mfma_f32_16x16x32_bf16 v[40:43], v[44:47], v[164:167], v[40:43]
	v_mfma_f32_16x16x32_bf16 v[32:35], v[36:39], v[164:167], v[32:35]
	ds_read2_b32 v[146:147], v221 offset0:128 offset1:144
	ds_read_b128 v[36:39], v222 offset:34816
	ds_read2_b32 v[174:175], v221 offset0:160 offset1:176
	ds_read_b128 v[184:187], v222 offset:39232
	ds_read_b128 v[190:193], v222 offset:43520
	s_waitcnt lgkmcnt(4)
; #define LAS __attribute__((address_space(3)))
; __device__ void passB_unit(const Params& p, LAS unsigned char* lds, int u, bool do_store = true) {
;     ...
;     for (int q = 0; q < 12; ++q) {
;         const int nh = q / 6, d = (q % 6) / 3, kind = q % 3;
;         if (q + 2 < 12) PB_ISSUE(q + 2);
;         __builtin_amdgcn_sched_barrier(0);
;         if (kind == 0) {
; #pragma unroll
;             for (int mt = 0; mt < 4; ++mt)
; #pragma unroll
;                 for (int n2 = 0; n2 < 2; ++n2) { acc[mt][n2] = (f32x4){0.f, 0.f, 0.f, 0.f}; if (d == 0) hsum[mt][nh * 2 + n2] = (f32x4){0.f, 0.f, 0.f, 0.f}; }
;         }
;         if (kind < 2) {
; #pragma unroll
;             for (int ks = 0; ks < 4; ++ks) { bf16x8 qf[4];
; #pragma unroll
;                 for (int mt = 0; mt < 4; ++mt) qf[mt] = *(const LAS bf16x8*)(Qs + (wt2 * 64 + mt * 16 + fr) * 264 + (kind * 4 + ks) * 32 + fq * 8);
; #pragma unroll
;                 for (int mt = 0; mt < 4; ++mt)
; #pragma unroll
;                     for (int n2 = 0; n2 < 2; ++n2) acc[mt][n2] = __builtin_amdgcn_mfma_f32_16x16x32_bf16(F[q % 3][ks][n2], qf[mt], acc[mt][n2], 0, 0, 0); }
;         } else {
;             const LAS bf16_t* Pp = Pd + d * 128 * 136;
; #pragma unroll
;             for (int mt = 0; mt < 4; ++mt) { const float wv = winA[d * 128 + wt2 * 64 + mt * 16 + fr];
; #pragma unroll
;                 for (int n2 = 0; n2 < 2; ++n2) acc[mt][n2] *= wv; }
; #pragma unroll
;             for (int ks = 0; ks < 4; ++ks) { bf16x8 pf[4];
; #pragma unroll
;                 for (int mt = 0; mt < 4; ++mt) pf[mt] = *(const LAS bf16x8*)(Pp + (wt2 * 64 + mt * 16 + fr) * 136 + ks * 32 + fq * 8);
; #pragma unroll
;                 for (int mt = 0; mt < 4; ++mt)
; #pragma unroll
;                     for (int n2 = 0; n2 < 2; ++n2) acc[mt][n2] = __builtin_amdgcn_mfma_f32_16x16x32_bf16(F[q % 3][ks][n2], pf[mt], acc[mt][n2], 0, 0, 0); }
; #pragma unroll
;             for (int mt = 0; mt < 4; ++mt) { const float iv = invA[d * 128 + wt2 * 64 + mt * 16 + fr];
; #pragma unroll
;                 for (int n2 = 0; n2 < 2; ++n2) hsum[mt][nh * 2 + n2] += acc[mt][n2] * iv; }
	v_pk_mul_f32 v[46:47], v[54:55], v[146:147] op_sel_hi:[1,0]
	v_pk_mul_f32 v[44:45], v[52:53], v[146:147] op_sel_hi:[1,0]
	v_pk_mul_f32 v[54:55], v[94:95], v[146:147] op_sel_hi:[1,0]
	v_pk_mul_f32 v[52:53], v[92:93], v[146:147] op_sel_hi:[1,0]
	v_mov_b32_e32 v146, v147
	ds_read_b128 v[92:95], v222 offset:34880
	v_pk_mul_f32 v[166:167], v[172:173], v[146:147] op_sel_hi:[1,0]
	v_pk_mul_f32 v[164:165], v[170:171], v[146:147] op_sel_hi:[1,0]
	ds_read_b128 v[170:173], v222 offset:39168
	s_waitcnt vmcnt(22) lgkmcnt(5)
	v_mfma_f32_16x16x32_bf16 v[44:47], v[132:135], v[36:39], v[44:47]
	s_waitcnt lgkmcnt(4)
	v_pk_mul_f32 v[154:155], v[154:155], v[174:175] op_sel_hi:[1,0]
	v_pk_mul_f32 v[152:153], v[152:153], v[174:175] op_sel_hi:[1,0]
	v_add_co_u32_e32 v194, vcc, s0, v144
	v_mfma_f32_16x16x32_bf16 v[36:39], v[124:127], v[36:39], v[52:55]
	s_nop 0
	v_addc_co_u32_e32 v195, vcc, 0, v145, vcc
	s_nop 0
	v_pk_mul_f32 v[54:55], v[130:131], v[146:147] op_sel_hi:[1,0]
	v_pk_mul_f32 v[52:53], v[128:129], v[146:147] op_sel_hi:[1,0]
	s_waitcnt lgkmcnt(0)
	v_mfma_f32_16x16x32_bf16 v[164:167], v[132:135], v[170:173], v[164:167]
	v_mul_f32_e64 v130, v182, v174
	v_mul_f32_e64 v131, v183, v174
	v_pk_mul_f32 v[128:129], v[180:181], v[174:175] op_sel_hi:[1,0]
	ds_read_b128 v[180:183], v222 offset:47872
	v_mfma_f32_16x16x32_bf16 v[52:55], v[124:127], v[170:173], v[52:55]
	ds_read_b128 v[170:173], v222 offset:43584
	v_mov_b32_e32 v146, v175
	v_pk_mul_f32 v[42:43], v[42:43], v[146:147] op_sel_hi:[1,0]
	v_mfma_f32_16x16x32_bf16 v[128:131], v[132:135], v[190:193], v[128:131]
	v_mul_f32_e64 v40, v40, v146
	v_mul_f32_e64 v41, v41, v146
	v_pk_mul_f32 v[34:35], v[34:35], v[146:147] op_sel_hi:[1,0]
	v_pk_mul_f32 v[32:33], v[32:33], v[146:147] op_sel_hi:[1,0]
	v_mfma_f32_16x16x32_bf16 v[152:155], v[124:127], v[190:193], v[152:155]
	ds_read_b128 v[190:193], v222 offset:47936
	s_waitcnt lgkmcnt(2)
	v_mfma_f32_16x16x32_bf16 v[40:43], v[132:135], v[180:183], v[40:43]
	v_mfma_f32_16x16x32_bf16 v[32:35], v[124:127], v[180:183], v[32:35]
	s_waitcnt vmcnt(21)
	v_mfma_f32_16x16x32_bf16 v[44:47], v[112:115], v[92:95], v[44:47]
	s_waitcnt vmcnt(20)
	v_mfma_f32_16x16x32_bf16 v[36:39], v[116:119], v[92:95], v[36:39]
	v_mfma_f32_16x16x32_bf16 v[92:95], v[112:115], v[184:187], v[164:167]
	v_mfma_f32_16x16x32_bf16 v[52:55], v[116:119], v[184:187], v[52:55]
	s_waitcnt lgkmcnt(1)
	v_mfma_f32_16x16x32_bf16 v[124:127], v[112:115], v[170:173], v[128:131]
	v_mfma_f32_16x16x32_bf16 v[128:131], v[116:119], v[170:173], v[152:155]
	s_waitcnt lgkmcnt(0)
	v_mfma_f32_16x16x32_bf16 v[40:43], v[112:115], v[190:193], v[40:43]
	v_mfma_f32_16x16x32_bf16 v[32:35], v[116:119], v[190:193], v[32:35]
	ds_read_b128 v[112:115], v222 offset:34944
	ds_read_b128 v[116:119], v222 offset:35008
	s_waitcnt vmcnt(18) lgkmcnt(1)
	v_mfma_f32_16x16x32_bf16 v[44:47], v[80:83], v[112:115], v[44:47]
	v_mfma_f32_16x16x32_bf16 v[36:39], v[76:79], v[112:115], v[36:39]
	ds_read_b128 v[112:115], v222 offset:39296
	ds_read_b128 v[132:135], v222 offset:39360
	s_waitcnt lgkmcnt(1)
	v_mfma_f32_16x16x32_bf16 v[92:95], v[80:83], v[112:115], v[92:95]
	v_mfma_f32_16x16x32_bf16 v[52:55], v[76:79], v[112:115], v[52:55]
	ds_read_b128 v[112:115], v222 offset:43648
	ds_read_b128 v[170:173], v222 offset:43712
	s_waitcnt lgkmcnt(1)
	v_mfma_f32_16x16x32_bf16 v[124:127], v[80:83], v[112:115], v[124:127]
	v_mfma_f32_16x16x32_bf16 v[112:115], v[76:79], v[112:115], v[128:131]
	s_nop 2
	ds_read_b128 v[128:131], v222 offset:48000
	ds_read_b128 v[228:231], v222 offset:48064
	s_waitcnt lgkmcnt(1)
	v_mfma_f32_16x16x32_bf16 v[80:83], v[80:83], v[128:131], v[40:43]
	v_mfma_f32_16x16x32_bf16 v[232:235], v[76:79], v[128:131], v[32:35]
	s_waitcnt vmcnt(17)
	v_mfma_f32_16x16x32_bf16 v[180:183], v[28:31], v[116:119], v[44:47]
	v_mfma_f32_16x16x32_bf16 v[40:43], v[28:31], v[132:135], v[92:95]
	s_waitcnt vmcnt(16)
	v_mfma_f32_16x16x32_bf16 v[44:47], v[24:27], v[132:135], v[52:55]
	global_load_dwordx4 v[152:155], v[188:189], off
	global_load_dwordx4 v[132:135], v[188:189], off offset:1024
	global_load_dwordx4 v[164:167], v[194:195], off
	global_load_dwordx4 v[144:147], v[194:195], off offset:1024
	global_load_dwordx4 v[76:79], v[188:189], off offset:2048
	global_load_dwordx4 v[128:131], v[188:189], off offset:3072
	global_load_dwordx4 v[92:95], v[194:195], off offset:2048
	global_load_dwordx4 v[52:55], v[194:195], off offset:3072
	ds_read2_b32 v[192:193], v220 offset0:128 offset1:144
	v_mfma_f32_16x16x32_bf16 v[116:119], v[24:27], v[116:119], v[36:39]
	ds_read2_b32 v[190:191], v220 offset0:160 offset1:176
	s_waitcnt lgkmcnt(1)
	v_pk_fma_f32 v[184:185], v[182:183], v[192:193], v[158:159] op_sel_hi:[1,0,1]
	v_mfma_f32_16x16x32_bf16 v[32:35], v[28:31], v[170:173], v[124:127]
	v_fma_f32 v186, v180, v192, v160
	v_fma_f32 v187, v181, v192, v161
	s_nop 1
	v_pk_fma_f32 v[180:181], v[118:119], v[192:193], v[162:163] op_sel_hi:[1,0,1]
	v_pk_fma_f32 v[182:183], v[116:117], v[192:193], v[168:169] op_sel_hi:[1,0,1]
	v_mfma_f32_16x16x32_bf16 v[36:39], v[24:27], v[170:173], v[112:115]
	v_mfma_f32_16x16x32_bf16 v[28:31], v[28:31], v[228:231], v[80:83]
	v_mfma_f32_16x16x32_bf16 v[24:27], v[24:27], v[228:231], v[232:235]
	s_nop 1
	ds_read_b128 v[80:83], v217
	ds_read_b128 v[112:115], v217 offset:64
	ds_read_b128 v[124:127], v217 offset:8448
	ds_read_b128 v[158:161], v217 offset:8512
	ds_read_b128 v[172:175], v217 offset:16896
	ds_read_b128 v[228:231], v217 offset:16960
	ds_read_b128 v[236:239], v217 offset:25344
	ds_read_b128 v[240:243], v217 offset:25408
	s_waitcnt vmcnt(23) lgkmcnt(7)
	v_mfma_f32_16x16x32_bf16 v[116:119], v[140:143], v[80:83], 0
	s_waitcnt vmcnt(22)
; #define LAS __attribute__((address_space(3)))
; __device__ void passB_unit(const Params& p, LAS unsigned char* lds, int u, bool do_store = true) {
;     ...
;     for (int q = 0; q < 12; ++q) {
;         const int nh = q / 6, d = (q % 6) / 3, kind = q % 3;
;         if (q + 2 < 12) PB_ISSUE(q + 2);
;         __builtin_amdgcn_sched_barrier(0);
;         if (kind == 0) {
; #pragma unroll
;             for (int mt = 0; mt < 4; ++mt)
; #pragma unroll
;                 for (int n2 = 0; n2 < 2; ++n2) { acc[mt][n2] = (f32x4){0.f, 0.f, 0.f, 0.f}; if (d == 0) hsum[mt][nh * 2 + n2] = (f32x4){0.f, 0.f, 0.f, 0.f}; }
;         }
;         if (kind < 2) {
; #pragma unroll
;             for (int ks = 0; ks < 4; ++ks) { bf16x8 qf[4];
; #pragma unroll
;                 for (int mt = 0; mt < 4; ++mt) qf[mt] = *(const LAS bf16x8*)(Qs + (wt2 * 64 + mt * 16 + fr) * 264 + (kind * 4 + ks) * 32 + fq * 8);
; #pragma unroll
;                 for (int mt = 0; mt < 4; ++mt)
; #pragma unroll
;                     for (int n2 = 0; n2 < 2; ++n2) acc[mt][n2] = __builtin_amdgcn_mfma_f32_16x16x32_bf16(F[q % 3][ks][n2], qf[mt], acc[mt][n2], 0, 0, 0); }
;         } else {
;             const LAS bf16_t* Pp = Pd + d * 128 * 136;
; #pragma unroll
;             for (int mt = 0; mt < 4; ++mt) { const float wv = winA[d * 128 + wt2 * 64 + mt * 16 + fr];
; #pragma unroll
;                 for (int n2 = 0; n2 < 2; ++n2) acc[mt][n2] *= wv; }
; #pragma unroll
;             for (int ks = 0; ks < 4; ++ks) { bf16x8 pf[4];
; #pragma unroll
;                 for (int mt = 0; mt < 4; ++mt) pf[mt] = *(const LAS bf16x8*)(Pp + (wt2 * 64 + mt * 16 + fr) * 136 + ks * 32 + fq * 8);
; #pragma unroll
;                 for (int mt = 0; mt < 4; ++mt)
; #pragma unroll
;                     for (int n2 = 0; n2 < 2; ++n2) acc[mt][n2] = __builtin_amdgcn_mfma_f32_16x16x32_bf16(F[q % 3][ks][n2], pf[mt], acc[mt][n2], 0, 0, 0); }
; #pragma unroll
;             for (int mt = 0; mt < 4; ++mt) { const float iv = invA[d * 128 + wt2 * 64 + mt * 16 + fr];
; #pragma unroll
;                 for (int n2 = 0; n2 < 2; ++n2) hsum[mt][nh * 2 + n2] += acc[mt][n2] * iv; }
	v_mfma_f32_16x16x32_bf16 v[80:83], v[148:151], v[80:83], 0
	s_waitcnt lgkmcnt(5)
	v_mfma_f32_16x16x32_bf16 v[168:171], v[140:143], v[124:127], 0
	v_mfma_f32_16x16x32_bf16 v[124:127], v[148:151], v[124:127], 0
	s_waitcnt lgkmcnt(3)
	v_mfma_f32_16x16x32_bf16 v[232:235], v[140:143], v[172:175], 0
	v_mfma_f32_16x16x32_bf16 v[172:175], v[148:151], v[172:175], 0
	s_waitcnt lgkmcnt(1)
	v_mfma_f32_16x16x32_bf16 v[140:143], v[140:143], v[236:239], 0
	v_mfma_f32_16x16x32_bf16 v[148:151], v[148:151], v[236:239], 0
	s_waitcnt vmcnt(21)
	v_mfma_f32_16x16x32_bf16 v[116:119], v[120:123], v[112:115], v[116:119]
	s_waitcnt vmcnt(19)
	v_mfma_f32_16x16x32_bf16 v[80:83], v[136:139], v[112:115], v[80:83]
	v_mfma_f32_16x16x32_bf16 v[112:115], v[120:123], v[158:161], v[168:171]
	v_mfma_f32_16x16x32_bf16 v[124:127], v[136:139], v[158:161], v[124:127]
	v_mfma_f32_16x16x32_bf16 v[158:161], v[120:123], v[228:231], v[232:235]
	v_mfma_f32_16x16x32_bf16 v[168:171], v[136:139], v[228:231], v[172:175]
	s_waitcnt lgkmcnt(0)
	v_mfma_f32_16x16x32_bf16 v[120:123], v[120:123], v[240:243], v[140:143]
	v_mfma_f32_16x16x32_bf16 v[136:139], v[136:139], v[240:243], v[148:151]
	s_nop 1
	ds_read_b128 v[140:143], v217 offset:128
	ds_read_b128 v[148:151], v217 offset:192
	s_waitcnt lgkmcnt(1)
	v_mfma_f32_16x16x32_bf16 v[116:119], v[84:87], v[140:143], v[116:119]
	s_waitcnt vmcnt(17)
	v_mfma_f32_16x16x32_bf16 v[80:83], v[96:99], v[140:143], v[80:83]
	ds_read_b128 v[140:143], v217 offset:8576
	ds_read_b128 v[172:175], v217 offset:8640
	s_waitcnt lgkmcnt(1)
	v_mfma_f32_16x16x32_bf16 v[112:115], v[84:87], v[140:143], v[112:115]
	v_mfma_f32_16x16x32_bf16 v[124:127], v[96:99], v[140:143], v[124:127]
	ds_read_b128 v[140:143], v217 offset:17024
	ds_read_b128 v[228:231], v217 offset:17088
	s_waitcnt lgkmcnt(1)
	v_mfma_f32_16x16x32_bf16 v[158:161], v[84:87], v[140:143], v[158:161]
	v_mfma_f32_16x16x32_bf16 v[140:143], v[96:99], v[140:143], v[168:171]
	s_nop 2
	ds_read_b128 v[168:171], v217 offset:25472
	ds_read_b128 v[232:235], v217 offset:25536
	s_waitcnt lgkmcnt(1)
	v_mfma_f32_16x16x32_bf16 v[84:87], v[84:87], v[168:171], v[120:123]
	s_waitcnt vmcnt(16)
	v_mfma_f32_16x16x32_bf16 v[120:123], v[48:51], v[148:151], v[80:83]
	s_nop 2
	v_add_co_u32_e32 v80, vcc, s1, v156
	v_mfma_f32_16x16x32_bf16 v[96:99], v[96:99], v[168:171], v[136:139]
	s_nop 0
	v_addc_co_u32_e32 v81, vcc, 0, v157, vcc
	v_add_co_u32_e32 v206, vcc, s6, v156
	v_mfma_f32_16x16x32_bf16 v[116:119], v[60:63], v[148:151], v[116:119]
	s_nop 0
	v_addc_co_u32_e32 v207, vcc, 0, v157, vcc
	v_add_co_u32_e32 v208, vcc, s7, v156
	v_mfma_f32_16x16x32_bf16 v[112:115], v[60:63], v[172:175], v[112:115]
	s_nop 0
	v_addc_co_u32_e32 v209, vcc, 0, v157, vcc
	v_add_co_u32_e32 v248, vcc, s10, v156
	v_mfma_f32_16x16x32_bf16 v[124:127], v[48:51], v[172:175], v[124:127]
	s_nop 0
	v_addc_co_u32_e32 v249, vcc, 0, v157, vcc
	v_mfma_f32_16x16x32_bf16 v[148:151], v[60:63], v[228:231], v[158:161]
	global_load_dwordx4 v[168:171], v[206:207], off offset:-4096 nt
	global_load_dwordx4 v[172:175], v[248:249], off offset:-4096 nt
	s_nop 0
	global_load_dwordx4 v[156:159], v[80:81], off offset:1024 nt
	global_load_dwordx4 v[136:139], v[80:81], off offset:2048 nt
	v_mfma_f32_16x16x32_bf16 v[228:231], v[48:51], v[228:231], v[140:143]
	s_waitcnt lgkmcnt(0)
	v_mfma_f32_16x16x32_bf16 v[60:63], v[60:63], v[232:235], v[84:87]
	global_load_dwordx4 v[160:163], v[208:209], off offset:1024 nt
	s_nop 0
	global_load_dwordx4 v[80:83], v[80:81], off offset:3072 nt
	s_nop 0
	global_load_dwordx4 v[140:143], v[208:209], off offset:2048 nt
	global_load_dwordx4 v[84:87], v[208:209], off offset:3072 nt
	v_mfma_f32_16x16x32_bf16 v[48:51], v[48:51], v[232:235], v[96:99]
	s_nop 2
	ds_read_b128 v[96:99], v217 offset:256
	ds_read_b128 v[232:235], v217 offset:320
	s_waitcnt vmcnt(23) lgkmcnt(1)
	v_mfma_f32_16x16x32_bf16 v[116:119], v[104:107], v[96:99], v[116:119]
	s_waitcnt vmcnt(21)
	v_mfma_f32_16x16x32_bf16 v[96:99], v[108:111], v[96:99], v[120:123]
	s_nop 2
	ds_read_b128 v[120:123], v217 offset:8704
	ds_read_b128 v[236:239], v217 offset:8768
	s_waitcnt lgkmcnt(1)
	v_mfma_f32_16x16x32_bf16 v[112:115], v[104:107], v[120:123], v[112:115]
	v_mfma_f32_16x16x32_bf16 v[120:123], v[108:111], v[120:123], v[124:127]
	s_nop 2
	ds_read_b128 v[124:127], v217 offset:17152
	ds_read_b128 v[240:243], v217 offset:17216
	s_waitcnt lgkmcnt(1)
	v_mfma_f32_16x16x32_bf16 v[148:151], v[104:107], v[124:127], v[148:151]
	v_mfma_f32_16x16x32_bf16 v[124:127], v[108:111], v[124:127], v[228:231]
	s_nop 2
	ds_read_b128 v[228:231], v217 offset:25600
	ds_read_b128 v[244:247], v217 offset:25664
	s_waitcnt lgkmcnt(1)
	v_mfma_f32_16x16x32_bf16 v[60:63], v[104:107], v[228:231], v[60:63]
	v_mfma_f32_16x16x32_bf16 v[48:51], v[108:111], v[228:231], v[48:51]
	v_mfma_f32_16x16x32_bf16 v[104:107], v[88:91], v[232:235], v[116:119]
	s_waitcnt vmcnt(20)
	v_mfma_f32_16x16x32_bf16 v[96:99], v[100:103], v[232:235], v[96:99]
	v_mfma_f32_16x16x32_bf16 v[108:111], v[88:91], v[236:239], v[112:115]
	v_mfma_f32_16x16x32_bf16 v[112:115], v[100:103], v[236:239], v[120:123]
	v_mfma_f32_16x16x32_bf16 v[116:119], v[88:91], v[240:243], v[148:151]
	v_mfma_f32_16x16x32_bf16 v[120:123], v[100:103], v[240:243], v[124:127]
	s_waitcnt lgkmcnt(0)
	v_mfma_f32_16x16x32_bf16 v[60:63], v[88:91], v[244:247], v[60:63]
	v_mfma_f32_16x16x32_bf16 v[48:51], v[100:103], v[244:247], v[48:51]
	ds_read_b128 v[88:91], v217 offset:384
	ds_read_b128 v[100:103], v217 offset:448
	s_waitcnt vmcnt(19) lgkmcnt(1)
	v_mfma_f32_16x16x32_bf16 v[104:107], v[68:71], v[88:91], v[104:107]
	s_waitcnt vmcnt(17)
; #define LAS __attribute__((address_space(3)))
; __device__ void passB_unit(const Params& p, LAS unsigned char* lds, int u, bool do_store = true) {
;     ...
;     for (int q = 0; q < 12; ++q) {
;         const int nh = q / 6, d = (q % 6) / 3, kind = q % 3;
;         if (q + 2 < 12) PB_ISSUE(q + 2);
;         __builtin_amdgcn_sched_barrier(0);
;         if (kind == 0) {
; #pragma unroll
;             for (int mt = 0; mt < 4; ++mt)
; #pragma unroll
;                 for (int n2 = 0; n2 < 2; ++n2) { acc[mt][n2] = (f32x4){0.f, 0.f, 0.f, 0.f}; if (d == 0) hsum[mt][nh * 2 + n2] = (f32x4){0.f, 0.f, 0.f, 0.f}; }
;         }
;         if (kind < 2) {
; #pragma unroll
;             for (int ks = 0; ks < 4; ++ks) { bf16x8 qf[4];
; #pragma unroll
;                 for (int mt = 0; mt < 4; ++mt) qf[mt] = *(const LAS bf16x8*)(Qs + (wt2 * 64 + mt * 16 + fr) * 264 + (kind * 4 + ks) * 32 + fq * 8);
; #pragma unroll
;                 for (int mt = 0; mt < 4; ++mt)
; #pragma unroll
;                     for (int n2 = 0; n2 < 2; ++n2) acc[mt][n2] = __builtin_amdgcn_mfma_f32_16x16x32_bf16(F[q % 3][ks][n2], qf[mt], acc[mt][n2], 0, 0, 0); }
;         } else {
;             const LAS bf16_t* Pp = Pd + d * 128 * 136;
; #pragma unroll
;             for (int mt = 0; mt < 4; ++mt) { const float wv = winA[d * 128 + wt2 * 64 + mt * 16 + fr];
; #pragma unroll
;                 for (int n2 = 0; n2 < 2; ++n2) acc[mt][n2] *= wv; }
; #pragma unroll
;             for (int ks = 0; ks < 4; ++ks) { bf16x8 pf[4];
; #pragma unroll
;                 for (int mt = 0; mt < 4; ++mt) pf[mt] = *(const LAS bf16x8*)(Pp + (wt2 * 64 + mt * 16 + fr) * 136 + ks * 32 + fq * 8);
; #pragma unroll
;                 for (int mt = 0; mt < 4; ++mt)
; #pragma unroll
;                     for (int n2 = 0; n2 < 2; ++n2) acc[mt][n2] = __builtin_amdgcn_mfma_f32_16x16x32_bf16(F[q % 3][ks][n2], pf[mt], acc[mt][n2], 0, 0, 0); }
; #pragma unroll
;             for (int mt = 0; mt < 4; ++mt) { const float iv = invA[d * 128 + wt2 * 64 + mt * 16 + fr];
; #pragma unroll
;                 for (int n2 = 0; n2 < 2; ++n2) hsum[mt][nh * 2 + n2] += acc[mt][n2] * iv; }
	v_mfma_f32_16x16x32_bf16 v[88:91], v[72:75], v[88:91], v[96:99]
	s_nop 2
	ds_read_b128 v[96:99], v217 offset:8832
	ds_read_b128 v[124:127], v217 offset:8896
	s_waitcnt lgkmcnt(1)
	v_mfma_f32_16x16x32_bf16 v[108:111], v[68:71], v[96:99], v[108:111]
	v_mfma_f32_16x16x32_bf16 v[96:99], v[72:75], v[96:99], v[112:115]
	s_nop 2
	ds_read_b128 v[112:115], v217 offset:17280
	ds_read_b128 v[148:151], v217 offset:17344
	s_waitcnt lgkmcnt(1)
	v_mfma_f32_16x16x32_bf16 v[116:119], v[68:71], v[112:115], v[116:119]
	v_mfma_f32_16x16x32_bf16 v[112:115], v[72:75], v[112:115], v[120:123]
	s_nop 2
	ds_read_b128 v[120:123], v217 offset:25728
	ds_read_b128 v[228:231], v217 offset:25792
	s_waitcnt lgkmcnt(1)
	v_mfma_f32_16x16x32_bf16 v[60:63], v[68:71], v[120:123], v[60:63]
	v_mfma_f32_16x16x32_bf16 v[48:51], v[72:75], v[120:123], v[48:51]
	v_mfma_f32_16x16x32_bf16 v[68:71], v[64:67], v[100:103], v[104:107]
	s_waitcnt vmcnt(16)
	v_mfma_f32_16x16x32_bf16 v[72:75], v[56:59], v[100:103], v[88:91]
	v_mfma_f32_16x16x32_bf16 v[88:91], v[64:67], v[124:127], v[108:111]
	v_mfma_f32_16x16x32_bf16 v[232:235], v[56:59], v[124:127], v[96:99]
	v_mfma_f32_16x16x32_bf16 v[236:239], v[64:67], v[148:151], v[116:119]
	v_mfma_f32_16x16x32_bf16 v[148:151], v[56:59], v[148:151], v[112:115]
	global_load_dwordx4 v[120:123], v[206:207], off nt
	s_nop 1
	global_load_dwordx4 v[112:115], v[206:207], off offset:1024 nt
	global_load_dwordx4 v[124:127], v[248:249], off nt
	global_load_dwordx4 v[116:119], v[248:249], off offset:1024 nt
	global_load_dwordx4 v[104:107], v[206:207], off offset:2048 nt
	global_load_dwordx4 v[96:99], v[206:207], off offset:3072 nt
	global_load_dwordx4 v[108:111], v[248:249], off offset:2048 nt
	global_load_dwordx4 v[100:103], v[248:249], off offset:3072 nt
	s_waitcnt lgkmcnt(0)
	v_mfma_f32_16x16x32_bf16 v[60:63], v[64:67], v[228:231], v[60:63]
	v_mfma_f32_16x16x32_bf16 v[48:51], v[56:59], v[228:231], v[48:51]
	ds_read2_b32 v[206:207], v221 offset1:16
	ds_read_b128 v[56:59], v222
	ds_read_b128 v[240:243], v222 offset:4416
	ds_read_b128 v[244:247], v222 offset:8704
	ds_read_b128 v[228:231], v222 offset:4352
	s_waitcnt lgkmcnt(4)
	v_pk_mul_f32 v[64:65], v[68:69], v[206:207] op_sel_hi:[1,0]
	v_pk_mul_f32 v[66:67], v[70:71], v[206:207] op_sel_hi:[1,0]
	v_pk_mul_f32 v[68:69], v[72:73], v[206:207] op_sel_hi:[1,0]
	v_pk_mul_f32 v[70:71], v[74:75], v[206:207] op_sel_hi:[1,0]
	v_mov_b32_e32 v178, v207
	ds_read_b128 v[72:75], v222 offset:64
	ds_read2_b32 v[206:207], v221 offset0:32 offset1:48
	s_waitcnt vmcnt(23) lgkmcnt(5)
	v_mfma_f32_16x16x32_bf16 v[64:67], v[152:155], v[56:59], v[64:67]
	v_mul_f32_e64 v88, v88, v178
	v_mul_f32_e64 v89, v89, v178
	v_pk_mul_f32 v[90:91], v[90:91], v[178:179] op_sel_hi:[1,0]
	s_waitcnt lgkmcnt(0)
	v_pk_mul_f32 v[148:149], v[148:149], v[206:207] op_sel_hi:[1,0]
	s_waitcnt vmcnt(21)
	v_mfma_f32_16x16x32_bf16 v[56:59], v[164:167], v[56:59], v[68:71]
	v_mul_f32_e64 v150, v150, v206
	v_mul_f32_e64 v151, v151, v206
	s_nop 0
	v_pk_mul_f32 v[68:69], v[232:233], v[178:179] op_sel_hi:[1,0]
	v_pk_mul_f32 v[70:71], v[234:235], v[178:179] op_sel_hi:[1,0]
	v_mfma_f32_16x16x32_bf16 v[88:91], v[152:155], v[228:231], v[88:91]
	v_mul_f32_e64 v232, v236, v206
	v_mul_f32_e64 v233, v237, v206
	v_pk_mul_f32 v[234:235], v[238:239], v[206:207] op_sel_hi:[1,0]
	ds_read_b128 v[236:239], v222 offset:13056
	v_mfma_f32_16x16x32_bf16 v[68:71], v[164:167], v[228:231], v[68:71]
	ds_read_b128 v[228:231], v222 offset:8768
	v_mov_b32_e32 v178, v207
	v_pk_mul_f32 v[60:61], v[60:61], v[178:179] op_sel_hi:[1,0]
	v_mfma_f32_16x16x32_bf16 v[232:235], v[152:155], v[244:247], v[232:235]
	v_mul_f32_e64 v62, v62, v178
	v_mul_f32_e64 v63, v63, v178
	v_pk_mul_f32 v[48:49], v[48:49], v[178:179] op_sel_hi:[1,0]
	v_pk_mul_f32 v[50:51], v[50:51], v[178:179] op_sel_hi:[1,0]
	v_mfma_f32_16x16x32_bf16 v[148:151], v[164:167], v[244:247], v[148:151]
	ds_read_b128 v[244:247], v222 offset:13120
	s_waitcnt lgkmcnt(2)
	v_mfma_f32_16x16x32_bf16 v[60:63], v[152:155], v[236:239], v[60:63]
	v_mfma_f32_16x16x32_bf16 v[48:51], v[164:167], v[236:239], v[48:51]
	v_mfma_f32_16x16x32_bf16 v[64:67], v[132:135], v[72:75], v[64:67]
	s_waitcnt vmcnt(20)
	v_mfma_f32_16x16x32_bf16 v[56:59], v[144:147], v[72:75], v[56:59]
	v_mfma_f32_16x16x32_bf16 v[72:75], v[132:135], v[240:243], v[88:91]
	v_mfma_f32_16x16x32_bf16 v[68:71], v[144:147], v[240:243], v[68:71]
	s_waitcnt lgkmcnt(1)
	v_mfma_f32_16x16x32_bf16 v[88:91], v[132:135], v[228:231], v[232:235]
	v_mfma_f32_16x16x32_bf16 v[148:151], v[144:147], v[228:231], v[148:151]
	s_waitcnt lgkmcnt(0)
	v_mfma_f32_16x16x32_bf16 v[60:63], v[132:135], v[244:247], v[60:63]
	v_mfma_f32_16x16x32_bf16 v[48:51], v[144:147], v[244:247], v[48:51]
	ds_read_b128 v[132:135], v222 offset:128
	ds_read_b128 v[144:147], v222 offset:192
	s_waitcnt vmcnt(19) lgkmcnt(1)
	v_mfma_f32_16x16x32_bf16 v[64:67], v[76:79], v[132:135], v[64:67]
	s_waitcnt vmcnt(17)
	v_mfma_f32_16x16x32_bf16 v[56:59], v[92:95], v[132:135], v[56:59]
	ds_read_b128 v[132:135], v222 offset:4480
	ds_read_b128 v[152:155], v222 offset:4544
	s_waitcnt lgkmcnt(1)
	v_mfma_f32_16x16x32_bf16 v[72:75], v[76:79], v[132:135], v[72:75]
	v_mfma_f32_16x16x32_bf16 v[132:135], v[92:95], v[132:135], v[68:71]
	s_nop 2
	ds_read_b128 v[68:71], v222 offset:8832
	ds_read_b128 v[164:167], v222 offset:8896
	s_waitcnt lgkmcnt(1)
	v_mfma_f32_16x16x32_bf16 v[228:231], v[76:79], v[68:71], v[88:91]
	v_mfma_f32_16x16x32_bf16 v[232:235], v[92:95], v[68:71], v[148:151]
	ds_read_b128 v[68:71], v222 offset:13184
	ds_read_b128 v[236:239], v222 offset:13248
	s_waitcnt lgkmcnt(1)
; #define LAS __attribute__((address_space(3)))
; __device__ void passB_unit(const Params& p, LAS unsigned char* lds, int u, bool do_store = true) {
;     ...
;     for (int q = 0; q < 12; ++q) {
;         const int nh = q / 6, d = (q % 6) / 3, kind = q % 3;
;         if (q + 2 < 12) PB_ISSUE(q + 2);
;         __builtin_amdgcn_sched_barrier(0);
;         if (kind == 0) {
; #pragma unroll
;             for (int mt = 0; mt < 4; ++mt)
; #pragma unroll
;                 for (int n2 = 0; n2 < 2; ++n2) { acc[mt][n2] = (f32x4){0.f, 0.f, 0.f, 0.f}; if (d == 0) hsum[mt][nh * 2 + n2] = (f32x4){0.f, 0.f, 0.f, 0.f}; }
;         }
;         if (kind < 2) {
; #pragma unroll
;             for (int ks = 0; ks < 4; ++ks) { bf16x8 qf[4];
; #pragma unroll
;                 for (int mt = 0; mt < 4; ++mt) qf[mt] = *(const LAS bf16x8*)(Qs + (wt2 * 64 + mt * 16 + fr) * 264 + (kind * 4 + ks) * 32 + fq * 8);
; #pragma unroll
;                 for (int mt = 0; mt < 4; ++mt)
; #pragma unroll
;                     for (int n2 = 0; n2 < 2; ++n2) acc[mt][n2] = __builtin_amdgcn_mfma_f32_16x16x32_bf16(F[q % 3][ks][n2], qf[mt], acc[mt][n2], 0, 0, 0); }
;         } else {
;             const LAS bf16_t* Pp = Pd + d * 128 * 136;
; #pragma unroll
;             for (int mt = 0; mt < 4; ++mt) { const float wv = winA[d * 128 + wt2 * 64 + mt * 16 + fr];
; #pragma unroll
;                 for (int n2 = 0; n2 < 2; ++n2) acc[mt][n2] *= wv; }
; #pragma unroll
;             for (int ks = 0; ks < 4; ++ks) { bf16x8 pf[4];
; #pragma unroll
;                 for (int mt = 0; mt < 4; ++mt) pf[mt] = *(const LAS bf16x8*)(Pp + (wt2 * 64 + mt * 16 + fr) * 136 + ks * 32 + fq * 8);
; #pragma unroll
;                 for (int mt = 0; mt < 4; ++mt)
; #pragma unroll
;                     for (int n2 = 0; n2 < 2; ++n2) acc[mt][n2] = __builtin_amdgcn_mfma_f32_16x16x32_bf16(F[q % 3][ks][n2], pf[mt], acc[mt][n2], 0, 0, 0); }
; #pragma unroll
;             for (int mt = 0; mt < 4; ++mt) { const float iv = invA[d * 128 + wt2 * 64 + mt * 16 + fr];
; #pragma unroll
;                 for (int n2 = 0; n2 < 2; ++n2) hsum[mt][nh * 2 + n2] += acc[mt][n2] * iv; }
	v_mfma_f32_16x16x32_bf16 v[240:243], v[76:79], v[68:71], v[60:63]
	v_mfma_f32_16x16x32_bf16 v[244:247], v[92:95], v[68:71], v[48:51]
	v_mfma_f32_16x16x32_bf16 v[248:251], v[128:131], v[144:147], v[64:67]
	s_waitcnt vmcnt(16)
	v_mfma_f32_16x16x32_bf16 v[206:209], v[52:55], v[144:147], v[56:59]
	v_mfma_f32_16x16x32_bf16 v[68:71], v[128:131], v[152:155], v[72:75]
	v_mfma_f32_16x16x32_bf16 v[64:67], v[52:55], v[152:155], v[132:135]
	global_load_dwordx4 v[152:155], v[194:195], off offset:-4096
	global_load_dwordx4 v[144:147], v[194:195], off
	s_nop 0
	global_load_dwordx4 v[132:135], v[194:195], off offset:1024
	global_load_dwordx4 v[88:91], v[194:195], off offset:2048
	global_load_dwordx4 v[92:95], v[188:189], off offset:2048
	global_load_dwordx4 v[76:79], v[188:189], off offset:3072
	global_load_dwordx4 v[148:151], v[188:189], off offset:1024
	global_load_dwordx4 v[72:75], v[194:195], off offset:3072
	v_mfma_f32_16x16x32_bf16 v[56:59], v[128:131], v[164:167], v[228:231]
	v_mfma_f32_16x16x32_bf16 v[60:63], v[52:55], v[164:167], v[232:235]
	ds_read2_b32 v[164:165], v220 offset1:16
	s_waitcnt lgkmcnt(0)
	v_pk_fma_f32 v[188:189], v[250:251], v[164:165], 0 op_sel_hi:[1,0,0]
	v_mfma_f32_16x16x32_bf16 v[48:51], v[128:131], v[236:239], v[240:243]
	ds_read2_b32 v[128:129], v220 offset0:32 offset1:48
	v_pk_fma_f32 v[194:195], v[248:249], v[164:165], 0 op_sel_hi:[1,0,0]
	v_pk_fma_f32 v[166:167], v[208:209], v[164:165], 0 op_sel_hi:[1,0,0]
	v_mfma_f32_16x16x32_bf16 v[52:55], v[52:55], v[236:239], v[244:247]
	v_fma_f32 v130, v206, v164, 0
	v_fma_f32 v131, v207, v164, 0
	ds_read_b128 v[206:209], v217
	ds_read_b128 v[232:235], v217 offset:8448
	ds_read_b128 v[240:243], v217 offset:16896
	ds_read_b128 v[248:251], v217 offset:25344
	s_waitcnt vmcnt(23) lgkmcnt(3)
	v_mfma_f32_16x16x32_bf16 v[228:231], v[168:171], v[206:209], 0
	s_waitcnt vmcnt(22)
	v_mfma_f32_16x16x32_bf16 v[206:209], v[172:175], v[206:209], 0
	s_waitcnt lgkmcnt(2)
	v_mfma_f32_16x16x32_bf16 v[236:239], v[168:171], v[232:235], 0
	v_mfma_f32_16x16x32_bf16 v[232:235], v[172:175], v[232:235], 0
	s_waitcnt lgkmcnt(1)
	v_mfma_f32_16x16x32_bf16 v[244:247], v[168:171], v[240:243], 0
	v_mfma_f32_16x16x32_bf16 v[240:243], v[172:175], v[240:243], 0
	s_waitcnt lgkmcnt(0)
	v_mfma_f32_16x16x32_bf16 v[168:171], v[168:171], v[248:251], 0
	v_mfma_f32_16x16x32_bf16 v[172:175], v[172:175], v[248:251], 0
	ds_read_b128 v[248:251], v217 offset:64
	s_waitcnt vmcnt(21) lgkmcnt(0)
	v_mfma_f32_16x16x32_bf16 v[228:231], v[156:159], v[248:251], v[228:231]
	s_waitcnt vmcnt(19)
	v_mfma_f32_16x16x32_bf16 v[206:209], v[160:163], v[248:251], v[206:209]
	ds_read_b128 v[248:251], v217 offset:8512
	s_waitcnt lgkmcnt(0)
	v_mfma_f32_16x16x32_bf16 v[236:239], v[156:159], v[248:251], v[236:239]
	v_mfma_f32_16x16x32_bf16 v[232:235], v[160:163], v[248:251], v[232:235]
	ds_read_b128 v[248:251], v217 offset:16960
	s_waitcnt lgkmcnt(0)
	v_mfma_f32_16x16x32_bf16 v[244:247], v[156:159], v[248:251], v[244:247]
	v_mfma_f32_16x16x32_bf16 v[240:243], v[160:163], v[248:251], v[240:243]
	ds_read_b128 v[248:251], v217 offset:25408
	s_waitcnt lgkmcnt(0)
	v_mfma_f32_16x16x32_bf16 v[156:159], v[156:159], v[248:251], v[168:171]
	s_nop 2
	ds_read_b128 v[168:171], v217 offset:128
	v_mfma_f32_16x16x32_bf16 v[160:163], v[160:163], v[248:251], v[172:175]
	s_waitcnt lgkmcnt(0)
	v_mfma_f32_16x16x32_bf16 v[172:175], v[136:139], v[168:171], v[228:231]
	s_waitcnt vmcnt(17)
	v_mfma_f32_16x16x32_bf16 v[168:171], v[140:143], v[168:171], v[206:209]
	s_nop 2
	ds_read_b128 v[206:209], v217 offset:8576
	s_waitcnt lgkmcnt(0)
	v_mfma_f32_16x16x32_bf16 v[228:231], v[136:139], v[206:209], v[236:239]
	v_mfma_f32_16x16x32_bf16 v[206:209], v[140:143], v[206:209], v[232:235]
	s_nop 2
	ds_read_b128 v[232:235], v217 offset:17024
	s_waitcnt lgkmcnt(0)
	v_mfma_f32_16x16x32_bf16 v[236:239], v[136:139], v[232:235], v[244:247]
	v_mfma_f32_16x16x32_bf16 v[232:235], v[140:143], v[232:235], v[240:243]
	s_nop 2
	ds_read_b128 v[240:243], v217 offset:25472
	s_waitcnt lgkmcnt(0)
	v_mfma_f32_16x16x32_bf16 v[136:139], v[136:139], v[240:243], v[156:159]
	s_nop 2
	ds_read_b128 v[156:159], v217 offset:192
	v_mfma_f32_16x16x32_bf16 v[140:143], v[140:143], v[240:243], v[160:163]
	s_waitcnt lgkmcnt(0)
	v_mfma_f32_16x16x32_bf16 v[160:163], v[80:83], v[156:159], v[172:175]
	s_waitcnt vmcnt(16)
	v_mfma_f32_16x16x32_bf16 v[156:159], v[84:87], v[156:159], v[168:171]
	s_nop 2
	ds_read_b128 v[168:171], v217 offset:8640
	s_waitcnt lgkmcnt(0)
	v_mfma_f32_16x16x32_bf16 v[172:175], v[80:83], v[168:171], v[228:231]
	v_mfma_f32_16x16x32_bf16 v[168:171], v[84:87], v[168:171], v[206:209]
	s_nop 2
	ds_read_b128 v[206:209], v217 offset:17088
	s_waitcnt lgkmcnt(0)
	v_mfma_f32_16x16x32_bf16 v[228:231], v[80:83], v[206:209], v[236:239]
	v_mfma_f32_16x16x32_bf16 v[206:209], v[84:87], v[206:209], v[232:235]
	s_nop 2
	ds_read_b128 v[232:235], v217 offset:25536
	s_waitcnt lgkmcnt(0)
	v_mfma_f32_16x16x32_bf16 v[80:83], v[80:83], v[232:235], v[136:139]
	v_mfma_f32_16x16x32_bf16 v[84:87], v[84:87], v[232:235], v[140:143]
	s_nop 1
	ds_read_b128 v[136:139], v217 offset:256
	ds_read_b128 v[140:143], v217 offset:320
	s_waitcnt vmcnt(15) lgkmcnt(1)
	v_mfma_f32_16x16x32_bf16 v[160:163], v[120:123], v[136:139], v[160:163]
	s_waitcnt vmcnt(13)
	v_mfma_f32_16x16x32_bf16 v[136:139], v[124:127], v[136:139], v[156:159]
	s_nop 2
	ds_read_b128 v[156:159], v217 offset:8704
	ds_read_b128 v[232:235], v217 offset:8768
	s_waitcnt lgkmcnt(1)
	v_mfma_f32_16x16x32_bf16 v[172:175], v[120:123], v[156:159], v[172:175]
	v_mfma_f32_16x16x32_bf16 v[156:159], v[124:127], v[156:159], v[168:171]
	s_nop 2
	ds_read_b128 v[168:171], v217 offset:17152
	ds_read_b128 v[236:239], v217 offset:17216
	s_waitcnt lgkmcnt(1)
; #define LAS __attribute__((address_space(3)))
; __device__ void passB_unit(const Params& p, LAS unsigned char* lds, int u, bool do_store = true) {
;     ...
;     for (int q = 0; q < 12; ++q) {
;         const int nh = q / 6, d = (q % 6) / 3, kind = q % 3;
;         if (q + 2 < 12) PB_ISSUE(q + 2);
;         __builtin_amdgcn_sched_barrier(0);
;         if (kind == 0) {
; #pragma unroll
;             for (int mt = 0; mt < 4; ++mt)
; #pragma unroll
;                 for (int n2 = 0; n2 < 2; ++n2) { acc[mt][n2] = (f32x4){0.f, 0.f, 0.f, 0.f}; if (d == 0) hsum[mt][nh * 2 + n2] = (f32x4){0.f, 0.f, 0.f, 0.f}; }
;         }
;         if (kind < 2) {
; #pragma unroll
;             for (int ks = 0; ks < 4; ++ks) { bf16x8 qf[4];
; #pragma unroll
;                 for (int mt = 0; mt < 4; ++mt) qf[mt] = *(const LAS bf16x8*)(Qs + (wt2 * 64 + mt * 16 + fr) * 264 + (kind * 4 + ks) * 32 + fq * 8);
; #pragma unroll
;                 for (int mt = 0; mt < 4; ++mt)
; #pragma unroll
;                     for (int n2 = 0; n2 < 2; ++n2) acc[mt][n2] = __builtin_amdgcn_mfma_f32_16x16x32_bf16(F[q % 3][ks][n2], qf[mt], acc[mt][n2], 0, 0, 0); }
;         } else {
;             const LAS bf16_t* Pp = Pd + d * 128 * 136;
; #pragma unroll
;             for (int mt = 0; mt < 4; ++mt) { const float wv = winA[d * 128 + wt2 * 64 + mt * 16 + fr];
; #pragma unroll
;                 for (int n2 = 0; n2 < 2; ++n2) acc[mt][n2] *= wv; }
; #pragma unroll
;             for (int ks = 0; ks < 4; ++ks) { bf16x8 pf[4];
; #pragma unroll
;                 for (int mt = 0; mt < 4; ++mt) pf[mt] = *(const LAS bf16x8*)(Pp + (wt2 * 64 + mt * 16 + fr) * 136 + ks * 32 + fq * 8);
; #pragma unroll
;                 for (int mt = 0; mt < 4; ++mt)
; #pragma unroll
;                     for (int n2 = 0; n2 < 2; ++n2) acc[mt][n2] = __builtin_amdgcn_mfma_f32_16x16x32_bf16(F[q % 3][ks][n2], pf[mt], acc[mt][n2], 0, 0, 0); }
; #pragma unroll
;             for (int mt = 0; mt < 4; ++mt) { const float iv = invA[d * 128 + wt2 * 64 + mt * 16 + fr];
; #pragma unroll
;                 for (int n2 = 0; n2 < 2; ++n2) hsum[mt][nh * 2 + n2] += acc[mt][n2] * iv; }
	v_mfma_f32_16x16x32_bf16 v[228:231], v[120:123], v[168:171], v[228:231]
	v_mfma_f32_16x16x32_bf16 v[168:171], v[124:127], v[168:171], v[206:209]
	s_nop 2
	ds_read_b128 v[206:209], v217 offset:25600
	ds_read_b128 v[240:243], v217 offset:25664
	s_waitcnt lgkmcnt(1)
	v_mfma_f32_16x16x32_bf16 v[80:83], v[120:123], v[206:209], v[80:83]
	v_mfma_f32_16x16x32_bf16 v[84:87], v[124:127], v[206:209], v[84:87]
	v_mfma_f32_16x16x32_bf16 v[120:123], v[112:115], v[140:143], v[160:163]
	s_waitcnt vmcnt(12)
	v_mfma_f32_16x16x32_bf16 v[124:127], v[116:119], v[140:143], v[136:139]
	v_mfma_f32_16x16x32_bf16 v[136:139], v[112:115], v[232:235], v[172:175]
	v_mfma_f32_16x16x32_bf16 v[140:143], v[116:119], v[232:235], v[156:159]
	v_mfma_f32_16x16x32_bf16 v[156:159], v[112:115], v[236:239], v[228:231]
	v_mfma_f32_16x16x32_bf16 v[160:163], v[116:119], v[236:239], v[168:171]
	s_waitcnt lgkmcnt(0)
	v_mfma_f32_16x16x32_bf16 v[80:83], v[112:115], v[240:243], v[80:83]
	v_mfma_f32_16x16x32_bf16 v[84:87], v[116:119], v[240:243], v[84:87]
	ds_read_b128 v[112:115], v217 offset:384
	ds_read_b128 v[116:119], v217 offset:448
	s_waitcnt vmcnt(11) lgkmcnt(1)
	v_mfma_f32_16x16x32_bf16 v[120:123], v[104:107], v[112:115], v[120:123]
	s_waitcnt vmcnt(9)
	v_mfma_f32_16x16x32_bf16 v[112:115], v[108:111], v[112:115], v[124:127]
	s_nop 2
	ds_read_b128 v[124:127], v217 offset:8832
	ds_read_b128 v[168:171], v217 offset:8896
	s_waitcnt lgkmcnt(1)
	v_mfma_f32_16x16x32_bf16 v[136:139], v[104:107], v[124:127], v[136:139]
	v_mfma_f32_16x16x32_bf16 v[124:127], v[108:111], v[124:127], v[140:143]
	s_nop 2
	ds_read_b128 v[140:143], v217 offset:17280
	ds_read_b128 v[172:175], v217 offset:17344
	s_waitcnt lgkmcnt(1)
	v_mfma_f32_16x16x32_bf16 v[156:159], v[104:107], v[140:143], v[156:159]
	v_mfma_f32_16x16x32_bf16 v[140:143], v[108:111], v[140:143], v[160:163]
	s_nop 2
	ds_read_b128 v[160:163], v217 offset:25728
	ds_read_b128 v[206:209], v217 offset:25792
	s_waitcnt lgkmcnt(1)
	v_mfma_f32_16x16x32_bf16 v[80:83], v[104:107], v[160:163], v[80:83]
	v_mfma_f32_16x16x32_bf16 v[84:87], v[108:111], v[160:163], v[84:87]
	v_mfma_f32_16x16x32_bf16 v[104:107], v[96:99], v[116:119], v[120:123]
	s_waitcnt vmcnt(8)
	v_mfma_f32_16x16x32_bf16 v[108:111], v[100:103], v[116:119], v[112:115]
	v_mfma_f32_16x16x32_bf16 v[112:115], v[96:99], v[168:171], v[136:139]
	s_waitcnt lgkmcnt(0)
	v_mfma_f32_16x16x32_bf16 v[80:83], v[96:99], v[206:209], v[80:83]
	v_mfma_f32_16x16x32_bf16 v[84:87], v[100:103], v[206:209], v[84:87]
	v_mfma_f32_16x16x32_bf16 v[116:119], v[100:103], v[168:171], v[124:127]
	v_mfma_f32_16x16x32_bf16 v[120:123], v[96:99], v[172:175], v[156:159]
	v_mfma_f32_16x16x32_bf16 v[124:127], v[100:103], v[172:175], v[140:143]
	ds_read2_b32 v[136:137], v221 offset0:128 offset1:144
	ds_read_b128 v[96:99], v222 offset:34816
	ds_read2_b32 v[168:169], v221 offset0:160 offset1:176
	ds_read_b128 v[140:143], v222 offset:39232
	s_add_i32 s49, 0, 0x24c00
	s_waitcnt lgkmcnt(3)
	v_pk_mul_f32 v[102:103], v[106:107], v[136:137] op_sel_hi:[1,0]
	v_pk_mul_f32 v[100:101], v[104:105], v[136:137] op_sel_hi:[1,0]
	v_pk_mul_f32 v[106:107], v[110:111], v[136:137] op_sel_hi:[1,0]
	v_pk_mul_f32 v[104:105], v[108:109], v[136:137] op_sel_hi:[1,0]
	v_mov_b32_e32 v156, v137
	ds_read_b128 v[108:111], v222 offset:34880
	ds_read_b128 v[136:139], v222 offset:39168
	s_waitcnt vmcnt(7) lgkmcnt(4)
	v_mfma_f32_16x16x32_bf16 v[100:103], v[152:155], v[96:99], v[100:103]
	v_mul_f32_e64 v114, v114, v156
	v_mul_f32_e64 v115, v115, v156
	v_pk_mul_f32 v[112:113], v[112:113], v[156:157] op_sel_hi:[1,0]
	s_waitcnt vmcnt(6)
	v_mfma_f32_16x16x32_bf16 v[96:99], v[144:147], v[96:99], v[104:107]
	s_nop 2
	v_mul_f32_e64 v106, v118, v156
	v_mul_f32_e64 v107, v119, v156
	v_pk_mul_f32 v[104:105], v[116:117], v[156:157] op_sel_hi:[1,0]
	ds_read_b128 v[156:159], v222 offset:43520
	s_waitcnt lgkmcnt(4)
	v_pk_mul_f32 v[118:119], v[122:123], v[168:169] op_sel_hi:[1,0]
	v_pk_mul_f32 v[116:117], v[120:121], v[168:169] op_sel_hi:[1,0]
	s_waitcnt lgkmcnt(1)
	v_mfma_f32_16x16x32_bf16 v[112:115], v[152:155], v[136:139], v[112:115]
	v_mul_f32_e64 v120, v126, v168
	v_mul_f32_e64 v121, v127, v168
	v_mov_b32_e32 v126, v169
	v_pk_mul_f32 v[86:87], v[86:87], v[126:127] op_sel_hi:[1,0]
	v_mfma_f32_16x16x32_bf16 v[104:107], v[144:147], v[136:139], v[104:107]
	ds_read_b128 v[136:139], v222 offset:43584
	v_pk_mul_f32 v[84:85], v[84:85], v[126:127] op_sel_hi:[1,0]
	v_pk_mul_f32 v[82:83], v[82:83], v[126:127] op_sel_hi:[1,0]
	s_waitcnt lgkmcnt(1)
	v_mfma_f32_16x16x32_bf16 v[160:163], v[152:155], v[156:159], v[116:119]
	v_mul_f32_e64 v80, v80, v126
	v_mul_f32_e64 v81, v81, v126
	s_nop 0
	v_pk_mul_f32 v[118:119], v[124:125], v[168:169] op_sel_hi:[1,0]
	ds_read_b128 v[122:125], v222 offset:47872
	s_waitcnt lgkmcnt(0)
	v_mfma_f32_16x16x32_bf16 v[84:87], v[144:147], v[122:125], v[84:87]
	v_mfma_f32_16x16x32_bf16 v[116:119], v[144:147], v[156:159], v[118:121]
	ds_read_b128 v[156:159], v222 offset:47936
	v_mfma_f32_16x16x32_bf16 v[80:83], v[152:155], v[122:125], v[80:83]
	s_waitcnt vmcnt(1)
	v_mfma_f32_16x16x32_bf16 v[100:103], v[148:151], v[108:111], v[100:103]
	v_mfma_f32_16x16x32_bf16 v[96:99], v[132:135], v[108:111], v[96:99]
	v_mfma_f32_16x16x32_bf16 v[120:123], v[132:135], v[140:143], v[104:107]
	v_mfma_f32_16x16x32_bf16 v[116:119], v[132:135], v[136:139], v[116:119]
	s_waitcnt lgkmcnt(0)
	v_mfma_f32_16x16x32_bf16 v[84:87], v[132:135], v[156:159], v[84:87]
	ds_read_b128 v[104:107], v222 offset:34944
	ds_read_b128 v[132:135], v222 offset:35008
	s_waitcnt lgkmcnt(1)
; #define LAS __attribute__((address_space(3)))
; __device__ void passB_unit(const Params& p, LAS unsigned char* lds, int u, bool do_store = true) {
;     ...
;         } else {
;             const LAS bf16_t* Pp = Pd + d * 128 * 136;
; #pragma unroll
;             for (int mt = 0; mt < 4; ++mt) { const float wv = winA[d * 128 + wt2 * 64 + mt * 16 + fr];
; #pragma unroll
;                 for (int n2 = 0; n2 < 2; ++n2) acc[mt][n2] *= wv; }
; #pragma unroll
;             for (int ks = 0; ks < 4; ++ks) { bf16x8 pf[4];
; #pragma unroll
;                 for (int mt = 0; mt < 4; ++mt) pf[mt] = *(const LAS bf16x8*)(Pp + (wt2 * 64 + mt * 16 + fr) * 136 + ks * 32 + fq * 8);
; #pragma unroll
;                 for (int mt = 0; mt < 4; ++mt)
; #pragma unroll
;                     for (int n2 = 0; n2 < 2; ++n2) acc[mt][n2] = __builtin_amdgcn_mfma_f32_16x16x32_bf16(F[q % 3][ks][n2], pf[mt], acc[mt][n2], 0, 0, 0); }
; #pragma unroll
;             for (int mt = 0; mt < 4; ++mt) { const float iv = invA[d * 128 + wt2 * 64 + mt * 16 + fr];
; #pragma unroll
;                 for (int n2 = 0; n2 < 2; ++n2) hsum[mt][nh * 2 + n2] += acc[mt][n2] * iv; }
;         }
;     }
;     ...
; #pragma unroll
;     for (int mt = 0; mt < 4; ++mt) { float sv = 0.f;
; #pragma unroll
;         for (int nt = 0; nt < 4; ++nt) { const f32x4 hv = hsum[mt][nt]; sv += (hv[0] * hv[0] + hv[1] * hv[1]) + (hv[2] * hv[2] + hv[3] * hv[3]); }
;         sv += __shfl_xor(sv, 16); sv += __shfl_xor(sv, 32);
;         if (fq == 0) ssP[w4 * 128 + wt2 * 64 + mt * 16 + fr] = sv; }
	v_mfma_f32_16x16x32_bf16 v[100:103], v[92:95], v[104:107], v[100:103]
	v_mfma_f32_16x16x32_bf16 v[96:99], v[88:91], v[104:107], v[96:99]
	v_mfma_f32_16x16x32_bf16 v[108:111], v[148:151], v[140:143], v[112:115]
	v_mfma_f32_16x16x32_bf16 v[124:127], v[148:151], v[136:139], v[160:163]
	ds_read_b128 v[136:139], v222 offset:39296
	ds_read_b128 v[140:143], v222 offset:39360
	v_mfma_f32_16x16x32_bf16 v[80:83], v[148:151], v[156:159], v[80:83]
	ds_read_b128 v[144:147], v222 offset:43648
	ds_read_b128 v[148:151], v222 offset:43712
	ds_read2_b32 v[114:115], v220 offset0:128 offset1:144
	ds_read_b128 v[152:155], v222 offset:48000
	ds_read_b128 v[156:159], v222 offset:48064
	ds_read2_b32 v[112:113], v220 offset0:160 offset1:176
	s_waitcnt lgkmcnt(8)
	v_mfma_f32_16x16x32_bf16 v[100:103], v[76:79], v[132:135], v[100:103]
	s_waitcnt vmcnt(0)
	v_mfma_f32_16x16x32_bf16 v[132:135], v[72:75], v[132:135], v[96:99]
	s_waitcnt lgkmcnt(7)
	v_mfma_f32_16x16x32_bf16 v[108:111], v[92:95], v[136:139], v[108:111]
	s_waitcnt lgkmcnt(3)
	s_nop 2
	v_pk_fma_f32 v[104:105], v[102:103], v[114:115], v[188:189] op_sel_hi:[1,0,1]
	v_pk_fma_f32 v[106:107], v[100:101], v[114:115], v[194:195] op_sel_hi:[1,0,1]
	v_pk_fma_f32 v[96:97], v[134:135], v[114:115], v[166:167] op_sel_hi:[1,0,1]
	v_mfma_f32_16x16x32_bf16 v[100:103], v[88:91], v[136:139], v[120:123]
	v_fma_f32 v98, v132, v114, v130
	v_fma_f32 v99, v133, v114, v131
	v_mul_f32_e32 v114, v187, v187
	v_fmac_f32_e32 v114, v186, v186
	v_mfma_f32_16x16x32_bf16 v[120:123], v[92:95], v[144:147], v[124:127]
	v_mul_f32_e32 v130, v183, v183
	v_fmac_f32_e32 v130, v182, v182
	s_nop 0
	v_mul_f32_e32 v124, v185, v185
	v_fmac_f32_e32 v124, v184, v184
	v_add_f32_e32 v114, v114, v124
	s_waitcnt lgkmcnt(2)
	v_mfma_f32_16x16x32_bf16 v[124:127], v[92:95], v[152:155], v[80:83]
	s_nop 2
	v_mul_f32_e32 v80, v181, v181
	v_fmac_f32_e32 v80, v180, v180
	v_mul_f32_e32 v81, v107, v107
	v_mul_f32_e32 v82, v105, v105
	v_add_f32_e32 v80, v130, v80
	v_mfma_f32_16x16x32_bf16 v[130:133], v[88:91], v[152:155], v[84:87]
	v_fmac_f32_e32 v81, v106, v106
	v_fmac_f32_e32 v82, v104, v104
	v_add_f32_e32 v80, v114, v80
	v_mul_f32_e32 v84, v99, v99
	v_mul_f32_e32 v85, v97, v97
	v_add_f32_e32 v81, v81, v82
	v_fmac_f32_e32 v84, v98, v98
	v_fmac_f32_e32 v85, v96, v96
	v_mfma_f32_16x16x32_bf16 v[92:95], v[72:75], v[140:143], v[100:103]
	s_nop 2
	v_add_f32_e32 v100, v80, v81
	v_add_f32_e32 v101, v84, v85
	v_add_f32_e32 v100, v101, v100
	v_mfma_f32_16x16x32_bf16 v[116:119], v[88:91], v[144:147], v[116:119]
	v_add_u32_e32 v102, s49, v216
	v_add3_u32 v114, v102, v218, v219
	s_waitcnt lgkmcnt(0)
	v_mov_b32_e32 v101, v100
	s_nop 1
	v_permlane16_swap_b32_e32 v101, v100
	v_add_f32_e32 v100, v100, v101
	v_mov_b32_e32 v101, v100
	s_nop 1
	v_permlane32_swap_b32_e32 v101, v100
	v_mfma_f32_16x16x32_bf16 v[88:91], v[76:79], v[140:143], v[108:111]
	v_mfma_f32_16x16x32_bf16 v[80:83], v[76:79], v[148:151], v[120:123]
	v_mfma_f32_16x16x32_bf16 v[84:87], v[72:75], v[148:151], v[116:119]
	v_mfma_f32_16x16x32_bf16 v[76:79], v[76:79], v[156:159], v[124:127]
	v_mfma_f32_16x16x32_bf16 v[72:75], v[72:75], v[156:159], v[130:133]
	s_and_saveexec_b64 s[0:1], s[4:5]
	s_cbranch_execz .LBB0_561
	s_waitcnt lgkmcnt(0)
	v_add_f32_e32 v100, v100, v101
	ds_write_b32 v114, v100
.LBB0_561:
	s_or_b64 exec, exec, s[0:1]
	v_mov_b32_e32 v100, v179
	s_waitcnt lgkmcnt(0)
	v_pk_fma_f32 v[22:23], v[22:23], v[100:101], 0 op_sel_hi:[1,0,0]
	v_pk_fma_f32 v[20:21], v[20:21], v[100:101], 0 op_sel_hi:[1,0,0]
	v_pk_fma_f32 v[18:19], v[18:19], v[100:101], 0 op_sel_hi:[1,0,0]
	v_pk_fma_f32 v[16:17], v[16:17], v[100:101], 0 op_sel_hi:[1,0,0]
	v_mov_b32_e32 v102, v193
	v_pk_fma_f32 v[108:109], v[42:43], v[102:103], v[22:23] op_sel_hi:[1,0,1]
	v_pk_fma_f32 v[110:111], v[40:41], v[102:103], v[20:21] op_sel_hi:[1,0,1]
	v_pk_fma_f32 v[100:101], v[46:47], v[102:103], v[18:19] op_sel_hi:[1,0,1]
	v_pk_fma_f32 v[102:103], v[44:45], v[102:103], v[16:17] op_sel_hi:[1,0,1]
	v_mov_b32_e32 v16, v165
	v_pk_fma_f32 v[18:19], v[70:71], v[16:17], 0 op_sel_hi:[1,0,0]
	v_pk_fma_f32 v[20:21], v[68:69], v[16:17], 0 op_sel_hi:[1,0,0]
	v_pk_fma_f32 v[22:23], v[66:67], v[16:17], 0 op_sel_hi:[1,0,0]
	v_pk_fma_f32 v[16:17], v[64:65], v[16:17], 0 op_sel_hi:[1,0,0]
	v_mov_b32_e32 v42, v115
	v_pk_fma_f32 v[44:45], v[90:91], v[42:43], v[18:19] op_sel_hi:[1,0,1]
	v_pk_fma_f32 v[46:47], v[88:89], v[42:43], v[20:21] op_sel_hi:[1,0,1]
	v_pk_fma_f32 v[40:41], v[94:95], v[42:43], v[22:23] op_sel_hi:[1,0,1]
	v_pk_fma_f32 v[42:43], v[92:93], v[42:43], v[16:17] op_sel_hi:[1,0,1]
	v_mul_f32_e32 v16, v111, v111
	v_mul_f32_e32 v17, v109, v109
	v_fmac_f32_e32 v16, v110, v110
	v_fmac_f32_e32 v17, v108, v108
	v_add_f32_e32 v16, v16, v17
	v_mul_f32_e32 v17, v103, v103
	v_mul_f32_e32 v18, v101, v101
	v_fmac_f32_e32 v17, v102, v102
	v_fmac_f32_e32 v18, v100, v100
	v_add_f32_e32 v17, v17, v18
	v_add_f32_e32 v16, v16, v17
	v_mul_f32_e32 v17, v47, v47
	v_mul_f32_e32 v18, v45, v45
	v_fmac_f32_e32 v17, v46, v46
	v_fmac_f32_e32 v18, v44, v44
	v_add_f32_e32 v17, v17, v18
	v_add_f32_e32 v16, v16, v17
	v_mul_f32_e32 v17, v43, v43
	v_mul_f32_e32 v18, v41, v41
	v_fmac_f32_e32 v17, v42, v42
	v_fmac_f32_e32 v18, v40, v40
	v_add_f32_e32 v17, v17, v18
	v_add_f32_e32 v16, v17, v16
	s_waitcnt lgkmcnt(0)
	v_mov_b32_e32 v17, v16
	s_nop 1
	v_permlane16_swap_b32_e32 v17, v16
	v_add_f32_e32 v16, v16, v17
	v_mov_b32_e32 v17, v16
	s_nop 1
	v_permlane32_swap_b32_e32 v17, v16
	s_and_saveexec_b64 s[0:1], s[4:5]
	s_cbranch_execz .LBB0_563
	s_waitcnt lgkmcnt(0)
	v_add_f32_e32 v16, v16, v17
	ds_write_b32 v114, v16 offset:64
; __device__ void passB_unit(const Params& p, LAS unsigned char* lds, int u, bool do_store = true) {
;     ...
; #pragma unroll
;     for (int mt = 0; mt < 4; ++mt) { float sv = 0.f;
; #pragma unroll
;         for (int nt = 0; nt < 4; ++nt) { const f32x4 hv = hsum[mt][nt]; sv += (hv[0] * hv[0] + hv[1] * hv[1]) + (hv[2] * hv[2] + hv[3] * hv[3]); }
;         sv += __shfl_xor(sv, 16); sv += __shfl_xor(sv, 32);
;         if (fq == 0) ssP[w4 * 128 + wt2 * 64 + mt * 16 + fr] = sv; }
.LBB0_563:
	s_or_b64 exec, exec, s[0:1]
	v_pk_fma_f32 v[10:11], v[10:11], v[176:177], 0 op_sel_hi:[1,0,0]
	v_pk_fma_f32 v[8:9], v[8:9], v[176:177], 0 op_sel_hi:[1,0,0]
	v_pk_fma_f32 v[12:13], v[12:13], v[176:177], 0 op_sel_hi:[1,0,0]
	v_pk_fma_f32 v[14:15], v[14:15], v[176:177], 0 op_sel_hi:[1,0,0]
	v_pk_fma_f32 v[34:35], v[34:35], v[190:191], v[10:11] op_sel_hi:[1,0,1]
	v_pk_fma_f32 v[32:33], v[32:33], v[190:191], v[8:9] op_sel_hi:[1,0,1]
	v_pk_fma_f32 v[22:23], v[36:37], v[190:191], v[12:13] op_sel_hi:[1,0,1]
	v_pk_fma_f32 v[8:9], v[58:59], v[128:129], 0 op_sel_hi:[1,0,0]
	v_pk_fma_f32 v[12:13], v[62:63], v[128:129], 0 op_sel_hi:[1,0,0]
	v_pk_fma_f32 v[20:21], v[38:39], v[190:191], v[14:15] op_sel_hi:[1,0,1]
	v_pk_fma_f32 v[14:15], v[82:83], v[112:113], v[8:9] op_sel_hi:[1,0,1]
	v_pk_fma_f32 v[8:9], v[86:87], v[112:113], v[12:13] op_sel_hi:[1,0,1]
	v_mul_f32_e32 v12, v33, v33
	v_mul_f32_e32 v13, v35, v35
	v_pk_fma_f32 v[10:11], v[56:57], v[128:129], 0 op_sel_hi:[1,0,0]
	s_waitcnt lgkmcnt(0)
	v_pk_fma_f32 v[16:17], v[60:61], v[128:129], 0 op_sel_hi:[1,0,0]
	v_fmac_f32_e32 v12, v32, v32
	v_fmac_f32_e32 v13, v34, v34
	v_pk_fma_f32 v[18:19], v[80:81], v[112:113], v[10:11] op_sel_hi:[1,0,1]
	v_pk_fma_f32 v[10:11], v[84:85], v[112:113], v[16:17] op_sel_hi:[1,0,1]
	v_add_f32_e32 v12, v12, v13
	v_mul_f32_e32 v13, v23, v23
	v_mul_f32_e32 v16, v21, v21
	v_fmac_f32_e32 v13, v22, v22
	v_fmac_f32_e32 v16, v20, v20
	v_add_f32_e32 v13, v13, v16
	v_add_f32_e32 v12, v12, v13
	v_mul_f32_e32 v13, v19, v19
	v_mul_f32_e32 v16, v15, v15
	v_fmac_f32_e32 v13, v18, v18
	v_fmac_f32_e32 v16, v14, v14
	v_add_f32_e32 v13, v13, v16
	v_add_f32_e32 v12, v12, v13
	v_mul_f32_e32 v13, v11, v11
	v_mul_f32_e32 v16, v9, v9
	v_fmac_f32_e32 v13, v10, v10
	v_fmac_f32_e32 v16, v8, v8
	v_add_f32_e32 v13, v13, v16
	v_add_f32_e32 v12, v13, v12
	s_waitcnt lgkmcnt(0)
	v_mov_b32_e32 v13, v12
	s_nop 1
	v_permlane16_swap_b32_e32 v13, v12
	v_add_f32_e32 v12, v12, v13
	v_mov_b32_e32 v13, v12
	s_nop 1
	v_permlane32_swap_b32_e32 v13, v12
	s_and_saveexec_b64 s[0:1], s[4:5]
	s_cbranch_execz .LBB0_565
	s_waitcnt lgkmcnt(0)
	v_add_f32_e32 v12, v12, v13
	ds_write_b32 v114, v12 offset:128
.LBB0_565:
	s_or_b64 exec, exec, s[0:1]
	v_mov_b32_e32 v12, v177
	s_waitcnt lgkmcnt(0)
	v_pk_fma_f32 v[2:3], v[2:3], v[12:13], 0 op_sel_hi:[1,0,0]
	v_pk_fma_f32 v[0:1], v[0:1], v[12:13], 0 op_sel_hi:[1,0,0]
	v_pk_fma_f32 v[6:7], v[6:7], v[12:13], 0 op_sel_hi:[1,0,0]
	v_pk_fma_f32 v[4:5], v[4:5], v[12:13], 0 op_sel_hi:[1,0,0]
	v_mov_b32_e32 v12, v191
	v_pk_fma_f32 v[28:29], v[28:29], v[12:13], v[0:1] op_sel_hi:[1,0,1]
	v_mov_b32_e32 v0, v129
	v_pk_fma_f32 v[30:31], v[30:31], v[12:13], v[2:3] op_sel_hi:[1,0,1]
	v_pk_fma_f32 v[16:17], v[24:25], v[12:13], v[4:5] op_sel_hi:[1,0,1]
	v_pk_fma_f32 v[24:25], v[54:55], v[0:1], 0 op_sel_hi:[1,0,0]
	v_mov_b32_e32 v36, v113
	v_pk_fma_f32 v[6:7], v[26:27], v[12:13], v[6:7] op_sel_hi:[1,0,1]
	v_pk_fma_f32 v[2:3], v[50:51], v[0:1], 0 op_sel_hi:[1,0,0]
	v_pk_fma_f32 v[12:13], v[48:49], v[0:1], 0 op_sel_hi:[1,0,0]
	v_pk_fma_f32 v[26:27], v[52:53], v[0:1], 0 op_sel_hi:[1,0,0]
	v_pk_fma_f32 v[0:1], v[74:75], v[36:37], v[24:25] op_sel_hi:[1,0,1]
	v_mul_f32_e32 v24, v29, v29
	v_mul_f32_e32 v25, v31, v31
	v_fmac_f32_e32 v24, v28, v28
	v_fmac_f32_e32 v25, v30, v30
	v_pk_fma_f32 v[4:5], v[78:79], v[36:37], v[2:3] op_sel_hi:[1,0,1]
	v_pk_fma_f32 v[2:3], v[72:73], v[36:37], v[26:27] op_sel_hi:[1,0,1]
	v_add_f32_e32 v24, v24, v25
	v_mul_f32_e32 v25, v17, v17
	v_mul_f32_e32 v26, v7, v7
	v_fmac_f32_e32 v25, v16, v16
	v_fmac_f32_e32 v26, v6, v6
	v_pk_fma_f32 v[12:13], v[76:77], v[36:37], v[12:13] op_sel_hi:[1,0,1]
	v_add_f32_e32 v25, v25, v26
	v_add_f32_e32 v24, v24, v25
	v_mul_f32_e32 v25, v13, v13
	v_mul_f32_e32 v26, v5, v5
	v_fmac_f32_e32 v25, v12, v12
	v_fmac_f32_e32 v26, v4, v4
	v_add_f32_e32 v25, v25, v26
	v_add_f32_e32 v24, v24, v25
	v_mul_f32_e32 v25, v3, v3
	v_mul_f32_e32 v26, v1, v1
	v_fmac_f32_e32 v25, v2, v2
	v_fmac_f32_e32 v26, v0, v0
	v_add_f32_e32 v25, v25, v26
	v_add_f32_e32 v24, v25, v24
	s_waitcnt lgkmcnt(0)
	v_mov_b32_e32 v25, v24
	s_nop 1
	v_permlane16_swap_b32_e32 v25, v24
	v_add_f32_e32 v24, v24, v25
	v_mov_b32_e32 v25, v24
	s_nop 1
	v_permlane32_swap_b32_e32 v25, v24
	s_and_saveexec_b64 s[0:1], s[4:5]
	s_cbranch_execz .LBB0_567
	s_waitcnt lgkmcnt(0)
	v_add_f32_e32 v24, v24, v25
	ds_write_b32 v114, v24 offset:192

; #define LAS __attribute__((address_space(3)))
; __device__ void passB_unit(const Params& p, LAS unsigned char* lds, int u, bool do_store = true) {
;     ...
;     {
;         f32x4 sacc[4][2];
; #pragma unroll
;         for (int mt = 0; mt < 4; ++mt)
; #pragma unroll
;             for (int nt = 0; nt < 2; ++nt) sacc[mt][nt] = (f32x4){0.f, 0.f, 0.f, 0.f};
; #pragma unroll
;         for (int ks = 0; ks < 8; ++ks) { bf16x8 qf[4];
; #pragma unroll
;             for (int mt = 0; mt < 4; ++mt) qf[mt] = *(const LAS bf16x8*)(Qs + (wt2 * 64 + mt * 16 + fr) * 264 + ks * 32 + fq * 8);
; #pragma unroll
;             for (int mt = 0; mt < 4; ++mt)
; #pragma unroll
;                 for (int nt = 0; nt < 2; ++nt) sacc[mt][nt] = __builtin_amdgcn_mfma_f32_16x16x32_bf16(kfa[ks][nt], qf[mt], sacc[mt][nt], 0, 0, 0); }
.LBB0_585:
	s_or_b64 exec, exec, s[4:5]
	v_lshl_or_b32 v209, v62, 6, v201
	s_movk_i32 s4, 0x210
	v_and_b32_e32 v124, 48, v196
	v_mul_lo_u32 v208, v209, s4
	v_add_u32_e32 v91, 0, v124
	v_add_u32_e32 v227, 0x2100, v208
	v_add_u32_e32 v223, 0x4200, v208
	v_add_u32_e32 v222, 0x6300, v208
	v_add_u32_e32 v215, v91, v208
	v_add_u32_e32 v114, v91, v227
	v_add_u32_e32 v115, v91, v223
	v_add_u32_e32 v91, v91, v222
	s_waitcnt lgkmcnt(0)
	s_barrier
	ds_read_b128 v[60:63], v215
	ds_read_b128 v[68:71], v215 offset:64
	ds_read_b128 v[76:79], v114
	ds_read_b128 v[80:83], v114 offset:64
	ds_read_b128 v[94:97], v115
	ds_read_b128 v[98:101], v115 offset:64
	ds_read_b128 v[106:109], v91
	ds_read_b128 v[110:113], v91 offset:64
	s_waitcnt vmcnt(15) lgkmcnt(7)
	v_mfma_f32_16x16x32_bf16 v[72:75], v[52:55], v[60:63], 0
	s_or_b32 s4, s59, s24
	s_lshl_b32 s4, s4, 17
	s_add_u32 s4, s58, s4
	s_waitcnt vmcnt(13)
	v_mfma_f32_16x16x32_bf16 v[60:63], v[56:59], v[60:63], 0
	s_addc_u32 s5, s57, 0
	v_lshlrev_b32_e32 v89, 13, v221
	s_waitcnt lgkmcnt(5)
	v_mfma_f32_16x16x32_bf16 v[84:87], v[52:55], v[76:79], 0
	v_mfma_f32_16x16x32_bf16 v[76:79], v[56:59], v[76:79], 0
	s_waitcnt lgkmcnt(3)
	v_mfma_f32_16x16x32_bf16 v[102:105], v[52:55], v[94:97], 0
	v_mfma_f32_16x16x32_bf16 v[94:97], v[56:59], v[94:97], 0
	s_waitcnt lgkmcnt(1)
	v_mfma_f32_16x16x32_bf16 v[52:55], v[52:55], v[106:109], 0
	v_mfma_f32_16x16x32_bf16 v[56:59], v[56:59], v[106:109], 0
	v_mfma_f32_16x16x32_bf16 v[72:75], v[44:47], v[68:71], v[72:75]
	s_waitcnt vmcnt(12)
	v_mfma_f32_16x16x32_bf16 v[60:63], v[48:51], v[68:71], v[60:63]
	v_mfma_f32_16x16x32_bf16 v[68:71], v[44:47], v[80:83], v[84:87]
	v_mfma_f32_16x16x32_bf16 v[76:79], v[48:51], v[80:83], v[76:79]
	v_mfma_f32_16x16x32_bf16 v[80:83], v[44:47], v[98:101], v[102:105]
	v_mfma_f32_16x16x32_bf16 v[84:87], v[48:51], v[98:101], v[94:97]
	s_waitcnt lgkmcnt(0)
	v_mfma_f32_16x16x32_bf16 v[44:47], v[44:47], v[110:113], v[52:55]
	v_mfma_f32_16x16x32_bf16 v[48:51], v[48:51], v[110:113], v[56:59]
	s_nop 1
	ds_read_b128 v[52:55], v215 offset:128
	ds_read_b128 v[56:59], v215 offset:192
	s_waitcnt vmcnt(11) lgkmcnt(1)
	v_mfma_f32_16x16x32_bf16 v[72:75], v[36:39], v[52:55], v[72:75]
	s_waitcnt vmcnt(9)
	v_mfma_f32_16x16x32_bf16 v[52:55], v[40:43], v[52:55], v[60:63]
	s_nop 2
	ds_read_b128 v[60:63], v114 offset:128
	ds_read_b128 v[94:97], v114 offset:192
	s_waitcnt lgkmcnt(1)
	v_mfma_f32_16x16x32_bf16 v[68:71], v[36:39], v[60:63], v[68:71]
	v_mfma_f32_16x16x32_bf16 v[60:63], v[40:43], v[60:63], v[76:79]
	s_nop 2
	ds_read_b128 v[76:79], v115 offset:128
	ds_read_b128 v[98:101], v115 offset:192
	s_waitcnt lgkmcnt(1)
	v_mfma_f32_16x16x32_bf16 v[80:83], v[36:39], v[76:79], v[80:83]
	v_mfma_f32_16x16x32_bf16 v[76:79], v[40:43], v[76:79], v[84:87]
	s_nop 2
	ds_read_b128 v[84:87], v91 offset:128
	ds_read_b128 v[102:105], v91 offset:192
	s_waitcnt lgkmcnt(1)
	v_mfma_f32_16x16x32_bf16 v[36:39], v[36:39], v[84:87], v[44:47]
	v_mfma_f32_16x16x32_bf16 v[40:43], v[40:43], v[84:87], v[48:51]
	v_mfma_f32_16x16x32_bf16 v[44:47], v[28:31], v[56:59], v[72:75]
	s_waitcnt vmcnt(8)
	v_mfma_f32_16x16x32_bf16 v[48:51], v[32:35], v[56:59], v[52:55]
	v_mfma_f32_16x16x32_bf16 v[52:55], v[28:31], v[94:97], v[68:71]
	v_mfma_f32_16x16x32_bf16 v[56:59], v[32:35], v[94:97], v[60:63]
	v_mfma_f32_16x16x32_bf16 v[60:63], v[28:31], v[98:101], v[80:83]
	v_mfma_f32_16x16x32_bf16 v[68:71], v[32:35], v[98:101], v[76:79]
	s_waitcnt lgkmcnt(0)
	v_mfma_f32_16x16x32_bf16 v[28:31], v[28:31], v[102:105], v[36:39]
	v_mfma_f32_16x16x32_bf16 v[32:35], v[32:35], v[102:105], v[40:43]
	s_nop 1
	ds_read_b128 v[36:39], v215 offset:256
	ds_read_b128 v[40:43], v215 offset:320
	s_waitcnt vmcnt(7) lgkmcnt(1)
	v_mfma_f32_16x16x32_bf16 v[44:47], v[20:23], v[36:39], v[44:47]
	s_waitcnt vmcnt(5)
	v_mfma_f32_16x16x32_bf16 v[36:39], v[24:27], v[36:39], v[48:51]
	s_nop 2
	ds_read_b128 v[48:51], v114 offset:256
	ds_read_b128 v[72:75], v114 offset:320
	s_waitcnt lgkmcnt(1)
	v_mfma_f32_16x16x32_bf16 v[52:55], v[20:23], v[48:51], v[52:55]
	v_mfma_f32_16x16x32_bf16 v[48:51], v[24:27], v[48:51], v[56:59]
	s_nop 2
	ds_read_b128 v[56:59], v115 offset:256
	ds_read_b128 v[76:79], v115 offset:320
	s_waitcnt lgkmcnt(1)
	v_mfma_f32_16x16x32_bf16 v[60:63], v[20:23], v[56:59], v[60:63]
	v_mfma_f32_16x16x32_bf16 v[56:59], v[24:27], v[56:59], v[68:71]
	s_nop 2
	ds_read_b128 v[68:71], v91 offset:256
	ds_read_b128 v[80:83], v91 offset:320
	s_waitcnt lgkmcnt(1)
	v_mfma_f32_16x16x32_bf16 v[20:23], v[20:23], v[68:71], v[28:31]
	v_mfma_f32_16x16x32_bf16 v[24:27], v[24:27], v[68:71], v[32:35]
	v_mfma_f32_16x16x32_bf16 v[28:31], v[12:15], v[40:43], v[44:47]
	s_waitcnt vmcnt(4)
	v_mfma_f32_16x16x32_bf16 v[32:35], v[16:19], v[40:43], v[36:39]
	v_mfma_f32_16x16x32_bf16 v[36:39], v[12:15], v[72:75], v[52:55]
	v_mfma_f32_16x16x32_bf16 v[40:43], v[16:19], v[72:75], v[48:51]
	v_mfma_f32_16x16x32_bf16 v[44:47], v[12:15], v[76:79], v[60:63]
	v_mfma_f32_16x16x32_bf16 v[48:51], v[16:19], v[76:79], v[56:59]
	s_waitcnt lgkmcnt(0)
	v_mfma_f32_16x16x32_bf16 v[12:15], v[12:15], v[80:83], v[20:23]
	v_mfma_f32_16x16x32_bf16 v[16:19], v[16:19], v[80:83], v[24:27]
	s_nop 1
	ds_read_b128 v[20:23], v215 offset:384
	ds_read_b128 v[24:27], v215 offset:448
	s_waitcnt vmcnt(3) lgkmcnt(1)
	v_mfma_f32_16x16x32_bf16 v[28:31], v[8:11], v[20:23], v[28:31]
	s_waitcnt vmcnt(1)
	v_mfma_f32_16x16x32_bf16 v[20:23], v[4:7], v[20:23], v[32:35]
	s_nop 2
	ds_read_b128 v[32:35], v114 offset:384
	ds_read_b128 v[60:63], v114 offset:448
	s_waitcnt lgkmcnt(1)
	v_mfma_f32_16x16x32_bf16 v[36:39], v[8:11], v[32:35], v[36:39]
	v_mfma_f32_16x16x32_bf16 v[32:35], v[4:7], v[32:35], v[40:43]
	s_nop 2
	ds_read_b128 v[40:43], v115 offset:384
	ds_read_b128 v[68:71], v115 offset:448
	ds_read_b128 v[98:101], v91 offset:448
	s_waitcnt lgkmcnt(2)
; #define LAS __attribute__((address_space(3)))
; __device__ __forceinline__ unsigned cvt_pk_bf16(float lo, float hi) { unsigned r; asm volatile("v_cvt_pk_bf16_f32 %0, %1, %2" : "=v"(r) : "v"(lo), "v"(hi)); return r; }
; __device__ void passB_unit(const Params& p, LAS unsigned char* lds, int u, bool do_store = true) {
;     ...
;         for (int ks = 0; ks < 8; ++ks) { bf16x8 qf[4];
; #pragma unroll
;             for (int mt = 0; mt < 4; ++mt) qf[mt] = *(const LAS bf16x8*)(Qs + (wt2 * 64 + mt * 16 + fr) * 264 + ks * 32 + fq * 8);
; #pragma unroll
;             for (int mt = 0; mt < 4; ++mt)
; #pragma unroll
;                 for (int nt = 0; nt < 2; ++nt) sacc[mt][nt] = __builtin_amdgcn_mfma_f32_16x16x32_bf16(kfa[ks][nt], qf[mt], sacc[mt][nt], 0, 0, 0); }
;         PB_ISSUE(0); PB_ISSUE(1);
;         __builtin_amdgcn_sched_barrier(0);
; #pragma unroll
;         for (int mt = 0; mt < 4; ++mt) { const int t = wt2 * 64 + mt * 16 + fr; const float Mf = MA[t], Mb = MA[128 + t]; float rf = 0.f, rb = 0.f;
; #pragma unroll
;             for (int nt = 0; nt < 2; ++nt) { const int s0 = w4 * 32 + nt * 16 + fq * 4; float pf[4], pb[4];
; #pragma unroll
;                 for (int r = 0; r < 4; ++r) { const int s = s0 + r; const float val = sacc[mt][nt][r];
;                     const float ef = __expf(fminf(aA[s] - Mf, 0.f)), eb = __expf(fminf(aA[128 + s] - Mb, 0.f));
;                     pf[r] = (s <= t) ? val * ef : 0.f; pb[r] = (s >= t) ? val * eb : 0.f; rf += pf[r]; rb += pb[r]; }
;                 u32x2 wf, wb; wf.x = cvt_pk_bf16(pf[0], pf[1]); wf.y = cvt_pk_bf16(pf[2], pf[3]); wb.x = cvt_pk_bf16(pb[0], pb[1]); wb.y = cvt_pk_bf16(pb[2], pb[3]);
;                 *(LAS u32x2*)(Pd + t * 136 + s0) = wf; *(LAS u32x2*)(Pd + 128 * 136 + t * 136 + s0) = wb; }
	v_mfma_f32_16x16x32_bf16 v[72:75], v[8:11], v[40:43], v[44:47]
	s_nop 2
	ds_read_b128 v[44:47], v91 offset:384
	s_waitcnt lgkmcnt(0)
	v_mfma_f32_16x16x32_bf16 v[12:15], v[8:11], v[44:47], v[12:15]
	v_mov_b32_e32 v9, 0
	v_lshlrev_b32_e32 v8, 15, v221
	v_lshl_add_u64 v[10:11], s[4:5], 0, v[8:9]
	v_mov_b32_e32 v91, v9
	v_lshl_add_u64 v[136:137], v[10:11], 0, v[90:91]
	s_movk_i32 s4, 0x2000
	v_mfma_f32_16x16x32_bf16 v[94:97], v[4:7], v[40:43], v[48:51]
	v_mfma_f32_16x16x32_bf16 v[102:105], v[4:7], v[44:47], v[16:19]
	v_add_co_u32_e32 v4, vcc, s4, v136
	s_movk_i32 s4, 0x3000
	s_nop 0
	v_addc_co_u32_e32 v5, vcc, 0, v137, vcc
	v_add_co_u32_e32 v114, vcc, s4, v136
	s_movk_i32 s4, 0x1000
	s_nop 0
	v_addc_co_u32_e32 v115, vcc, 0, v137, vcc
	v_add_co_u32_e32 v6, vcc, s4, v136
	v_mfma_f32_16x16x32_bf16 v[106:109], v[0:3], v[24:27], v[28:31]
	s_nop 0
	v_addc_co_u32_e32 v7, vcc, 0, v137, vcc
	global_load_dwordx4 v[56:59], v[136:137], off nt
	global_load_dwordx4 v[48:51], v[136:137], off offset:1024 nt
	global_load_dwordx4 v[52:55], v[4:5], off offset:1024 nt
	global_load_dwordx4 v[40:43], v[4:5], off offset:2048 nt
	s_waitcnt vmcnt(4)
	v_mfma_f32_16x16x32_bf16 v[110:113], v[64:67], v[24:27], v[20:23]
	v_mfma_f32_16x16x32_bf16 v[84:87], v[0:3], v[60:63], v[36:39]
	v_mfma_f32_16x16x32_bf16 v[80:83], v[64:67], v[60:63], v[32:35]
	global_load_dwordx4 v[44:47], v[136:137], off offset:2048 nt
	s_nop 1
	global_load_dwordx4 v[32:35], v[136:137], off offset:3072 nt
	global_load_dwordx4 v[36:39], v[4:5], off offset:3072 nt
	global_load_dwordx4 v[24:27], v[6:7], off nt
	global_load_dwordx4 v[28:31], v[114:115], off nt
	global_load_dwordx4 v[16:19], v[114:115], off offset:1024 nt
	global_load_dwordx4 v[20:23], v[6:7], off offset:1024 nt
	global_load_dwordx4 v[8:11], v[6:7], off offset:2048 nt
	v_mfma_f32_16x16x32_bf16 v[76:79], v[0:3], v[68:71], v[72:75]
	v_mfma_f32_16x16x32_bf16 v[72:75], v[64:67], v[68:71], v[94:97]
	v_mfma_f32_16x16x32_bf16 v[68:71], v[0:3], v[98:101], v[12:15]
	global_load_dwordx4 v[60:63], v[114:115], off offset:-4096 nt
	s_nop 0
	global_load_dwordx4 v[4:7], v[6:7], off offset:3072 nt
	s_nop 0
	global_load_dwordx4 v[12:15], v[114:115], off offset:2048 nt
	global_load_dwordx4 v[0:3], v[114:115], off offset:3072 nt
	v_mfma_f32_16x16x32_bf16 v[64:67], v[64:67], v[98:101], v[102:105]
	v_lshlrev_b32_e32 v210, 2, v93
	v_lshl_or_b32 v91, v221, 5, v210
	v_lshl_add_u32 v93, v209, 2, 0
	v_add_u32_e32 v93, 0x22400, v93
	v_lshl_add_u32 v96, v91, 2, s51
	ds_read2st64_b32 v[118:119], v93 offset1:2
	ds_read_b128 v[100:103], v96
	ds_read_b128 v[114:117], v96 offset:512
	s_movk_i32 s6, 0x88
	v_cmp_gt_i32_e32 vcc, v91, v209
	v_mul_lo_u32 v104, v209, s6
	s_waitcnt lgkmcnt(1)
	v_sub_f32_e32 v94, v100, v118
	v_min_f32_e32 v94, 0, v94
	s_waitcnt lgkmcnt(0)
	v_sub_f32_e32 v95, v114, v119
	v_mul_f32_e32 v94, 0x3fb8aa3b, v94
	v_min_f32_e32 v95, 0, v95
	v_sub_f32_e32 v99, v115, v119
	v_exp_f32_e32 v94, v94
	v_mul_f32_e32 v95, 0x3fb8aa3b, v95
	v_min_f32_e32 v99, 0, v99
	v_exp_f32_e32 v95, v95
	v_mul_f32_e32 v99, 0x3fb8aa3b, v99
	v_exp_f32_e32 v99, v99
	v_mul_f32_e32 v94, v106, v94
	v_cndmask_b32_e64 v97, v94, 0, vcc
	v_mul_f32_e32 v94, v106, v95
	v_cmp_lt_i32_e64 s[6:7], v91, v209
	v_sub_f32_e32 v98, v101, v118
	v_or_b32_e32 v100, 1, v91
	v_cndmask_b32_e64 v105, v94, 0, s[6:7]
	v_min_f32_e32 v98, 0, v98
	v_mul_f32_e32 v99, v107, v99
	v_cmp_ge_i32_e64 s[10:11], v100, v209
	v_add_f32_e32 v95, 0, v105
	v_mul_f32_e32 v98, 0x3fb8aa3b, v98
	v_cndmask_b32_e64 v101, 0, v99, s[10:11]
	v_exp_f32_e32 v98, v98
	v_add_f32_e32 v114, v95, v101
	v_sub_f32_e32 v95, v102, v118
	v_min_f32_e32 v95, 0, v95
	v_mul_f32_e32 v95, 0x3fb8aa3b, v95
	v_exp_f32_e32 v95, v95
	v_mul_f32_e32 v98, v107, v98
	v_add_f32_e32 v94, 0, v97
	v_cndmask_b32_e64 v98, 0, v98, s[6:7]
	v_add_f32_e32 v99, v94, v98
	v_or_b32_e32 v94, 2, v91
	v_sub_f32_e32 v102, v116, v119
	v_mul_f32_e32 v95, v108, v95
	v_cmp_le_i32_e64 s[10:11], v94, v209
	v_min_f32_e32 v102, 0, v102
	v_mul_f32_e32 v102, 0x3fb8aa3b, v102
	v_cndmask_b32_e64 v106, 0, v95, s[10:11]
	v_add_f32_e32 v115, v99, v106
	v_sub_f32_e32 v99, v103, v118
	v_exp_f32_e32 v102, v102
	v_min_f32_e32 v99, 0, v99
	v_sub_f32_e32 v103, v117, v119
	v_mul_f32_e32 v99, 0x3fb8aa3b, v99
	v_min_f32_e32 v103, 0, v103
	v_exp_f32_e32 v99, v99
	v_mul_f32_e32 v103, 0x3fb8aa3b, v103
	v_exp_f32_e32 v103, v103
	v_mul_f32_e32 v95, v108, v102
	v_cmp_ge_i32_e64 s[10:11], v94, v209
	v_mul_f32_e32 v99, v109, v99
	v_lshlrev_b32_e32 v93, 1, v104
	v_cndmask_b32_e64 v102, 0, v95, s[10:11]
	v_or_b32_e32 v95, 3, v91
	v_cmp_le_i32_e64 s[10:11], v95, v209
	v_cvt_pk_bf16_f32 v98, v97, v98
	v_add_f32_e32 v97, v114, v102
	v_lshlrev_b32_e32 v214, 9, v221
	v_cndmask_b32_e64 v116, 0, v99, s[10:11]
	v_mul_f32_e32 v99, v109, v103
	v_lshlrev_b32_e32 v103, 1, v91
	v_cmp_ge_i32_e64 s[10:11], v95, v209
	v_add3_u32 v121, s46, v93, v103
	v_add3_u32 v122, s48, v93, v103
	v_or_b32_e32 v93, 16, v91
	v_cndmask_b32_e64 v117, 0, v99, s[10:11]
	v_cvt_pk_bf16_f32 v99, v106, v116
	v_cvt_pk_bf16_f32 v106, v105, v101
	v_cvt_pk_bf16_f32 v107, v102, v117
	ds_write_b64 v121, v[98:99]
	ds_write_b64 v122, v[106:107]
	v_lshl_add_u32 v101, v93, 2, s51
	ds_read_b128 v[106:109], v101
	v_add_f32_e32 v98, v115, v116
	v_add_f32_e32 v97, v97, v117
	ds_read_b128 v[114:117], v101 offset:512
	v_cmp_le_i32_e64 s[10:11], v93, v209
	s_waitcnt lgkmcnt(1)
	v_sub_f32_e32 v99, v106, v118
	v_sub_f32_e32 v106, v107, v118
	v_min_f32_e32 v106, 0, v106
	s_waitcnt lgkmcnt(0)
; #define LAS __attribute__((address_space(3)))
; __device__ __forceinline__ unsigned cvt_pk_bf16(float lo, float hi) { unsigned r; asm volatile("v_cvt_pk_bf16_f32 %0, %1, %2" : "=v"(r) : "v"(lo), "v"(hi)); return r; }
; __device__ void passB_unit(const Params& p, LAS unsigned char* lds, int u, bool do_store = true) {
;     ...
;         for (int mt = 0; mt < 4; ++mt) { const int t = wt2 * 64 + mt * 16 + fr; const float Mf = MA[t], Mb = MA[128 + t]; float rf = 0.f, rb = 0.f;
; #pragma unroll
;             for (int nt = 0; nt < 2; ++nt) { const int s0 = w4 * 32 + nt * 16 + fq * 4; float pf[4], pb[4];
; #pragma unroll
;                 for (int r = 0; r < 4; ++r) { const int s = s0 + r; const float val = sacc[mt][nt][r];
;                     const float ef = __expf(fminf(aA[s] - Mf, 0.f)), eb = __expf(fminf(aA[128 + s] - Mb, 0.f));
;                     pf[r] = (s <= t) ? val * ef : 0.f; pb[r] = (s >= t) ? val * eb : 0.f; rf += pf[r]; rb += pb[r]; }
;                 u32x2 wf, wb; wf.x = cvt_pk_bf16(pf[0], pf[1]); wf.y = cvt_pk_bf16(pf[2], pf[3]); wb.x = cvt_pk_bf16(pb[0], pb[1]); wb.y = cvt_pk_bf16(pb[2], pb[3]);
;                 *(LAS u32x2*)(Pd + t * 136 + s0) = wf; *(LAS u32x2*)(Pd + 128 * 136 + t * 136 + s0) = wb; }
;             rf += __shfl_xor(rf, 16); rf += __shfl_xor(rf, 32); rb += __shfl_xor(rb, 16); rb += __shfl_xor(rb, 32);
;             if (fq == 0) { rsP[w4 * 128 + t] = rf; rsP[512 + w4 * 128 + t] = rb; } }
	v_sub_f32_e32 v107, v115, v119
	v_min_f32_e32 v107, 0, v107
	v_mul_f32_e32 v106, 0x3fb8aa3b, v106
	v_mul_f32_e32 v107, 0x3fb8aa3b, v107
	v_min_f32_e32 v99, 0, v99
	v_sub_f32_e32 v102, v114, v119
	v_exp_f32_e32 v106, v106
	v_exp_f32_e32 v107, v107
	v_mul_f32_e32 v99, 0x3fb8aa3b, v99
	v_min_f32_e32 v102, 0, v102
	v_exp_f32_e32 v99, v99
	v_mul_f32_e32 v102, 0x3fb8aa3b, v102
	v_exp_f32_e32 v102, v102
	v_mul_f32_e32 v106, v111, v106
	v_mul_f32_e32 v107, v111, v107
	v_sub_f32_e32 v108, v108, v118
	v_sub_f32_e32 v111, v116, v119
	v_min_f32_e32 v108, 0, v108
	v_min_f32_e32 v111, 0, v111
	v_mul_f32_e32 v99, v110, v99
	v_mul_f32_e32 v108, 0x3fb8aa3b, v108
	v_mul_f32_e32 v111, 0x3fb8aa3b, v111
	v_cndmask_b32_e64 v105, 0, v99, s[10:11]
	v_mul_f32_e32 v99, v110, v102
	v_cmp_ge_i32_e64 s[10:11], v93, v209
	v_exp_f32_e32 v108, v108
	v_exp_f32_e32 v111, v111
	v_cndmask_b32_e64 v102, 0, v99, s[10:11]
	v_add_f32_e32 v99, v97, v102
	v_or_b32_e32 v97, 17, v91
	v_cmp_le_i32_e64 s[10:11], v97, v209
	v_sub_f32_e32 v109, v109, v118
	v_add_f32_e32 v98, v98, v105
	v_cndmask_b32_e64 v106, 0, v106, s[10:11]
	v_mul_f32_e32 v108, v112, v108
	v_mul_f32_e32 v111, v112, v111
	v_min_f32_e32 v109, 0, v109
	v_sub_f32_e32 v112, v117, v119
	v_cmp_ge_i32_e64 s[10:11], v97, v209
	v_add_f32_e32 v110, v98, v106
	v_or_b32_e32 v98, 18, v91
	v_mul_f32_e32 v109, 0x3fb8aa3b, v109
	v_min_f32_e32 v112, 0, v112
	v_cndmask_b32_e64 v107, 0, v107, s[10:11]
	v_cmp_le_i32_e64 s[10:11], v98, v209
	v_exp_f32_e32 v109, v109
	v_mul_f32_e32 v112, 0x3fb8aa3b, v112
	v_cndmask_b32_e64 v108, 0, v108, s[10:11]
	v_cmp_ge_i32_e64 s[10:11], v98, v209
	v_exp_f32_e32 v112, v112
	v_add_f32_e32 v99, v99, v107
	v_cndmask_b32_e64 v114, 0, v111, s[10:11]
	v_add_f32_e32 v111, v99, v114
	v_or_b32_e32 v99, 19, v91
	v_mul_f32_e32 v109, v113, v109
	v_cmp_le_i32_e64 s[10:11], v99, v209
	v_mul_f32_e32 v112, v113, v112
	v_add_f32_e32 v110, v110, v108
	v_cndmask_b32_e64 v109, 0, v109, s[10:11]
	v_cmp_ge_i32_e64 s[10:11], v99, v209
	v_add_f32_e32 v115, v110, v109
	v_cndmask_b32_e64 v113, 0, v112, s[10:11]
	v_add_f32_e32 v116, v111, v113
	v_cvt_pk_bf16_f32 v110, v105, v106
	v_cvt_pk_bf16_f32 v111, v108, v109
	v_cvt_pk_bf16_f32 v112, v102, v107
	s_waitcnt lgkmcnt(0)
	v_mov_b32_e32 v117, v115
	v_mov_b32_e32 v105, v115
	s_nop 1
	v_permlane16_swap_b32_e32 v117, v105
	v_add_f32_e32 v105, v105, v117
	s_waitcnt lgkmcnt(0)
	v_mov_b32_e32 v118, v116
	v_mov_b32_e32 v107, v116
	s_nop 1
	v_permlane16_swap_b32_e32 v118, v107
	v_add_f32_e32 v107, v107, v118
	v_mov_b32_e32 v106, v105
	s_nop 1
	v_permlane32_swap_b32_e32 v106, v105
	v_mov_b32_e32 v108, v107
	s_nop 1
	v_permlane32_swap_b32_e32 v108, v107
	v_add_u32_e32 v120, s47, v214
	v_cmp_gt_u32_e64 s[4:5], 16, v197
	v_lshl_add_u32 v102, v209, 2, v120
	v_cvt_pk_bf16_f32 v113, v114, v113
	ds_write_b64 v121, v[110:111] offset:32
	ds_write_b64 v122, v[112:113] offset:32
	s_and_saveexec_b64 s[10:11], s[4:5]
	s_cbranch_execz .LBB0_587
	s_waitcnt lgkmcnt(2)
	v_add_f32_e32 v107, v107, v108
	v_add_f32_e32 v105, v105, v106
	ds_write2st64_b32 v102, v105, v107 offset1:8
.LBB0_587:
	s_or_b64 exec, exec, s[10:11]
	v_or_b32_e32 v211, 16, v209
	v_lshl_add_u32 v105, v211, 2, 0
	v_add_u32_e32 v105, 0x22400, v105
	s_waitcnt lgkmcnt(2)
	ds_read_b128 v[106:109], v96
	ds_read2st64_b32 v[114:115], v105 offset1:2
	ds_read_b128 v[110:113], v96 offset:512
	v_cmp_le_i32_e64 s[10:11], v91, v211
	v_add_u32_e32 v104, 0x880, v104
	v_lshlrev_b32_e32 v105, 1, v104
	s_waitcnt lgkmcnt(1)
	v_sub_f32_e32 v106, v106, v114
	v_min_f32_e32 v106, 0, v106
	s_waitcnt lgkmcnt(0)
	v_sub_f32_e32 v110, v110, v115
	v_sub_f32_e32 v107, v107, v114
	v_mul_f32_e32 v106, 0x3fb8aa3b, v106
	v_min_f32_e32 v110, 0, v110
	v_min_f32_e32 v107, 0, v107
	v_exp_f32_e32 v106, v106
	v_mul_f32_e32 v110, 0x3fb8aa3b, v110
	v_mul_f32_e32 v107, 0x3fb8aa3b, v107
	v_sub_f32_e32 v111, v111, v115
	v_exp_f32_e32 v110, v110
	v_exp_f32_e32 v107, v107
	v_min_f32_e32 v111, 0, v111
	v_mul_f32_e32 v111, 0x3fb8aa3b, v111
	v_exp_f32_e32 v111, v111
	v_mul_f32_e32 v106, v84, v106
	v_cndmask_b32_e64 v106, 0, v106, s[10:11]
	v_mul_f32_e32 v84, v84, v110
	v_cmp_lt_i32_e64 s[10:11], v91, v211
	v_mul_f32_e32 v107, v85, v107
	v_mul_f32_e32 v85, v85, v111
	v_cndmask_b32_e64 v110, v84, 0, s[10:11]
	v_add_f32_e32 v84, 0, v106
	v_cndmask_b32_e64 v107, 0, v107, s[10:11]
	v_cmp_ge_i32_e64 s[10:11], v100, v211
	v_add_f32_e32 v117, v84, v107
	v_sub_f32_e32 v84, v108, v114
	v_cndmask_b32_e64 v111, 0, v85, s[10:11]
	v_min_f32_e32 v84, 0, v84
	v_sub_f32_e32 v85, v112, v115
	v_mul_f32_e32 v84, 0x3fb8aa3b, v84
	v_min_f32_e32 v85, 0, v85
	v_exp_f32_e32 v84, v84
	v_mul_f32_e32 v85, 0x3fb8aa3b, v85
	v_exp_f32_e32 v85, v85
	v_cmp_le_i32_e64 s[10:11], v94, v211
	v_mul_f32_e32 v84, v86, v84
	v_add_f32_e32 v116, 0, v110
	v_cndmask_b32_e64 v108, 0, v84, s[10:11]
	v_mul_f32_e32 v84, v86, v85
	v_cmp_ge_i32_e64 s[10:11], v94, v211
	v_sub_f32_e32 v85, v113, v115
	v_min_f32_e32 v85, 0, v85
	v_cndmask_b32_e64 v112, 0, v84, s[10:11]
	v_sub_f32_e32 v84, v109, v114
	v_min_f32_e32 v84, 0, v84
	v_mul_f32_e32 v84, 0x3fb8aa3b, v84
	v_exp_f32_e32 v84, v84
	v_mul_f32_e32 v85, 0x3fb8aa3b, v85
	v_exp_f32_e32 v85, v85
	v_cmp_le_i32_e64 s[10:11], v95, v211
	v_mul_f32_e32 v84, v87, v84
	v_add_f32_e32 v116, v116, v111
	v_cndmask_b32_e64 v109, 0, v84, s[10:11]
	v_mul_f32_e32 v84, v87, v85
	v_cmp_ge_i32_e64 s[10:11], v95, v211
	s_nop 1
	v_cndmask_b32_e64 v113, 0, v84, s[10:11]
	v_cvt_pk_bf16_f32 v84, v106, v107
	v_cvt_pk_bf16_f32 v85, v108, v109
	v_cvt_pk_bf16_f32 v86, v110, v111
	v_add3_u32 v110, s46, v105, v103
	v_add3_u32 v105, s48, v105, v103
	v_cvt_pk_bf16_f32 v87, v112, v113
	ds_write_b64 v110, v[84:85]
	ds_write_b64 v105, v[86:87]
	ds_read_b128 v[84:87], v101
	v_add_f32_e32 v106, v117, v108
	v_add_f32_e32 v111, v116, v112
	v_add_f32_e32 v112, v106, v109
	ds_read_b128 v[106:109], v101 offset:512
	s_waitcnt lgkmcnt(1)
; #define LAS __attribute__((address_space(3)))
; __device__ __forceinline__ unsigned cvt_pk_bf16(float lo, float hi) { unsigned r; asm volatile("v_cvt_pk_bf16_f32 %0, %1, %2" : "=v"(r) : "v"(lo), "v"(hi)); return r; }
; __device__ void passB_unit(const Params& p, LAS unsigned char* lds, int u, bool do_store = true) {
;     ...
;         for (int mt = 0; mt < 4; ++mt) { const int t = wt2 * 64 + mt * 16 + fr; const float Mf = MA[t], Mb = MA[128 + t]; float rf = 0.f, rb = 0.f;
; #pragma unroll
;             for (int nt = 0; nt < 2; ++nt) { const int s0 = w4 * 32 + nt * 16 + fq * 4; float pf[4], pb[4];
; #pragma unroll
;                 for (int r = 0; r < 4; ++r) { const int s = s0 + r; const float val = sacc[mt][nt][r];
;                     const float ef = __expf(fminf(aA[s] - Mf, 0.f)), eb = __expf(fminf(aA[128 + s] - Mb, 0.f));
;                     pf[r] = (s <= t) ? val * ef : 0.f; pb[r] = (s >= t) ? val * eb : 0.f; rf += pf[r]; rb += pb[r]; }
;                 u32x2 wf, wb; wf.x = cvt_pk_bf16(pf[0], pf[1]); wf.y = cvt_pk_bf16(pf[2], pf[3]); wb.x = cvt_pk_bf16(pb[0], pb[1]); wb.y = cvt_pk_bf16(pb[2], pb[3]);
;                 *(LAS u32x2*)(Pd + t * 136 + s0) = wf; *(LAS u32x2*)(Pd + 128 * 136 + t * 136 + s0) = wb; }
;             rf += __shfl_xor(rf, 16); rf += __shfl_xor(rf, 32); rb += __shfl_xor(rb, 16); rb += __shfl_xor(rb, 32);
;             if (fq == 0) { rsP[w4 * 128 + t] = rf; rsP[512 + w4 * 128 + t] = rb; } }
	v_sub_f32_e32 v84, v84, v114
	v_min_f32_e32 v84, 0, v84
	v_sub_f32_e32 v85, v85, v114
	v_mul_f32_e32 v84, 0x3fb8aa3b, v84
	v_min_f32_e32 v85, 0, v85
	s_waitcnt lgkmcnt(0)
	v_sub_f32_e32 v107, v107, v115
	v_exp_f32_e32 v84, v84
	v_mul_f32_e32 v85, 0x3fb8aa3b, v85
	v_min_f32_e32 v107, 0, v107
	v_sub_f32_e32 v86, v86, v114
	v_exp_f32_e32 v85, v85
	v_mul_f32_e32 v107, 0x3fb8aa3b, v107
	v_min_f32_e32 v86, 0, v86
	v_sub_f32_e32 v108, v108, v115
	v_exp_f32_e32 v107, v107
	v_mul_f32_e32 v86, 0x3fb8aa3b, v86
	v_min_f32_e32 v108, 0, v108
	v_exp_f32_e32 v86, v86
	v_mul_f32_e32 v108, 0x3fb8aa3b, v108
	v_mul_f32_e32 v84, v80, v84
	v_exp_f32_e32 v108, v108
	v_cndmask_b32_e64 v84, v84, 0, vcc
	v_mul_f32_e32 v85, v81, v85
	v_cmp_le_i32_e32 vcc, v97, v211
	v_mul_f32_e32 v81, v81, v107
	v_sub_f32_e32 v106, v106, v115
	v_cndmask_b32_e32 v85, 0, v85, vcc
	v_cmp_ge_i32_e32 vcc, v97, v211
	v_mul_f32_e32 v86, v82, v86
	v_min_f32_e32 v106, 0, v106
	v_cndmask_b32_e32 v107, 0, v81, vcc
	v_cmp_le_i32_e32 vcc, v98, v211
	v_mul_f32_e32 v82, v82, v108
	v_mul_f32_e32 v106, 0x3fb8aa3b, v106
	v_cndmask_b32_e32 v86, 0, v86, vcc
	v_cmp_ge_i32_e32 vcc, v98, v211
	v_exp_f32_e32 v106, v106
	v_add_f32_e32 v111, v111, v113
	v_cndmask_b32_e32 v108, 0, v82, vcc
	v_sub_f32_e32 v82, v87, v114
	v_min_f32_e32 v82, 0, v82
	v_sub_f32_e32 v87, v109, v115
	v_mul_f32_e32 v82, 0x3fb8aa3b, v82
	v_min_f32_e32 v87, 0, v87
	v_exp_f32_e32 v82, v82
	v_mul_f32_e32 v87, 0x3fb8aa3b, v87
	v_exp_f32_e32 v87, v87
	v_mul_f32_e32 v80, v80, v106
	v_cndmask_b32_e64 v106, v80, 0, s[6:7]
	v_add_f32_e32 v80, v112, v84
	v_add_f32_e32 v111, v111, v106
	v_mul_f32_e32 v82, v83, v82
	v_cmp_le_i32_e32 vcc, v99, v211
	v_add_f32_e32 v80, v80, v85
	v_add_f32_e32 v81, v111, v107
	v_cndmask_b32_e32 v82, 0, v82, vcc
	v_mul_f32_e32 v83, v83, v87
	v_cmp_ge_i32_e32 vcc, v99, v211
	v_add_f32_e32 v80, v80, v86
	v_add_f32_e32 v81, v81, v108
	v_cndmask_b32_e32 v87, 0, v83, vcc
	v_add_f32_e32 v80, v80, v82
	v_add_f32_e32 v109, v81, v87
	v_cvt_pk_bf16_f32 v84, v84, v85
	v_cvt_pk_bf16_f32 v85, v86, v82
	v_cvt_pk_bf16_f32 v86, v106, v107
	s_waitcnt lgkmcnt(0)
	v_mov_b32_e32 v83, v80
	s_nop 1
	v_permlane16_swap_b32_e32 v83, v80
	v_add_f32_e32 v80, v80, v83
	s_waitcnt lgkmcnt(0)
	v_mov_b32_e32 v111, v109
	v_mov_b32_e32 v82, v109
	s_nop 1
	v_permlane16_swap_b32_e32 v111, v82
	v_add_f32_e32 v82, v82, v111
	v_mov_b32_e32 v81, v80
	s_nop 1
	v_permlane32_swap_b32_e32 v81, v80
	v_mov_b32_e32 v83, v82
	s_nop 1
	v_permlane32_swap_b32_e32 v83, v82
	v_cvt_pk_bf16_f32 v87, v108, v87
	ds_write_b64 v110, v[84:85] offset:32
	ds_write_b64 v105, v[86:87] offset:32
	s_and_saveexec_b64 s[6:7], s[4:5]
	v_readlane_b32 s56, v254, 28
	v_readlane_b32 s57, v254, 29
	s_cbranch_execz .LBB0_589
	s_waitcnt lgkmcnt(2)
	v_add_f32_e32 v82, v82, v83
	v_add_f32_e32 v80, v80, v81
	v_add_u32_e32 v81, 64, v102
	ds_write2st64_b32 v81, v80, v82 offset1:8
.LBB0_589:
	s_or_b64 exec, exec, s[6:7]
	v_or_b32_e32 v212, 32, v209
	v_lshl_add_u32 v80, v212, 2, 0
	v_add_u32_e32 v80, 0x22400, v80
	s_waitcnt lgkmcnt(2)
	ds_read_b128 v[82:85], v96
	ds_read2st64_b32 v[86:87], v80 offset1:2
	v_add_u32_e32 v80, 0x880, v104
	ds_read_b128 v[104:107], v96 offset:512
	v_cmp_le_i32_e32 vcc, v91, v212
	v_lshlrev_b32_e32 v81, 1, v80
	s_waitcnt lgkmcnt(1)
	v_sub_f32_e32 v82, v82, v86
	v_min_f32_e32 v82, 0, v82
	s_waitcnt lgkmcnt(0)
	v_sub_f32_e32 v104, v104, v87
	v_sub_f32_e32 v83, v83, v86
	v_mul_f32_e32 v82, 0x3fb8aa3b, v82
	v_min_f32_e32 v104, 0, v104
	v_min_f32_e32 v83, 0, v83
	v_sub_f32_e32 v105, v105, v87
	v_exp_f32_e32 v82, v82
	v_mul_f32_e32 v104, 0x3fb8aa3b, v104
	v_mul_f32_e32 v83, 0x3fb8aa3b, v83
	v_min_f32_e32 v105, 0, v105
	v_exp_f32_e32 v104, v104
	v_exp_f32_e32 v83, v83
	v_mul_f32_e32 v105, 0x3fb8aa3b, v105
	v_exp_f32_e32 v105, v105
	v_mul_f32_e32 v82, v76, v82
	v_cndmask_b32_e32 v82, 0, v82, vcc
	v_mul_f32_e32 v76, v76, v104
	v_cmp_lt_i32_e32 vcc, v91, v212
	v_mul_f32_e32 v83, v77, v83
	v_mul_f32_e32 v77, v77, v105
	v_cndmask_b32_e64 v104, v76, 0, vcc
	v_cndmask_b32_e32 v83, 0, v83, vcc
	v_cmp_ge_i32_e32 vcc, v100, v212
	v_add_f32_e32 v76, 0, v82
	v_add_f32_e32 v76, v76, v83
	v_cndmask_b32_e32 v105, 0, v77, vcc
	v_sub_f32_e32 v77, v84, v86
	v_min_f32_e32 v77, 0, v77
	v_mul_f32_e32 v77, 0x3fb8aa3b, v77
	v_sub_f32_e32 v84, v106, v87
	v_exp_f32_e32 v77, v77
	v_min_f32_e32 v84, 0, v84
	v_mul_f32_e32 v84, 0x3fb8aa3b, v84
	v_exp_f32_e32 v84, v84
	v_mul_f32_e32 v77, v78, v77
	v_cmp_le_i32_e32 vcc, v94, v212
	v_add_f32_e32 v108, 0, v104
	v_mul_f32_e32 v78, v78, v84
	v_cndmask_b32_e32 v77, 0, v77, vcc
	v_cmp_ge_i32_e32 vcc, v94, v212
	v_add_f32_e32 v106, v76, v77
	v_sub_f32_e32 v76, v85, v86
	v_cndmask_b32_e32 v84, 0, v78, vcc
	v_min_f32_e32 v76, 0, v76
	v_sub_f32_e32 v78, v107, v87
	v_mul_f32_e32 v76, 0x3fb8aa3b, v76
	v_min_f32_e32 v78, 0, v78
	v_exp_f32_e32 v76, v76
	v_mul_f32_e32 v78, 0x3fb8aa3b, v78
	v_exp_f32_e32 v78, v78
	v_cmp_le_i32_e32 vcc, v95, v212
	v_mul_f32_e32 v76, v79, v76
	v_add_f32_e32 v108, v108, v105
	v_cndmask_b32_e32 v85, 0, v76, vcc
	v_mul_f32_e32 v76, v79, v78
	v_cmp_ge_i32_e32 vcc, v95, v212
	s_nop 1
	v_cndmask_b32_e32 v107, 0, v76, vcc
	v_cvt_pk_bf16_f32 v76, v82, v83
	v_cvt_pk_bf16_f32 v77, v77, v85
	v_cvt_pk_bf16_f32 v78, v104, v105
	v_add3_u32 v104, s46, v81, v103
	v_add3_u32 v81, s48, v81, v103
	v_cvt_pk_bf16_f32 v79, v84, v107
	ds_write_b64 v104, v[76:77]
	ds_write_b64 v81, v[78:79]
	ds_read_b128 v[76:79], v101
	v_add_f32_e32 v82, v108, v84
	v_add_f32_e32 v105, v106, v85
	v_add_f32_e32 v106, v82, v107
	ds_read_b128 v[82:85], v101 offset:512
	s_waitcnt lgkmcnt(1)
	v_sub_f32_e32 v76, v76, v86
	v_min_f32_e32 v76, 0, v76
	v_mul_f32_e32 v76, 0x3fb8aa3b, v76
	v_sub_f32_e32 v77, v77, v86
	s_waitcnt lgkmcnt(0)
; #define LAS __attribute__((address_space(3)))
; __device__ __forceinline__ unsigned cvt_pk_bf16(float lo, float hi) { unsigned r; asm volatile("v_cvt_pk_bf16_f32 %0, %1, %2" : "=v"(r) : "v"(lo), "v"(hi)); return r; }
; __device__ void passB_unit(const Params& p, LAS unsigned char* lds, int u, bool do_store = true) {
;     ...
;         for (int mt = 0; mt < 4; ++mt) { const int t = wt2 * 64 + mt * 16 + fr; const float Mf = MA[t], Mb = MA[128 + t]; float rf = 0.f, rb = 0.f;
; #pragma unroll
;             for (int nt = 0; nt < 2; ++nt) { const int s0 = w4 * 32 + nt * 16 + fq * 4; float pf[4], pb[4];
; #pragma unroll
;                 for (int r = 0; r < 4; ++r) { const int s = s0 + r; const float val = sacc[mt][nt][r];
;                     const float ef = __expf(fminf(aA[s] - Mf, 0.f)), eb = __expf(fminf(aA[128 + s] - Mb, 0.f));
;                     pf[r] = (s <= t) ? val * ef : 0.f; pb[r] = (s >= t) ? val * eb : 0.f; rf += pf[r]; rb += pb[r]; }
;                 u32x2 wf, wb; wf.x = cvt_pk_bf16(pf[0], pf[1]); wf.y = cvt_pk_bf16(pf[2], pf[3]); wb.x = cvt_pk_bf16(pb[0], pb[1]); wb.y = cvt_pk_bf16(pb[2], pb[3]);
;                 *(LAS u32x2*)(Pd + t * 136 + s0) = wf; *(LAS u32x2*)(Pd + 128 * 136 + t * 136 + s0) = wb; }
;             rf += __shfl_xor(rf, 16); rf += __shfl_xor(rf, 32); rb += __shfl_xor(rb, 16); rb += __shfl_xor(rb, 32);
;             if (fq == 0) { rsP[w4 * 128 + t] = rf; rsP[512 + w4 * 128 + t] = rb; } }
	v_sub_f32_e32 v82, v82, v87
	v_min_f32_e32 v82, 0, v82
	v_exp_f32_e32 v76, v76
	v_mul_f32_e32 v82, 0x3fb8aa3b, v82
	v_min_f32_e32 v77, 0, v77
	v_sub_f32_e32 v83, v83, v87
	v_exp_f32_e32 v82, v82
	v_mul_f32_e32 v77, 0x3fb8aa3b, v77
	v_min_f32_e32 v83, 0, v83
	v_sub_f32_e32 v78, v78, v86
	v_exp_f32_e32 v77, v77
	v_mul_f32_e32 v83, 0x3fb8aa3b, v83
	v_min_f32_e32 v78, 0, v78
	v_sub_f32_e32 v84, v84, v87
	v_exp_f32_e32 v83, v83
	v_mul_f32_e32 v78, 0x3fb8aa3b, v78
	v_min_f32_e32 v84, 0, v84
	v_mul_f32_e32 v76, v72, v76
	v_cmp_le_i32_e32 vcc, v93, v212
	v_exp_f32_e32 v78, v78
	v_mul_f32_e32 v84, 0x3fb8aa3b, v84
	v_cndmask_b32_e32 v76, 0, v76, vcc
	v_mul_f32_e32 v72, v72, v82
	v_cmp_ge_i32_e32 vcc, v93, v212
	v_exp_f32_e32 v84, v84
	v_mul_f32_e32 v77, v73, v77
	v_cndmask_b32_e32 v82, 0, v72, vcc
	v_cmp_le_i32_e32 vcc, v97, v212
	v_mul_f32_e32 v73, v73, v83
	v_mul_f32_e32 v78, v74, v78
	v_cndmask_b32_e32 v77, 0, v77, vcc
	v_cmp_ge_i32_e32 vcc, v97, v212
	v_mul_f32_e32 v74, v74, v84
	v_add_f32_e32 v72, v105, v76
	v_cndmask_b32_e32 v83, 0, v73, vcc
	v_cmp_le_i32_e32 vcc, v98, v212
	v_add_f32_e32 v105, v106, v82
	v_add_f32_e32 v72, v72, v77
	v_cndmask_b32_e32 v78, 0, v78, vcc
	v_cmp_ge_i32_e32 vcc, v98, v212
	v_add_f32_e32 v73, v105, v83
	v_add_f32_e32 v72, v72, v78
	v_cndmask_b32_e32 v84, 0, v74, vcc
	v_sub_f32_e32 v74, v79, v86
	v_min_f32_e32 v74, 0, v74
	v_sub_f32_e32 v79, v85, v87
	v_mul_f32_e32 v74, 0x3fb8aa3b, v74
	v_min_f32_e32 v79, 0, v79
	v_exp_f32_e32 v74, v74
	v_mul_f32_e32 v79, 0x3fb8aa3b, v79
	v_exp_f32_e32 v79, v79
	v_cmp_le_i32_e32 vcc, v99, v212
	v_mul_f32_e32 v74, v75, v74
	v_add_f32_e32 v73, v73, v84
	v_cndmask_b32_e32 v74, 0, v74, vcc
	v_mul_f32_e32 v75, v75, v79
	v_cmp_ge_i32_e32 vcc, v99, v212
	v_add_f32_e32 v72, v72, v74
	v_cvt_pk_bf16_f32 v76, v76, v77
	v_cvt_pk_bf16_f32 v77, v78, v74
	v_cvt_pk_bf16_f32 v78, v82, v83
	s_nop 0
	v_cndmask_b32_e32 v79, 0, v75, vcc
	v_add_f32_e32 v85, v73, v79
	v_cvt_pk_bf16_f32 v79, v84, v79
	ds_write_b64 v104, v[76:77] offset:32
	ds_write_b64 v81, v[78:79] offset:32
	s_waitcnt lgkmcnt(2)
	v_mov_b32_e32 v75, v72
	s_nop 1
	v_permlane16_swap_b32_e32 v75, v72
	v_add_f32_e32 v72, v72, v75
	s_waitcnt lgkmcnt(2)
	v_mov_b32_e32 v86, v85
	v_mov_b32_e32 v74, v85
	s_nop 1
	v_permlane16_swap_b32_e32 v86, v74
	v_add_f32_e32 v74, v74, v86
	v_mov_b32_e32 v73, v72
	s_nop 1
	v_permlane32_swap_b32_e32 v73, v72
	v_mov_b32_e32 v75, v74
	s_nop 1
	v_permlane32_swap_b32_e32 v75, v74
	s_and_saveexec_b64 s[6:7], s[4:5]
	s_cbranch_execz .LBB0_591
	s_waitcnt lgkmcnt(0)
	v_add_f32_e32 v74, v74, v75
	v_add_f32_e32 v72, v72, v73
	v_add_u32_e32 v73, 0x80, v102
	ds_write2st64_b32 v73, v72, v74 offset1:8
; #define LAS __attribute__((address_space(3)))
; __device__ __forceinline__ unsigned cvt_pk_bf16(float lo, float hi) { unsigned r; asm volatile("v_cvt_pk_bf16_f32 %0, %1, %2" : "=v"(r) : "v"(lo), "v"(hi)); return r; }
; __device__ void passB_unit(const Params& p, LAS unsigned char* lds, int u, bool do_store = true) {
;     ...
;         for (int mt = 0; mt < 4; ++mt) { const int t = wt2 * 64 + mt * 16 + fr; const float Mf = MA[t], Mb = MA[128 + t]; float rf = 0.f, rb = 0.f;
; #pragma unroll
;             for (int nt = 0; nt < 2; ++nt) { const int s0 = w4 * 32 + nt * 16 + fq * 4; float pf[4], pb[4];
; #pragma unroll
;                 for (int r = 0; r < 4; ++r) { const int s = s0 + r; const float val = sacc[mt][nt][r];
;                     const float ef = __expf(fminf(aA[s] - Mf, 0.f)), eb = __expf(fminf(aA[128 + s] - Mb, 0.f));
;                     pf[r] = (s <= t) ? val * ef : 0.f; pb[r] = (s >= t) ? val * eb : 0.f; rf += pf[r]; rb += pb[r]; }
;                 u32x2 wf, wb; wf.x = cvt_pk_bf16(pf[0], pf[1]); wf.y = cvt_pk_bf16(pf[2], pf[3]); wb.x = cvt_pk_bf16(pb[0], pb[1]); wb.y = cvt_pk_bf16(pb[2], pb[3]);
;                 *(LAS u32x2*)(Pd + t * 136 + s0) = wf; *(LAS u32x2*)(Pd + 128 * 136 + t * 136 + s0) = wb; }
;             rf += __shfl_xor(rf, 16); rf += __shfl_xor(rf, 32); rb += __shfl_xor(rb, 16); rb += __shfl_xor(rb, 32);
;             if (fq == 0) { rsP[w4 * 128 + t] = rf; rsP[512 + w4 * 128 + t] = rb; } }
.LBB0_591:
	s_or_b64 exec, exec, s[6:7]
	v_or_b32_e32 v213, 48, v209
	v_lshl_add_u32 v72, v213, 2, 0
	v_add_u32_e32 v76, 0x22400, v72
	s_waitcnt lgkmcnt(0)
	ds_read_b128 v[72:75], v96
	ds_read2st64_b32 v[82:83], v76 offset1:2
	ds_read_b128 v[76:79], v96 offset:512
	v_cmp_le_i32_e32 vcc, v91, v213
	v_mov_b32_e32 v81, 0x1100
	v_lshl_add_u32 v80, v80, 1, v81
	s_waitcnt lgkmcnt(1)
	v_sub_f32_e32 v72, v72, v82
	v_min_f32_e32 v72, 0, v72
	s_waitcnt lgkmcnt(0)
	v_sub_f32_e32 v76, v76, v83
	v_sub_f32_e32 v73, v73, v82
	v_mul_f32_e32 v72, 0x3fb8aa3b, v72
	v_min_f32_e32 v76, 0, v76
	v_min_f32_e32 v73, 0, v73
	v_sub_f32_e32 v77, v77, v83
	v_exp_f32_e32 v72, v72
	v_mul_f32_e32 v76, 0x3fb8aa3b, v76
	v_mul_f32_e32 v73, 0x3fb8aa3b, v73
	v_min_f32_e32 v77, 0, v77
	v_exp_f32_e32 v76, v76
	v_exp_f32_e32 v73, v73
	v_mul_f32_e32 v77, 0x3fb8aa3b, v77
	v_exp_f32_e32 v77, v77
	v_mul_f32_e32 v72, v68, v72
	v_cndmask_b32_e32 v72, 0, v72, vcc
	v_mul_f32_e32 v68, v68, v76
	v_cmp_lt_i32_e32 vcc, v91, v213
	v_mul_f32_e32 v73, v69, v73
	v_mul_f32_e32 v69, v69, v77
	v_cndmask_b32_e64 v76, v68, 0, vcc
	v_cndmask_b32_e32 v73, 0, v73, vcc
	v_cmp_ge_i32_e32 vcc, v100, v213
	v_add_f32_e32 v68, 0, v72
	v_add_f32_e32 v68, v68, v73
	v_cndmask_b32_e32 v77, 0, v69, vcc
	v_sub_f32_e32 v69, v74, v82
	v_min_f32_e32 v69, 0, v69
	v_mul_f32_e32 v69, 0x3fb8aa3b, v69
	v_sub_f32_e32 v74, v78, v83
	v_exp_f32_e32 v69, v69
	v_min_f32_e32 v74, 0, v74
	v_mul_f32_e32 v74, 0x3fb8aa3b, v74
	v_exp_f32_e32 v74, v74
	v_mul_f32_e32 v69, v70, v69
	v_cmp_le_i32_e32 vcc, v94, v213
	v_add_f32_e32 v81, 0, v76
	v_mul_f32_e32 v70, v70, v74
	v_cndmask_b32_e32 v69, 0, v69, vcc
	v_cmp_ge_i32_e32 vcc, v94, v213
	v_add_f32_e32 v78, v68, v69
	v_sub_f32_e32 v68, v75, v82
	v_cndmask_b32_e32 v74, 0, v70, vcc
	v_min_f32_e32 v68, 0, v68
	v_sub_f32_e32 v70, v79, v83
	v_mul_f32_e32 v68, 0x3fb8aa3b, v68
	v_min_f32_e32 v70, 0, v70
	v_exp_f32_e32 v68, v68
	v_mul_f32_e32 v70, 0x3fb8aa3b, v70
	v_exp_f32_e32 v70, v70
	v_cmp_le_i32_e32 vcc, v95, v213
	v_mul_f32_e32 v68, v71, v68
	v_add_f32_e32 v81, v81, v77
	v_cndmask_b32_e32 v75, 0, v68, vcc
	v_mul_f32_e32 v68, v71, v70
	v_cmp_ge_i32_e32 vcc, v95, v213
	v_add_f32_e32 v78, v78, v75
	s_nop 0
	v_cndmask_b32_e32 v79, 0, v68, vcc
	v_cvt_pk_bf16_f32 v68, v72, v73
	v_cvt_pk_bf16_f32 v69, v69, v75
	v_cvt_pk_bf16_f32 v70, v76, v77
	v_add3_u32 v76, s46, v80, v103
	v_add3_u32 v77, s48, v80, v103
	v_cvt_pk_bf16_f32 v71, v74, v79
	ds_write_b64 v76, v[68:69]
	ds_write_b64 v77, v[70:71]
	ds_read_b128 v[68:71], v101
	v_add_f32_e32 v72, v81, v74
	v_add_f32_e32 v79, v72, v79
	ds_read_b128 v[72:75], v101 offset:512
	v_cmp_le_i32_e32 vcc, v93, v213
	s_waitcnt lgkmcnt(1)
	v_sub_f32_e32 v68, v68, v82
	v_min_f32_e32 v68, 0, v68
	v_mul_f32_e32 v68, 0x3fb8aa3b, v68
	s_waitcnt lgkmcnt(0)
	v_sub_f32_e32 v72, v72, v83
	v_min_f32_e32 v72, 0, v72
	v_sub_f32_e32 v69, v69, v82
	v_exp_f32_e32 v68, v68
	v_mul_f32_e32 v72, 0x3fb8aa3b, v72
	v_min_f32_e32 v69, 0, v69
	v_sub_f32_e32 v73, v73, v83
	v_exp_f32_e32 v72, v72
	v_mul_f32_e32 v69, 0x3fb8aa3b, v69
	v_min_f32_e32 v73, 0, v73
	v_sub_f32_e32 v70, v70, v82
	v_exp_f32_e32 v69, v69
	v_mul_f32_e32 v73, 0x3fb8aa3b, v73
	v_min_f32_e32 v70, 0, v70
	v_sub_f32_e32 v74, v74, v83
	v_exp_f32_e32 v73, v73
	v_mul_f32_e32 v70, 0x3fb8aa3b, v70
	v_min_f32_e32 v74, 0, v74
	v_mul_f32_e32 v68, v64, v68
	v_exp_f32_e32 v70, v70
	v_mul_f32_e32 v74, 0x3fb8aa3b, v74
	v_cndmask_b32_e32 v68, 0, v68, vcc
	v_mul_f32_e32 v64, v64, v72
	v_cmp_ge_i32_e32 vcc, v93, v213
	v_exp_f32_e32 v74, v74
	v_mul_f32_e32 v69, v65, v69
	v_cndmask_b32_e32 v72, 0, v64, vcc
	v_cmp_le_i32_e32 vcc, v97, v213
	v_mul_f32_e32 v65, v65, v73
	v_mul_f32_e32 v70, v66, v70
	v_cndmask_b32_e32 v69, 0, v69, vcc
	v_cmp_ge_i32_e32 vcc, v97, v213
	v_mul_f32_e32 v66, v66, v74
	v_add_f32_e32 v64, v78, v68
	v_cndmask_b32_e32 v73, 0, v65, vcc
	v_cmp_le_i32_e32 vcc, v98, v213
	v_add_f32_e32 v78, v79, v72
	v_add_f32_e32 v64, v64, v69
	v_cndmask_b32_e32 v70, 0, v70, vcc
	v_cmp_ge_i32_e32 vcc, v98, v213
	v_add_f32_e32 v65, v78, v73
	v_add_f32_e32 v64, v64, v70
	v_cndmask_b32_e32 v74, 0, v66, vcc
	v_sub_f32_e32 v66, v71, v82
	v_min_f32_e32 v66, 0, v66
	v_sub_f32_e32 v71, v75, v83
	v_mul_f32_e32 v66, 0x3fb8aa3b, v66
	v_min_f32_e32 v71, 0, v71
	v_exp_f32_e32 v66, v66
	v_mul_f32_e32 v71, 0x3fb8aa3b, v71
	v_exp_f32_e32 v71, v71
	v_cmp_le_i32_e32 vcc, v99, v213
	v_mul_f32_e32 v66, v67, v66
	v_add_f32_e32 v65, v65, v74
	v_cndmask_b32_e32 v66, 0, v66, vcc
	v_mul_f32_e32 v67, v67, v71
	v_cmp_ge_i32_e32 vcc, v99, v213
	v_add_f32_e32 v64, v64, v66
	v_cvt_pk_bf16_f32 v68, v68, v69
	v_cvt_pk_bf16_f32 v69, v70, v66
	v_cvt_pk_bf16_f32 v70, v72, v73
	s_nop 0
	v_cndmask_b32_e32 v71, 0, v67, vcc
	v_add_f32_e32 v75, v65, v71
	v_cvt_pk_bf16_f32 v71, v74, v71
	ds_write_b64 v76, v[68:69] offset:32
	ds_write_b64 v77, v[70:71] offset:32
	s_waitcnt lgkmcnt(2)
	v_mov_b32_e32 v67, v64
	s_nop 1
	v_permlane16_swap_b32_e32 v67, v64
	v_add_f32_e32 v64, v64, v67
	s_waitcnt lgkmcnt(2)
	v_mov_b32_e32 v78, v75
	v_mov_b32_e32 v66, v75
	s_nop 1
	v_permlane16_swap_b32_e32 v78, v66
	v_add_f32_e32 v66, v66, v78
	v_mov_b32_e32 v65, v64
	s_nop 1
	v_permlane32_swap_b32_e32 v65, v64
	v_mov_b32_e32 v67, v66
	s_nop 1
	v_permlane32_swap_b32_e32 v67, v66
	s_and_saveexec_b64 s[6:7], s[4:5]
	s_cbranch_execz .LBB0_593
	s_waitcnt lgkmcnt(0)
	v_add_f32_e32 v66, v66, v67
	v_add_f32_e32 v64, v64, v65
	v_add_u32_e32 v65, 0xc0, v102
	ds_write2st64_b32 v65, v64, v66 offset1:8

; #define LAS __attribute__((address_space(3)))
; __device__ void passB_unit(const Params& p, LAS unsigned char* lds, int u, bool do_store = true) {
;     ...
;     f32x4 hsum[4][4], acc[4][2];
; #pragma unroll
;     for (int q = 0; q < 12; ++q) {
;         const int nh = q / 6, d = (q % 6) / 3, kind = q % 3;
;         if (q + 2 < 12) PB_ISSUE(q + 2);
;         __builtin_amdgcn_sched_barrier(0);
;         if (kind == 0) {
; #pragma unroll
;             for (int mt = 0; mt < 4; ++mt)
; #pragma unroll
;                 for (int n2 = 0; n2 < 2; ++n2) { acc[mt][n2] = (f32x4){0.f, 0.f, 0.f, 0.f}; if (d == 0) hsum[mt][nh * 2 + n2] = (f32x4){0.f, 0.f, 0.f, 0.f}; }
;         }
;         if (kind < 2) {
; #pragma unroll
;             for (int ks = 0; ks < 4; ++ks) { bf16x8 qf[4];
; #pragma unroll
;                 for (int mt = 0; mt < 4; ++mt) qf[mt] = *(const LAS bf16x8*)(Qs + (wt2 * 64 + mt * 16 + fr) * 264 + (kind * 4 + ks) * 32 + fq * 8);
; #pragma unroll
;                 for (int mt = 0; mt < 4; ++mt)
; #pragma unroll
;                     for (int n2 = 0; n2 < 2; ++n2) acc[mt][n2] = __builtin_amdgcn_mfma_f32_16x16x32_bf16(F[q % 3][ks][n2], qf[mt], acc[mt][n2], 0, 0, 0); }
.LBB0_595:
	s_or_b64 exec, exec, s[6:7]
	s_ashr_i32 s41, s40, 31
	s_lshl_b64 s[0:1], s[40:41], 18
	v_readlane_b32 s6, v254, 31
	s_add_u32 s0, s6, s0
	v_readlane_b32 s6, v254, 32
	v_or_b32_e32 v64, s74, v89
	s_addc_u32 s1, s6, s1
	v_lshlrev_b32_e32 v84, 1, v64
	v_mov_b32_e32 v85, 0
	v_lshl_add_u64 v[64:65], s[0:1], 0, v[84:85]
	v_mov_b32_e32 v91, v85
	v_lshl_add_u64 v[144:145], v[64:65], 0, v[90:91]
	s_movk_i32 s6, 0x1000
	v_add_co_u32_e32 v138, vcc, s6, v144
	s_movk_i32 s7, 0x2000
	s_nop 0
	v_addc_co_u32_e32 v139, vcc, 0, v145, vcc
	v_add_co_u32_e32 v188, vcc, s7, v144
	s_waitcnt lgkmcnt(0)
	s_barrier
	v_addc_co_u32_e32 v189, vcc, 0, v145, vcc
	global_load_dwordx4 v[112:115], v[144:145], off
	global_load_dwordx4 v[80:83], v[144:145], off offset:1024
	global_load_dwordx4 v[108:111], v[138:139], off offset:1024
	global_load_dwordx4 v[72:75], v[138:139], off offset:2048
	global_load_dwordx4 v[76:79], v[144:145], off offset:2048
	global_load_dwordx4 v[68:71], v[144:145], off offset:3072
	global_load_dwordx4 v[116:119], v[188:189], off offset:-4096
	global_load_dwordx4 v[64:67], v[138:139], off offset:3072
	s_or_b32 s0, s77, s24
	s_lshl_b32 s0, s0, 17
	s_add_u32 s0, s76, s0
	s_addc_u32 s1, s75, 0
	v_lshlrev_b32_e32 v84, 1, v88
	v_lshl_add_u64 v[84:85], s[0:1], 0, v[84:85]
	v_and_b32_e32 v216, 0xffffff00, v196
	v_lshlrev_b32_e32 v217, 2, v201
	v_lshl_add_u64 v[156:157], v[84:85], 0, v[90:91]
	v_add3_u32 v219, s78, v216, v217
	v_add3_u32 v218, s79, v216, v217
	ds_read_b128 v[84:87], v215
	ds_read_b128 v[88:91], v215 offset:64
	ds_read_b128 v[96:99], v215 offset:8448
	ds_read_b128 v[100:103], v215 offset:8512
	ds_read_b128 v[120:123], v215 offset:16896
	ds_read_b128 v[126:129], v215 offset:16960
	ds_read_b128 v[140:143], v215 offset:25344
	ds_read_b128 v[146:149], v215 offset:25408
	s_waitcnt vmcnt(23) lgkmcnt(7)
	v_mfma_f32_16x16x32_bf16 v[92:95], v[56:59], v[84:87], 0
	s_movk_i32 s0, 0x3000
	s_waitcnt vmcnt(11)
	v_mfma_f32_16x16x32_bf16 v[84:87], v[60:63], v[84:87], 0
	s_waitcnt lgkmcnt(5)
	v_mfma_f32_16x16x32_bf16 v[104:107], v[56:59], v[96:99], 0
	v_mfma_f32_16x16x32_bf16 v[96:99], v[60:63], v[96:99], 0
	s_waitcnt lgkmcnt(3)
	v_mfma_f32_16x16x32_bf16 v[130:133], v[56:59], v[120:123], 0
	v_mfma_f32_16x16x32_bf16 v[120:123], v[60:63], v[120:123], 0
	s_waitcnt lgkmcnt(1)
	v_mfma_f32_16x16x32_bf16 v[56:59], v[56:59], v[140:143], 0
	v_mfma_f32_16x16x32_bf16 v[60:63], v[60:63], v[140:143], 0
	v_mfma_f32_16x16x32_bf16 v[92:95], v[48:51], v[88:91], v[92:95]
	v_mfma_f32_16x16x32_bf16 v[84:87], v[52:55], v[88:91], v[84:87]
	v_mfma_f32_16x16x32_bf16 v[88:91], v[48:51], v[100:103], v[104:107]
	v_mfma_f32_16x16x32_bf16 v[96:99], v[52:55], v[100:103], v[96:99]
	v_mfma_f32_16x16x32_bf16 v[100:103], v[48:51], v[126:129], v[130:133]
	v_mfma_f32_16x16x32_bf16 v[104:107], v[52:55], v[126:129], v[120:123]
	s_nop 1
	v_add_co_u32_e32 v130, vcc, s7, v156
	s_waitcnt lgkmcnt(0)
	v_mfma_f32_16x16x32_bf16 v[48:51], v[48:51], v[146:149], v[56:59]
	v_addc_co_u32_e32 v131, vcc, 0, v157, vcc
	v_add_co_u32_e32 v154, vcc, s0, v156
	v_mfma_f32_16x16x32_bf16 v[52:55], v[52:55], v[146:149], v[60:63]
	ds_read_b128 v[56:59], v215 offset:128
	s_nop 1
	ds_read_b128 v[60:63], v215 offset:192
	v_addc_co_u32_e32 v155, vcc, 0, v157, vcc
	s_waitcnt lgkmcnt(1)
	v_mfma_f32_16x16x32_bf16 v[92:95], v[44:47], v[56:59], v[92:95]
	v_mfma_f32_16x16x32_bf16 v[56:59], v[40:43], v[56:59], v[84:87]
	s_nop 2
	ds_read_b128 v[84:87], v215 offset:8576
	ds_read_b128 v[120:123], v215 offset:8640
	s_waitcnt lgkmcnt(1)
	v_mfma_f32_16x16x32_bf16 v[88:91], v[44:47], v[84:87], v[88:91]
	v_mfma_f32_16x16x32_bf16 v[84:87], v[40:43], v[84:87], v[96:99]
	s_nop 2
	ds_read_b128 v[96:99], v215 offset:17024
	ds_read_b128 v[126:129], v215 offset:17088
	s_waitcnt lgkmcnt(1)
	v_mfma_f32_16x16x32_bf16 v[100:103], v[44:47], v[96:99], v[100:103]
	v_mfma_f32_16x16x32_bf16 v[96:99], v[40:43], v[96:99], v[104:107]
	s_nop 2
	ds_read_b128 v[104:107], v215 offset:25472
	ds_read_b128 v[140:143], v215 offset:25536
	s_waitcnt lgkmcnt(1)
	v_mfma_f32_16x16x32_bf16 v[44:47], v[44:47], v[104:107], v[48:51]
	v_mfma_f32_16x16x32_bf16 v[52:55], v[40:43], v[104:107], v[52:55]
	v_mfma_f32_16x16x32_bf16 v[92:95], v[32:35], v[60:63], v[92:95]
	v_mfma_f32_16x16x32_bf16 v[56:59], v[36:39], v[60:63], v[56:59]
	v_mfma_f32_16x16x32_bf16 v[88:91], v[32:35], v[120:123], v[88:91]
	v_mfma_f32_16x16x32_bf16 v[104:107], v[36:39], v[120:123], v[84:87]
	v_mfma_f32_16x16x32_bf16 v[100:103], v[32:35], v[126:129], v[100:103]
	v_mfma_f32_16x16x32_bf16 v[126:129], v[36:39], v[126:129], v[96:99]
	global_load_dwordx4 v[120:123], v[156:157], off nt
	global_load_dwordx4 v[84:87], v[156:157], off offset:1024 nt
	s_nop 0
	global_load_dwordx4 v[96:99], v[130:131], off offset:1024 nt
	global_load_dwordx4 v[48:51], v[130:131], off offset:2048 nt
	s_waitcnt lgkmcnt(0)
	v_mfma_f32_16x16x32_bf16 v[44:47], v[32:35], v[140:143], v[44:47]
	global_load_dwordx4 v[60:63], v[156:157], off offset:2048 nt
	global_load_dwordx4 v[40:43], v[156:157], off offset:3072 nt
	global_load_dwordx4 v[132:135], v[154:155], off offset:-4096 nt
	global_load_dwordx4 v[32:35], v[130:131], off offset:3072 nt
	v_mfma_f32_16x16x32_bf16 v[36:39], v[36:39], v[140:143], v[52:55]
	s_nop 2
	ds_read_b128 v[52:55], v215 offset:256
	ds_read_b128 v[140:143], v215 offset:320
	s_waitcnt lgkmcnt(1)
	v_mfma_f32_16x16x32_bf16 v[92:95], v[24:27], v[52:55], v[92:95]
	v_mfma_f32_16x16x32_bf16 v[52:55], v[28:31], v[52:55], v[56:59]
	s_nop 2
	ds_read_b128 v[56:59], v215 offset:8704
	ds_read_b128 v[146:149], v215 offset:8768
	s_waitcnt lgkmcnt(1)
; #define LAS __attribute__((address_space(3)))
; __device__ void passB_unit(const Params& p, LAS unsigned char* lds, int u, bool do_store = true) {
;     ...
;             for (int ks = 0; ks < 4; ++ks) { bf16x8 qf[4];
; #pragma unroll
;                 for (int mt = 0; mt < 4; ++mt) qf[mt] = *(const LAS bf16x8*)(Qs + (wt2 * 64 + mt * 16 + fr) * 264 + (kind * 4 + ks) * 32 + fq * 8);
; #pragma unroll
;                 for (int mt = 0; mt < 4; ++mt)
; #pragma unroll
;                     for (int n2 = 0; n2 < 2; ++n2) acc[mt][n2] = __builtin_amdgcn_mfma_f32_16x16x32_bf16(F[q % 3][ks][n2], qf[mt], acc[mt][n2], 0, 0, 0); }
;         } else {
;             const LAS bf16_t* Pp = Pd + d * 128 * 136;
; #pragma unroll
;             for (int mt = 0; mt < 4; ++mt) { const float wv = winA[d * 128 + wt2 * 64 + mt * 16 + fr];
; #pragma unroll
;                 for (int n2 = 0; n2 < 2; ++n2) acc[mt][n2] *= wv; }
; #pragma unroll
;             for (int ks = 0; ks < 4; ++ks) { bf16x8 pf[4];
; #pragma unroll
;                 for (int mt = 0; mt < 4; ++mt) pf[mt] = *(const LAS bf16x8*)(Pp + (wt2 * 64 + mt * 16 + fr) * 136 + ks * 32 + fq * 8);
; #pragma unroll
;                 for (int mt = 0; mt < 4; ++mt)
; #pragma unroll
;                     for (int n2 = 0; n2 < 2; ++n2) acc[mt][n2] = __builtin_amdgcn_mfma_f32_16x16x32_bf16(F[q % 3][ks][n2], pf[mt], acc[mt][n2], 0, 0, 0); }
; #pragma unroll
;             for (int mt = 0; mt < 4; ++mt) { const float iv = invA[d * 128 + wt2 * 64 + mt * 16 + fr];
; #pragma unroll
;                 for (int n2 = 0; n2 < 2; ++n2) hsum[mt][nh * 2 + n2] += acc[mt][n2] * iv; }
	v_mfma_f32_16x16x32_bf16 v[88:91], v[24:27], v[56:59], v[88:91]
	v_mfma_f32_16x16x32_bf16 v[56:59], v[28:31], v[56:59], v[104:107]
	s_nop 2
	ds_read_b128 v[104:107], v215 offset:17152
	ds_read_b128 v[150:153], v215 offset:17216
	s_waitcnt lgkmcnt(1)
	v_mfma_f32_16x16x32_bf16 v[100:103], v[24:27], v[104:107], v[100:103]
	v_mfma_f32_16x16x32_bf16 v[104:107], v[28:31], v[104:107], v[126:129]
	s_nop 2
	ds_read_b128 v[126:129], v215 offset:25600
	ds_read_b128 v[158:161], v215 offset:25664
	s_waitcnt lgkmcnt(1)
	v_mfma_f32_16x16x32_bf16 v[24:27], v[24:27], v[126:129], v[44:47]
	v_mfma_f32_16x16x32_bf16 v[28:31], v[28:31], v[126:129], v[36:39]
	v_mfma_f32_16x16x32_bf16 v[36:39], v[20:23], v[140:143], v[92:95]
	v_mfma_f32_16x16x32_bf16 v[44:47], v[16:19], v[140:143], v[52:55]
	v_mfma_f32_16x16x32_bf16 v[52:55], v[20:23], v[146:149], v[88:91]
	v_mfma_f32_16x16x32_bf16 v[56:59], v[16:19], v[146:149], v[56:59]
	v_mfma_f32_16x16x32_bf16 v[88:91], v[20:23], v[150:153], v[100:103]
	v_mfma_f32_16x16x32_bf16 v[92:95], v[16:19], v[150:153], v[104:107]
	s_waitcnt lgkmcnt(0)
	v_mfma_f32_16x16x32_bf16 v[20:23], v[20:23], v[158:161], v[24:27]
	v_mfma_f32_16x16x32_bf16 v[16:19], v[16:19], v[158:161], v[28:31]
	s_nop 1
	ds_read_b128 v[24:27], v215 offset:384
	ds_read_b128 v[28:31], v215 offset:448
	s_waitcnt lgkmcnt(1)
	v_mfma_f32_16x16x32_bf16 v[36:39], v[8:11], v[24:27], v[36:39]
	s_waitcnt vmcnt(17)
	v_mfma_f32_16x16x32_bf16 v[24:27], v[12:15], v[24:27], v[44:47]
	s_nop 2
	ds_read_b128 v[44:47], v215 offset:8832
	ds_read_b128 v[100:103], v215 offset:8896
	s_waitcnt lgkmcnt(1)
	v_mfma_f32_16x16x32_bf16 v[52:55], v[8:11], v[44:47], v[52:55]
	v_mfma_f32_16x16x32_bf16 v[44:47], v[12:15], v[44:47], v[56:59]
	s_nop 2
	ds_read_b128 v[56:59], v215 offset:17280
	ds_read_b128 v[104:107], v215 offset:17344
	s_waitcnt lgkmcnt(1)
	v_mfma_f32_16x16x32_bf16 v[88:91], v[8:11], v[56:59], v[88:91]
	v_mfma_f32_16x16x32_bf16 v[56:59], v[12:15], v[56:59], v[92:95]
	s_nop 2
	ds_read_b128 v[92:95], v215 offset:25728
	ds_read_b128 v[126:129], v215 offset:25792
	s_waitcnt lgkmcnt(1)
	v_mfma_f32_16x16x32_bf16 v[12:15], v[12:15], v[92:95], v[16:19]
	v_mfma_f32_16x16x32_bf16 v[16:19], v[4:7], v[28:31], v[36:39]
	s_nop 2
	v_add_co_u32_e32 v36, vcc, s6, v156
	v_mfma_f32_16x16x32_bf16 v[8:11], v[8:11], v[92:95], v[20:23]
	s_nop 0
	v_addc_co_u32_e32 v37, vcc, 0, v157, vcc
	s_waitcnt vmcnt(16)
	v_mfma_f32_16x16x32_bf16 v[20:23], v[0:3], v[28:31], v[24:27]
	v_mfma_f32_16x16x32_bf16 v[24:27], v[4:7], v[100:103], v[52:55]
	v_mfma_f32_16x16x32_bf16 v[28:31], v[0:3], v[100:103], v[44:47]
	v_mfma_f32_16x16x32_bf16 v[140:143], v[4:7], v[104:107], v[88:91]
	v_mfma_f32_16x16x32_bf16 v[146:149], v[0:3], v[104:107], v[56:59]
	global_load_dwordx4 v[100:103], v[36:37], off nt
	s_nop 0
	global_load_dwordx4 v[88:91], v[36:37], off offset:1024 nt
	global_load_dwordx4 v[104:107], v[154:155], off nt
	global_load_dwordx4 v[92:95], v[154:155], off offset:1024 nt
	global_load_dwordx4 v[52:55], v[36:37], off offset:2048 nt
	global_load_dwordx4 v[44:47], v[36:37], off offset:3072 nt
	global_load_dwordx4 v[56:59], v[154:155], off offset:2048 nt
	s_nop 0
	global_load_dwordx4 v[36:39], v[154:155], off offset:3072 nt
	s_waitcnt lgkmcnt(0)
	v_mfma_f32_16x16x32_bf16 v[4:7], v[4:7], v[126:129], v[8:11]
	v_mfma_f32_16x16x32_bf16 v[0:3], v[0:3], v[126:129], v[12:15]
	ds_read2_b32 v[126:127], v219 offset1:16
	s_movk_i32 s1, 0x110
	v_mul_lo_u32 v8, v209, s1
	v_add3_u32 v220, s46, v124, v8
	ds_read_b128 v[12:15], v220
	s_waitcnt lgkmcnt(1)
	v_pk_mul_f32 v[10:11], v[18:19], v[126:127] op_sel_hi:[1,0]
	v_pk_mul_f32 v[8:9], v[16:17], v[126:127] op_sel_hi:[1,0]
	v_pk_mul_f32 v[18:19], v[22:23], v[126:127] op_sel_hi:[1,0]
	v_pk_mul_f32 v[16:17], v[20:21], v[126:127] op_sel_hi:[1,0]
	v_mov_b32_e32 v150, v127
	ds_read_b128 v[124:127], v220 offset:4352
	ds_read_b128 v[128:131], v220 offset:4416
	ds_read2_b32 v[154:155], v219 offset0:32 offset1:48
	ds_read_b128 v[20:23], v220 offset:64
	s_waitcnt vmcnt(23) lgkmcnt(4)
	v_mfma_f32_16x16x32_bf16 v[8:11], v[112:115], v[12:15], v[8:11]
	v_mul_f32_e64 v26, v26, v150
	v_mul_f32_e64 v27, v27, v150
	v_pk_mul_f32 v[24:25], v[24:25], v[150:151] op_sel_hi:[1,0]
	s_waitcnt vmcnt(17)
	v_mfma_f32_16x16x32_bf16 v[12:15], v[116:119], v[12:15], v[16:19]
	s_nop 2
	v_mul_f32_e64 v18, v30, v150
	v_mul_f32_e64 v19, v31, v150
	v_pk_mul_f32 v[16:17], v[28:29], v[150:151] op_sel_hi:[1,0]
	ds_read_b128 v[150:153], v220 offset:8704
	s_waitcnt lgkmcnt(4)
	v_mfma_f32_16x16x32_bf16 v[24:27], v[112:115], v[124:127], v[24:27]
	s_waitcnt lgkmcnt(2)
	v_pk_mul_f32 v[30:31], v[142:143], v[154:155] op_sel_hi:[1,0]
	v_pk_mul_f32 v[28:29], v[140:141], v[154:155] op_sel_hi:[1,0]
	ds_read_b128 v[140:143], v220 offset:8768
	v_mfma_f32_16x16x32_bf16 v[16:19], v[116:119], v[124:127], v[16:19]
	v_mul_f32_e64 v126, v148, v154
	v_mul_f32_e64 v127, v149, v154
	v_pk_mul_f32 v[124:125], v[146:147], v[154:155] op_sel_hi:[1,0]
	ds_read_b128 v[146:149], v220 offset:13056
	v_mov_b32_e32 v154, v155
	s_waitcnt lgkmcnt(2)
	v_mfma_f32_16x16x32_bf16 v[28:31], v[112:115], v[150:153], v[28:31]
	v_mul_f32_e64 v6, v6, v154
	v_mul_f32_e64 v7, v7, v154
	v_pk_mul_f32 v[4:5], v[4:5], v[154:155] op_sel_hi:[1,0]
	v_pk_mul_f32 v[2:3], v[2:3], v[154:155] op_sel_hi:[1,0]
	v_mfma_f32_16x16x32_bf16 v[124:127], v[116:119], v[150:153], v[124:127]
	ds_read_b128 v[150:153], v220 offset:13120
	v_pk_mul_f32 v[0:1], v[0:1], v[154:155] op_sel_hi:[1,0]
	s_waitcnt lgkmcnt(1)
; #define LAS __attribute__((address_space(3)))
; __device__ void passB_unit(const Params& p, LAS unsigned char* lds, int u, bool do_store = true) {
;     ...
;             for (int ks = 0; ks < 4; ++ks) { bf16x8 pf[4];
; #pragma unroll
;                 for (int mt = 0; mt < 4; ++mt) pf[mt] = *(const LAS bf16x8*)(Pp + (wt2 * 64 + mt * 16 + fr) * 136 + ks * 32 + fq * 8);
; #pragma unroll
;                 for (int mt = 0; mt < 4; ++mt)
; #pragma unroll
;                     for (int n2 = 0; n2 < 2; ++n2) acc[mt][n2] = __builtin_amdgcn_mfma_f32_16x16x32_bf16(F[q % 3][ks][n2], pf[mt], acc[mt][n2], 0, 0, 0); }
; #pragma unroll
;             for (int mt = 0; mt < 4; ++mt) { const float iv = invA[d * 128 + wt2 * 64 + mt * 16 + fr];
; #pragma unroll
;                 for (int n2 = 0; n2 < 2; ++n2) hsum[mt][nh * 2 + n2] += acc[mt][n2] * iv; }
	v_mfma_f32_16x16x32_bf16 v[4:7], v[112:115], v[146:149], v[4:7]
	v_mfma_f32_16x16x32_bf16 v[0:3], v[116:119], v[146:149], v[0:3]
	v_mfma_f32_16x16x32_bf16 v[8:11], v[80:83], v[20:23], v[8:11]
	v_mfma_f32_16x16x32_bf16 v[12:15], v[108:111], v[20:23], v[12:15]
	v_mfma_f32_16x16x32_bf16 v[20:23], v[80:83], v[128:131], v[24:27]
	v_mfma_f32_16x16x32_bf16 v[16:19], v[108:111], v[128:131], v[16:19]
	v_mfma_f32_16x16x32_bf16 v[24:27], v[80:83], v[140:143], v[28:31]
	v_mfma_f32_16x16x32_bf16 v[28:31], v[108:111], v[140:143], v[124:127]
	s_waitcnt lgkmcnt(0)
	v_mfma_f32_16x16x32_bf16 v[4:7], v[80:83], v[150:153], v[4:7]
	v_mfma_f32_16x16x32_bf16 v[0:3], v[108:111], v[150:153], v[0:3]
	ds_read_b128 v[80:83], v220 offset:128
	ds_read_b128 v[108:111], v220 offset:192
	s_waitcnt lgkmcnt(1)
	v_mfma_f32_16x16x32_bf16 v[8:11], v[76:79], v[80:83], v[8:11]
	v_mfma_f32_16x16x32_bf16 v[12:15], v[72:75], v[80:83], v[12:15]
	ds_read_b128 v[80:83], v220 offset:4480
	ds_read_b128 v[112:115], v220 offset:4544
	s_waitcnt lgkmcnt(1)
	v_mfma_f32_16x16x32_bf16 v[20:23], v[76:79], v[80:83], v[20:23]
	v_mfma_f32_16x16x32_bf16 v[16:19], v[72:75], v[80:83], v[16:19]
	ds_read_b128 v[80:83], v220 offset:8832
	ds_read_b128 v[140:143], v220 offset:8896
	s_waitcnt lgkmcnt(1)
	v_mfma_f32_16x16x32_bf16 v[24:27], v[76:79], v[80:83], v[24:27]
	v_mfma_f32_16x16x32_bf16 v[146:149], v[72:75], v[80:83], v[28:31]
	s_nop 2
	ds_read_b128 v[28:31], v220 offset:13184
	ds_read_b128 v[150:153], v220 offset:13248
	s_waitcnt lgkmcnt(1)
	v_mfma_f32_16x16x32_bf16 v[4:7], v[76:79], v[28:31], v[4:7]
	v_mfma_f32_16x16x32_bf16 v[72:75], v[72:75], v[28:31], v[0:3]
	v_mfma_f32_16x16x32_bf16 v[160:163], v[68:71], v[108:111], v[8:11]
	v_mfma_f32_16x16x32_bf16 v[20:23], v[68:71], v[112:115], v[20:23]
	s_waitcnt vmcnt(16)
	v_mfma_f32_16x16x32_bf16 v[16:19], v[64:67], v[112:115], v[16:19]
	global_load_dwordx4 v[124:127], v[188:189], off offset:-4096
	global_load_dwordx4 v[128:131], v[144:145], off
	global_load_dwordx4 v[112:115], v[144:145], off offset:1024
	v_mfma_f32_16x16x32_bf16 v[8:11], v[68:71], v[140:143], v[24:27]
	global_load_dwordx4 v[116:119], v[138:139], off offset:1024
	global_load_dwordx4 v[76:79], v[138:139], off offset:2048
	global_load_dwordx4 v[80:83], v[144:145], off offset:2048
	global_load_dwordx4 v[28:31], v[144:145], off offset:3072
	global_load_dwordx4 v[24:27], v[138:139], off offset:3072
	ds_read2_b32 v[178:179], v218 offset1:16
	ds_read2_b32 v[176:177], v218 offset0:32 offset1:48
	v_mfma_f32_16x16x32_bf16 v[108:111], v[64:67], v[108:111], v[12:15]
	s_waitcnt lgkmcnt(1)
	v_pk_fma_f32 v[158:159], v[162:163], v[178:179], 0 op_sel_hi:[1,0,0]
	v_mfma_f32_16x16x32_bf16 v[12:15], v[64:67], v[140:143], v[146:149]
	v_fma_f32 v160, v160, v178, 0
	v_fma_f32 v161, v161, v178, 0
	s_nop 2
	v_pk_fma_f32 v[162:163], v[110:111], v[178:179], 0 op_sel_hi:[1,0,0]
	v_pk_fma_f32 v[168:169], v[108:109], v[178:179], 0 op_sel_hi:[1,0,0]
	v_mfma_f32_16x16x32_bf16 v[0:3], v[68:71], v[150:153], v[4:7]
	v_mfma_f32_16x16x32_bf16 v[4:7], v[64:67], v[150:153], v[72:75]
	ds_read_b128 v[64:67], v215
	ds_read_b128 v[68:71], v215 offset:64
	ds_read_b128 v[108:111], v215 offset:8448
	ds_read_b128 v[138:141], v215 offset:8512
	ds_read_b128 v[150:153], v215 offset:16896
	ds_read_b128 v[164:167], v215 offset:16960
	ds_read_b128 v[180:183], v215 offset:25344
	ds_read_b128 v[184:187], v215 offset:25408
	s_waitcnt vmcnt(23) lgkmcnt(7)
	v_mfma_f32_16x16x32_bf16 v[72:75], v[120:123], v[64:67], 0
	s_movk_i32 s1, 0x4000
	s_movk_i32 s6, 0x5000
	s_movk_i32 s7, 0x6000
	s_waitcnt vmcnt(17)
	v_mfma_f32_16x16x32_bf16 v[64:67], v[132:135], v[64:67], 0
	s_movk_i32 s10, 0x7000
	s_waitcnt lgkmcnt(5)
	v_mfma_f32_16x16x32_bf16 v[146:149], v[120:123], v[108:111], 0
	v_mfma_f32_16x16x32_bf16 v[108:111], v[132:135], v[108:111], 0
	s_waitcnt lgkmcnt(3)
	v_mfma_f32_16x16x32_bf16 v[170:173], v[120:123], v[150:153], 0
	v_mfma_f32_16x16x32_bf16 v[150:153], v[132:135], v[150:153], 0
	s_waitcnt lgkmcnt(1)
	v_mfma_f32_16x16x32_bf16 v[120:123], v[120:123], v[180:183], 0
	v_mfma_f32_16x16x32_bf16 v[132:135], v[132:135], v[180:183], 0
	v_mfma_f32_16x16x32_bf16 v[72:75], v[84:87], v[68:71], v[72:75]
	v_mfma_f32_16x16x32_bf16 v[64:67], v[96:99], v[68:71], v[64:67]
	v_mfma_f32_16x16x32_bf16 v[68:71], v[84:87], v[138:141], v[146:149]
	v_mfma_f32_16x16x32_bf16 v[108:111], v[96:99], v[138:141], v[108:111]
	v_mfma_f32_16x16x32_bf16 v[138:141], v[84:87], v[164:167], v[170:173]
	v_mfma_f32_16x16x32_bf16 v[146:149], v[96:99], v[164:167], v[150:153]
	s_waitcnt lgkmcnt(0)
	v_mfma_f32_16x16x32_bf16 v[84:87], v[84:87], v[184:187], v[120:123]
	v_mfma_f32_16x16x32_bf16 v[96:99], v[96:99], v[184:187], v[132:135]
	s_nop 1
	ds_read_b128 v[120:123], v215 offset:128
	ds_read_b128 v[132:135], v215 offset:192
	s_waitcnt lgkmcnt(1)
	v_mfma_f32_16x16x32_bf16 v[72:75], v[60:63], v[120:123], v[72:75]
	v_mfma_f32_16x16x32_bf16 v[64:67], v[48:51], v[120:123], v[64:67]
	ds_read_b128 v[120:123], v215 offset:8576
	ds_read_b128 v[150:153], v215 offset:8640
	s_waitcnt lgkmcnt(1)
	v_mfma_f32_16x16x32_bf16 v[68:71], v[60:63], v[120:123], v[68:71]
	v_mfma_f32_16x16x32_bf16 v[108:111], v[48:51], v[120:123], v[108:111]
	ds_read_b128 v[120:123], v215 offset:17024
	ds_read_b128 v[164:167], v215 offset:17088
	s_waitcnt lgkmcnt(1)
	v_mfma_f32_16x16x32_bf16 v[138:141], v[60:63], v[120:123], v[138:141]
	v_mfma_f32_16x16x32_bf16 v[120:123], v[48:51], v[120:123], v[146:149]
	s_nop 2
	ds_read_b128 v[146:149], v215 offset:25472
	ds_read_b128 v[170:173], v215 offset:25536
	s_waitcnt lgkmcnt(1)
; #define LAS __attribute__((address_space(3)))
; __device__ void passB_unit(const Params& p, LAS unsigned char* lds, int u, bool do_store = true) {
;     ...
;         if (kind < 2) {
; #pragma unroll
;             for (int ks = 0; ks < 4; ++ks) { bf16x8 qf[4];
; #pragma unroll
;                 for (int mt = 0; mt < 4; ++mt) qf[mt] = *(const LAS bf16x8*)(Qs + (wt2 * 64 + mt * 16 + fr) * 264 + (kind * 4 + ks) * 32 + fq * 8);
; #pragma unroll
;                 for (int mt = 0; mt < 4; ++mt)
; #pragma unroll
;                     for (int n2 = 0; n2 < 2; ++n2) acc[mt][n2] = __builtin_amdgcn_mfma_f32_16x16x32_bf16(F[q % 3][ks][n2], qf[mt], acc[mt][n2], 0, 0, 0); }
	v_mfma_f32_16x16x32_bf16 v[180:183], v[48:51], v[146:149], v[96:99]
	v_add_co_u32_e32 v48, vcc, s1, v136
	s_nop 1
	v_addc_co_u32_e32 v49, vcc, 0, v137, vcc
	v_mfma_f32_16x16x32_bf16 v[60:63], v[60:63], v[146:149], v[84:87]
	v_add_co_u32_e32 v146, vcc, s6, v136
	s_nop 1
	v_addc_co_u32_e32 v147, vcc, 0, v137, vcc
	v_add_co_u32_e32 v50, vcc, s7, v136
	v_mfma_f32_16x16x32_bf16 v[72:75], v[40:43], v[132:135], v[72:75]
	s_nop 0
	v_addc_co_u32_e32 v51, vcc, 0, v137, vcc
	v_add_co_u32_e32 v174, vcc, s10, v136
	s_waitcnt vmcnt(16)
	v_mfma_f32_16x16x32_bf16 v[64:67], v[32:35], v[132:135], v[64:67]
	v_addc_co_u32_e32 v175, vcc, 0, v137, vcc
	v_mfma_f32_16x16x32_bf16 v[68:71], v[40:43], v[150:153], v[68:71]
	v_mfma_f32_16x16x32_bf16 v[108:111], v[32:35], v[150:153], v[108:111]
	v_mfma_f32_16x16x32_bf16 v[132:135], v[40:43], v[164:167], v[138:141]
	v_mfma_f32_16x16x32_bf16 v[152:155], v[32:35], v[164:167], v[120:123]
	s_nop 1
	global_load_dwordx4 v[140:143], v[146:147], off offset:-4096 nt
	global_load_dwordx4 v[148:151], v[174:175], off offset:-4096 nt
	global_load_dwordx4 v[120:123], v[48:49], off offset:1024 nt
	global_load_dwordx4 v[84:87], v[48:49], off offset:2048 nt
	s_waitcnt lgkmcnt(0)
	v_mfma_f32_16x16x32_bf16 v[40:43], v[40:43], v[170:173], v[60:63]
	global_load_dwordx4 v[136:139], v[50:51], off offset:1024 nt
	s_nop 1
	global_load_dwordx4 v[60:63], v[48:49], off offset:3072 nt
	global_load_dwordx4 v[96:99], v[50:51], off offset:2048 nt
	s_nop 0
	global_load_dwordx4 v[48:51], v[50:51], off offset:3072 nt
	v_mfma_f32_16x16x32_bf16 v[32:35], v[32:35], v[170:173], v[180:183]
	ds_read_b128 v[164:167], v215 offset:256
	ds_read_b128 v[170:173], v215 offset:320
	s_waitcnt vmcnt(23) lgkmcnt(1)
	v_mfma_f32_16x16x32_bf16 v[72:75], v[100:103], v[164:167], v[72:75]
	s_waitcnt vmcnt(21)
	v_mfma_f32_16x16x32_bf16 v[64:67], v[104:107], v[164:167], v[64:67]
	ds_read_b128 v[164:167], v215 offset:8704
	ds_read_b128 v[180:183], v215 offset:8768
	s_waitcnt lgkmcnt(1)
	v_mfma_f32_16x16x32_bf16 v[68:71], v[100:103], v[164:167], v[68:71]
	v_mfma_f32_16x16x32_bf16 v[108:111], v[104:107], v[164:167], v[108:111]
	ds_read_b128 v[164:167], v215 offset:17152
	ds_read_b128 v[184:187], v215 offset:17216
	s_waitcnt lgkmcnt(1)
	v_mfma_f32_16x16x32_bf16 v[132:135], v[100:103], v[164:167], v[132:135]
	v_mfma_f32_16x16x32_bf16 v[152:155], v[104:107], v[164:167], v[152:155]
	ds_read_b128 v[164:167], v215 offset:25600
	ds_read_b128 v[190:193], v215 offset:25664
	s_waitcnt lgkmcnt(1)
	v_mfma_f32_16x16x32_bf16 v[40:43], v[100:103], v[164:167], v[40:43]
	v_mfma_f32_16x16x32_bf16 v[32:35], v[104:107], v[164:167], v[32:35]
	v_mfma_f32_16x16x32_bf16 v[72:75], v[88:91], v[170:173], v[72:75]
	s_waitcnt vmcnt(20)
	v_mfma_f32_16x16x32_bf16 v[64:67], v[92:95], v[170:173], v[64:67]
	v_mfma_f32_16x16x32_bf16 v[68:71], v[88:91], v[180:183], v[68:71]
	v_mfma_f32_16x16x32_bf16 v[100:103], v[92:95], v[180:183], v[108:111]
	v_mfma_f32_16x16x32_bf16 v[104:107], v[88:91], v[184:187], v[132:135]
	v_mfma_f32_16x16x32_bf16 v[108:111], v[92:95], v[184:187], v[152:155]
	s_waitcnt lgkmcnt(0)
	v_mfma_f32_16x16x32_bf16 v[40:43], v[88:91], v[190:193], v[40:43]
	v_mfma_f32_16x16x32_bf16 v[32:35], v[92:95], v[190:193], v[32:35]
	ds_read_b128 v[88:91], v215 offset:384
	ds_read_b128 v[92:95], v215 offset:448
	s_waitcnt vmcnt(19) lgkmcnt(1)
	v_mfma_f32_16x16x32_bf16 v[72:75], v[52:55], v[88:91], v[72:75]
	s_waitcnt vmcnt(17)
	v_mfma_f32_16x16x32_bf16 v[64:67], v[56:59], v[88:91], v[64:67]
	ds_read_b128 v[88:91], v215 offset:8832
	ds_read_b128 v[132:135], v215 offset:8896
	s_waitcnt lgkmcnt(1)
	v_mfma_f32_16x16x32_bf16 v[68:71], v[52:55], v[88:91], v[68:71]
	v_mfma_f32_16x16x32_bf16 v[88:91], v[56:59], v[88:91], v[100:103]
	s_nop 2
	ds_read_b128 v[100:103], v215 offset:17280
	ds_read_b128 v[152:155], v215 offset:17344
	s_waitcnt lgkmcnt(1)
	v_mfma_f32_16x16x32_bf16 v[104:107], v[52:55], v[100:103], v[104:107]
	v_mfma_f32_16x16x32_bf16 v[100:103], v[56:59], v[100:103], v[108:111]
	s_nop 2
	ds_read_b128 v[108:111], v215 offset:25728
	ds_read_b128 v[164:167], v215 offset:25792
	s_waitcnt lgkmcnt(1)
	v_mfma_f32_16x16x32_bf16 v[40:43], v[52:55], v[108:111], v[40:43]
	v_mfma_f32_16x16x32_bf16 v[32:35], v[56:59], v[108:111], v[32:35]
	v_mfma_f32_16x16x32_bf16 v[52:55], v[44:47], v[92:95], v[72:75]
	s_waitcnt vmcnt(16)
	v_mfma_f32_16x16x32_bf16 v[92:95], v[36:39], v[92:95], v[64:67]
	v_mfma_f32_16x16x32_bf16 v[170:173], v[44:47], v[132:135], v[68:71]
	v_mfma_f32_16x16x32_bf16 v[132:135], v[36:39], v[132:135], v[88:91]
	v_mfma_f32_16x16x32_bf16 v[180:183], v[44:47], v[152:155], v[104:107]
	v_mfma_f32_16x16x32_bf16 v[152:155], v[36:39], v[152:155], v[100:103]
	s_nop 1
	global_load_dwordx4 v[104:107], v[146:147], off nt
	global_load_dwordx4 v[88:91], v[146:147], off offset:1024 nt
	global_load_dwordx4 v[108:111], v[174:175], off nt
	global_load_dwordx4 v[100:103], v[174:175], off offset:1024 nt
	global_load_dwordx4 v[68:71], v[146:147], off offset:2048 nt
	global_load_dwordx4 v[64:67], v[146:147], off offset:3072 nt
	global_load_dwordx4 v[72:75], v[174:175], off offset:2048 nt
	global_load_dwordx4 v[56:59], v[174:175], off offset:3072 nt
	s_waitcnt lgkmcnt(0)
	v_mfma_f32_16x16x32_bf16 v[40:43], v[44:47], v[164:167], v[40:43]
	v_mfma_f32_16x16x32_bf16 v[32:35], v[36:39], v[164:167], v[32:35]
	ds_read2_b32 v[146:147], v219 offset0:128 offset1:144
	ds_read_b128 v[36:39], v220 offset:34816
	ds_read2_b32 v[174:175], v219 offset0:160 offset1:176
	ds_read_b128 v[184:187], v220 offset:39232
	ds_read_b128 v[190:193], v220 offset:43520
	s_waitcnt lgkmcnt(4)
; #define LAS __attribute__((address_space(3)))
; __device__ void passB_unit(const Params& p, LAS unsigned char* lds, int u, bool do_store = true) {
;     ...
;             const LAS bf16_t* Pp = Pd + d * 128 * 136;
; #pragma unroll
;             for (int mt = 0; mt < 4; ++mt) { const float wv = winA[d * 128 + wt2 * 64 + mt * 16 + fr];
; #pragma unroll
;                 for (int n2 = 0; n2 < 2; ++n2) acc[mt][n2] *= wv; }
; #pragma unroll
;             for (int ks = 0; ks < 4; ++ks) { bf16x8 pf[4];
; #pragma unroll
;                 for (int mt = 0; mt < 4; ++mt) pf[mt] = *(const LAS bf16x8*)(Pp + (wt2 * 64 + mt * 16 + fr) * 136 + ks * 32 + fq * 8);
; #pragma unroll
;                 for (int mt = 0; mt < 4; ++mt)
; #pragma unroll
;                     for (int n2 = 0; n2 < 2; ++n2) acc[mt][n2] = __builtin_amdgcn_mfma_f32_16x16x32_bf16(F[q % 3][ks][n2], pf[mt], acc[mt][n2], 0, 0, 0); }
; #pragma unroll
;             for (int mt = 0; mt < 4; ++mt) { const float iv = invA[d * 128 + wt2 * 64 + mt * 16 + fr];
; #pragma unroll
;                 for (int n2 = 0; n2 < 2; ++n2) hsum[mt][nh * 2 + n2] += acc[mt][n2] * iv; }
	v_pk_mul_f32 v[46:47], v[54:55], v[146:147] op_sel_hi:[1,0]
	v_pk_mul_f32 v[44:45], v[52:53], v[146:147] op_sel_hi:[1,0]
	v_pk_mul_f32 v[54:55], v[94:95], v[146:147] op_sel_hi:[1,0]
	v_pk_mul_f32 v[52:53], v[92:93], v[146:147] op_sel_hi:[1,0]
	v_mov_b32_e32 v146, v147
	ds_read_b128 v[92:95], v220 offset:34880
	v_pk_mul_f32 v[166:167], v[172:173], v[146:147] op_sel_hi:[1,0]
	v_pk_mul_f32 v[164:165], v[170:171], v[146:147] op_sel_hi:[1,0]
	ds_read_b128 v[170:173], v220 offset:39168
	s_waitcnt vmcnt(22) lgkmcnt(5)
	v_mfma_f32_16x16x32_bf16 v[44:47], v[128:131], v[36:39], v[44:47]
	s_waitcnt lgkmcnt(4)
	v_pk_mul_f32 v[154:155], v[154:155], v[174:175] op_sel_hi:[1,0]
	v_pk_mul_f32 v[152:153], v[152:153], v[174:175] op_sel_hi:[1,0]
	v_add_co_u32_e32 v194, vcc, s0, v144
	v_mfma_f32_16x16x32_bf16 v[36:39], v[124:127], v[36:39], v[52:55]
	s_nop 0
	v_addc_co_u32_e32 v195, vcc, 0, v145, vcc
	s_nop 0
	v_pk_mul_f32 v[54:55], v[134:135], v[146:147] op_sel_hi:[1,0]
	v_pk_mul_f32 v[52:53], v[132:133], v[146:147] op_sel_hi:[1,0]
	s_waitcnt lgkmcnt(0)
	v_mfma_f32_16x16x32_bf16 v[164:167], v[128:131], v[170:173], v[164:167]
	v_mul_f32_e64 v134, v182, v174
	v_mul_f32_e64 v135, v183, v174
	v_pk_mul_f32 v[132:133], v[180:181], v[174:175] op_sel_hi:[1,0]
	ds_read_b128 v[180:183], v220 offset:47872
	v_mfma_f32_16x16x32_bf16 v[52:55], v[124:127], v[170:173], v[52:55]
	ds_read_b128 v[170:173], v220 offset:43584
	v_mov_b32_e32 v146, v175
	v_pk_mul_f32 v[42:43], v[42:43], v[146:147] op_sel_hi:[1,0]
	v_mfma_f32_16x16x32_bf16 v[132:135], v[128:131], v[190:193], v[132:135]
	v_mul_f32_e64 v40, v40, v146
	v_mul_f32_e64 v41, v41, v146
	v_pk_mul_f32 v[34:35], v[34:35], v[146:147] op_sel_hi:[1,0]
	v_pk_mul_f32 v[32:33], v[32:33], v[146:147] op_sel_hi:[1,0]
	v_mfma_f32_16x16x32_bf16 v[152:155], v[124:127], v[190:193], v[152:155]
	ds_read_b128 v[190:193], v220 offset:47936
	s_waitcnt lgkmcnt(2)
	v_mfma_f32_16x16x32_bf16 v[40:43], v[128:131], v[180:183], v[40:43]
	v_mfma_f32_16x16x32_bf16 v[32:35], v[124:127], v[180:183], v[32:35]
	s_waitcnt vmcnt(21)
	v_mfma_f32_16x16x32_bf16 v[44:47], v[112:115], v[92:95], v[44:47]
	s_waitcnt vmcnt(20)
	v_mfma_f32_16x16x32_bf16 v[36:39], v[116:119], v[92:95], v[36:39]
	v_mfma_f32_16x16x32_bf16 v[92:95], v[112:115], v[184:187], v[164:167]
	v_mfma_f32_16x16x32_bf16 v[52:55], v[116:119], v[184:187], v[52:55]
	s_waitcnt lgkmcnt(1)
	v_mfma_f32_16x16x32_bf16 v[124:127], v[112:115], v[170:173], v[132:135]
	v_mfma_f32_16x16x32_bf16 v[128:131], v[116:119], v[170:173], v[152:155]
	s_waitcnt lgkmcnt(0)
	v_mfma_f32_16x16x32_bf16 v[40:43], v[112:115], v[190:193], v[40:43]
	v_mfma_f32_16x16x32_bf16 v[32:35], v[116:119], v[190:193], v[32:35]
	ds_read_b128 v[112:115], v220 offset:34944
	ds_read_b128 v[116:119], v220 offset:35008
	s_waitcnt vmcnt(18) lgkmcnt(1)
	v_mfma_f32_16x16x32_bf16 v[44:47], v[80:83], v[112:115], v[44:47]
	v_mfma_f32_16x16x32_bf16 v[36:39], v[76:79], v[112:115], v[36:39]
	ds_read_b128 v[112:115], v220 offset:39296
	ds_read_b128 v[132:135], v220 offset:39360
	s_waitcnt lgkmcnt(1)
	v_mfma_f32_16x16x32_bf16 v[92:95], v[80:83], v[112:115], v[92:95]
	v_mfma_f32_16x16x32_bf16 v[52:55], v[76:79], v[112:115], v[52:55]
	ds_read_b128 v[112:115], v220 offset:43648
	ds_read_b128 v[170:173], v220 offset:43712
	s_waitcnt lgkmcnt(1)
	v_mfma_f32_16x16x32_bf16 v[124:127], v[80:83], v[112:115], v[124:127]
	v_mfma_f32_16x16x32_bf16 v[112:115], v[76:79], v[112:115], v[128:131]
	s_nop 2
	ds_read_b128 v[128:131], v220 offset:48000
	ds_read_b128 v[228:231], v220 offset:48064
	s_waitcnt lgkmcnt(1)
	v_mfma_f32_16x16x32_bf16 v[80:83], v[80:83], v[128:131], v[40:43]
	v_mfma_f32_16x16x32_bf16 v[232:235], v[76:79], v[128:131], v[32:35]
	s_waitcnt vmcnt(17)
	v_mfma_f32_16x16x32_bf16 v[180:183], v[28:31], v[116:119], v[44:47]
	v_mfma_f32_16x16x32_bf16 v[40:43], v[28:31], v[132:135], v[92:95]
	s_waitcnt vmcnt(16)
	v_mfma_f32_16x16x32_bf16 v[44:47], v[24:27], v[132:135], v[52:55]
	global_load_dwordx4 v[152:155], v[188:189], off
	global_load_dwordx4 v[132:135], v[188:189], off offset:1024
	global_load_dwordx4 v[164:167], v[194:195], off
	global_load_dwordx4 v[144:147], v[194:195], off offset:1024
	global_load_dwordx4 v[76:79], v[188:189], off offset:2048
	global_load_dwordx4 v[128:131], v[188:189], off offset:3072
	global_load_dwordx4 v[92:95], v[194:195], off offset:2048
	global_load_dwordx4 v[52:55], v[194:195], off offset:3072
	ds_read2_b32 v[192:193], v218 offset0:128 offset1:144
	v_mfma_f32_16x16x32_bf16 v[116:119], v[24:27], v[116:119], v[36:39]
	ds_read2_b32 v[190:191], v218 offset0:160 offset1:176
	s_waitcnt lgkmcnt(1)
	v_pk_fma_f32 v[184:185], v[182:183], v[192:193], v[158:159] op_sel_hi:[1,0,1]
	v_mfma_f32_16x16x32_bf16 v[32:35], v[28:31], v[170:173], v[124:127]
	v_fma_f32 v186, v180, v192, v160
	v_fma_f32 v187, v181, v192, v161
	s_nop 1
	v_pk_fma_f32 v[180:181], v[118:119], v[192:193], v[162:163] op_sel_hi:[1,0,1]
	v_pk_fma_f32 v[182:183], v[116:117], v[192:193], v[168:169] op_sel_hi:[1,0,1]
	v_mfma_f32_16x16x32_bf16 v[36:39], v[24:27], v[170:173], v[112:115]
	v_mfma_f32_16x16x32_bf16 v[28:31], v[28:31], v[228:231], v[80:83]
	v_mfma_f32_16x16x32_bf16 v[24:27], v[24:27], v[228:231], v[232:235]
	s_nop 1
	ds_read_b128 v[80:83], v215
	ds_read_b128 v[112:115], v215 offset:64
	ds_read_b128 v[124:127], v215 offset:8448
	ds_read_b128 v[158:161], v215 offset:8512
	ds_read_b128 v[172:175], v215 offset:16896
	ds_read_b128 v[228:231], v215 offset:16960
	ds_read_b128 v[236:239], v215 offset:25344
	ds_read_b128 v[240:243], v215 offset:25408
	s_waitcnt vmcnt(23) lgkmcnt(7)
	v_mfma_f32_16x16x32_bf16 v[116:119], v[140:143], v[80:83], 0
	s_waitcnt vmcnt(22)
; #define LAS __attribute__((address_space(3)))
; __device__ void passB_unit(const Params& p, LAS unsigned char* lds, int u, bool do_store = true) {
;     ...
;         if (kind < 2) {
; #pragma unroll
;             for (int ks = 0; ks < 4; ++ks) { bf16x8 qf[4];
; #pragma unroll
;                 for (int mt = 0; mt < 4; ++mt) qf[mt] = *(const LAS bf16x8*)(Qs + (wt2 * 64 + mt * 16 + fr) * 264 + (kind * 4 + ks) * 32 + fq * 8);
; #pragma unroll
;                 for (int mt = 0; mt < 4; ++mt)
; #pragma unroll
;                     for (int n2 = 0; n2 < 2; ++n2) acc[mt][n2] = __builtin_amdgcn_mfma_f32_16x16x32_bf16(F[q % 3][ks][n2], qf[mt], acc[mt][n2], 0, 0, 0); }
	v_mfma_f32_16x16x32_bf16 v[80:83], v[148:151], v[80:83], 0
	s_waitcnt lgkmcnt(5)
	v_mfma_f32_16x16x32_bf16 v[168:171], v[140:143], v[124:127], 0
	v_mfma_f32_16x16x32_bf16 v[124:127], v[148:151], v[124:127], 0
	s_waitcnt lgkmcnt(3)
	v_mfma_f32_16x16x32_bf16 v[232:235], v[140:143], v[172:175], 0
	v_mfma_f32_16x16x32_bf16 v[172:175], v[148:151], v[172:175], 0
	s_waitcnt lgkmcnt(1)
	v_mfma_f32_16x16x32_bf16 v[140:143], v[140:143], v[236:239], 0
	v_mfma_f32_16x16x32_bf16 v[148:151], v[148:151], v[236:239], 0
	s_waitcnt vmcnt(21)
	v_mfma_f32_16x16x32_bf16 v[116:119], v[120:123], v[112:115], v[116:119]
	s_waitcnt vmcnt(19)
	v_mfma_f32_16x16x32_bf16 v[80:83], v[136:139], v[112:115], v[80:83]
	v_mfma_f32_16x16x32_bf16 v[112:115], v[120:123], v[158:161], v[168:171]
	v_mfma_f32_16x16x32_bf16 v[124:127], v[136:139], v[158:161], v[124:127]
	v_mfma_f32_16x16x32_bf16 v[158:161], v[120:123], v[228:231], v[232:235]
	v_mfma_f32_16x16x32_bf16 v[168:171], v[136:139], v[228:231], v[172:175]
	s_waitcnt lgkmcnt(0)
	v_mfma_f32_16x16x32_bf16 v[120:123], v[120:123], v[240:243], v[140:143]
	v_mfma_f32_16x16x32_bf16 v[136:139], v[136:139], v[240:243], v[148:151]
	s_nop 1
	ds_read_b128 v[140:143], v215 offset:128
	ds_read_b128 v[148:151], v215 offset:192
	s_waitcnt lgkmcnt(1)
	v_mfma_f32_16x16x32_bf16 v[116:119], v[84:87], v[140:143], v[116:119]
	s_waitcnt vmcnt(17)
	v_mfma_f32_16x16x32_bf16 v[80:83], v[96:99], v[140:143], v[80:83]
	ds_read_b128 v[140:143], v215 offset:8576
	ds_read_b128 v[172:175], v215 offset:8640
	s_waitcnt lgkmcnt(1)
	v_mfma_f32_16x16x32_bf16 v[112:115], v[84:87], v[140:143], v[112:115]
	v_mfma_f32_16x16x32_bf16 v[124:127], v[96:99], v[140:143], v[124:127]
	ds_read_b128 v[140:143], v215 offset:17024
	ds_read_b128 v[228:231], v215 offset:17088
	s_waitcnt lgkmcnt(1)
	v_mfma_f32_16x16x32_bf16 v[158:161], v[84:87], v[140:143], v[158:161]
	v_mfma_f32_16x16x32_bf16 v[140:143], v[96:99], v[140:143], v[168:171]
	s_nop 2
	ds_read_b128 v[168:171], v215 offset:25472
	ds_read_b128 v[232:235], v215 offset:25536
	s_waitcnt lgkmcnt(1)
	v_mfma_f32_16x16x32_bf16 v[84:87], v[84:87], v[168:171], v[120:123]
	s_waitcnt vmcnt(16)
	v_mfma_f32_16x16x32_bf16 v[120:123], v[48:51], v[148:151], v[80:83]
	s_nop 2
	v_add_co_u32_e32 v80, vcc, s1, v156
	v_mfma_f32_16x16x32_bf16 v[96:99], v[96:99], v[168:171], v[136:139]
	s_nop 0
	v_addc_co_u32_e32 v81, vcc, 0, v157, vcc
	v_add_co_u32_e32 v204, vcc, s6, v156
	v_mfma_f32_16x16x32_bf16 v[116:119], v[60:63], v[148:151], v[116:119]
	s_nop 0
	v_addc_co_u32_e32 v205, vcc, 0, v157, vcc
	v_add_co_u32_e32 v206, vcc, s7, v156
	v_mfma_f32_16x16x32_bf16 v[112:115], v[60:63], v[172:175], v[112:115]
	s_nop 0
	v_addc_co_u32_e32 v207, vcc, 0, v157, vcc
	v_add_co_u32_e32 v248, vcc, s10, v156
	v_mfma_f32_16x16x32_bf16 v[124:127], v[48:51], v[172:175], v[124:127]
	s_nop 0
	v_addc_co_u32_e32 v249, vcc, 0, v157, vcc
	v_mfma_f32_16x16x32_bf16 v[148:151], v[60:63], v[228:231], v[158:161]
	global_load_dwordx4 v[168:171], v[204:205], off offset:-4096 nt
	global_load_dwordx4 v[172:175], v[248:249], off offset:-4096 nt
	s_nop 0
	global_load_dwordx4 v[156:159], v[80:81], off offset:1024 nt
	global_load_dwordx4 v[136:139], v[80:81], off offset:2048 nt
	v_mfma_f32_16x16x32_bf16 v[228:231], v[48:51], v[228:231], v[140:143]
	s_waitcnt lgkmcnt(0)
	v_mfma_f32_16x16x32_bf16 v[60:63], v[60:63], v[232:235], v[84:87]
	global_load_dwordx4 v[160:163], v[206:207], off offset:1024 nt
	s_nop 0
	global_load_dwordx4 v[80:83], v[80:81], off offset:3072 nt
	s_nop 0
	global_load_dwordx4 v[140:143], v[206:207], off offset:2048 nt
	global_load_dwordx4 v[84:87], v[206:207], off offset:3072 nt
	v_mfma_f32_16x16x32_bf16 v[48:51], v[48:51], v[232:235], v[96:99]
	s_nop 2
	ds_read_b128 v[96:99], v215 offset:256
	ds_read_b128 v[232:235], v215 offset:320
	s_waitcnt vmcnt(23) lgkmcnt(1)
	v_mfma_f32_16x16x32_bf16 v[116:119], v[104:107], v[96:99], v[116:119]
	s_waitcnt vmcnt(21)
	v_mfma_f32_16x16x32_bf16 v[96:99], v[108:111], v[96:99], v[120:123]
	s_nop 2
	ds_read_b128 v[120:123], v215 offset:8704
	ds_read_b128 v[236:239], v215 offset:8768
	s_waitcnt lgkmcnt(1)
	v_mfma_f32_16x16x32_bf16 v[112:115], v[104:107], v[120:123], v[112:115]
	v_mfma_f32_16x16x32_bf16 v[120:123], v[108:111], v[120:123], v[124:127]
	s_nop 2
	ds_read_b128 v[124:127], v215 offset:17152
	ds_read_b128 v[240:243], v215 offset:17216
	s_waitcnt lgkmcnt(1)
	v_mfma_f32_16x16x32_bf16 v[148:151], v[104:107], v[124:127], v[148:151]
	v_mfma_f32_16x16x32_bf16 v[124:127], v[108:111], v[124:127], v[228:231]
	s_nop 2
	ds_read_b128 v[228:231], v215 offset:25600
	ds_read_b128 v[244:247], v215 offset:25664
	s_waitcnt lgkmcnt(1)
	v_mfma_f32_16x16x32_bf16 v[60:63], v[104:107], v[228:231], v[60:63]
	v_mfma_f32_16x16x32_bf16 v[48:51], v[108:111], v[228:231], v[48:51]
	v_mfma_f32_16x16x32_bf16 v[104:107], v[88:91], v[232:235], v[116:119]
	s_waitcnt vmcnt(20)
	v_mfma_f32_16x16x32_bf16 v[96:99], v[100:103], v[232:235], v[96:99]
	v_mfma_f32_16x16x32_bf16 v[108:111], v[88:91], v[236:239], v[112:115]
	v_mfma_f32_16x16x32_bf16 v[112:115], v[100:103], v[236:239], v[120:123]
	v_mfma_f32_16x16x32_bf16 v[116:119], v[88:91], v[240:243], v[148:151]
	v_mfma_f32_16x16x32_bf16 v[120:123], v[100:103], v[240:243], v[124:127]
	s_waitcnt lgkmcnt(0)
	v_mfma_f32_16x16x32_bf16 v[60:63], v[88:91], v[244:247], v[60:63]
	v_mfma_f32_16x16x32_bf16 v[48:51], v[100:103], v[244:247], v[48:51]
	ds_read_b128 v[88:91], v215 offset:384
	ds_read_b128 v[100:103], v215 offset:448
	s_waitcnt vmcnt(19) lgkmcnt(1)
	v_mfma_f32_16x16x32_bf16 v[104:107], v[68:71], v[88:91], v[104:107]
	s_waitcnt vmcnt(17)
; #define LAS __attribute__((address_space(3)))
; __device__ void passB_unit(const Params& p, LAS unsigned char* lds, int u, bool do_store = true) {
;     ...
;             for (int ks = 0; ks < 4; ++ks) { bf16x8 qf[4];
; #pragma unroll
;                 for (int mt = 0; mt < 4; ++mt) qf[mt] = *(const LAS bf16x8*)(Qs + (wt2 * 64 + mt * 16 + fr) * 264 + (kind * 4 + ks) * 32 + fq * 8);
; #pragma unroll
;                 for (int mt = 0; mt < 4; ++mt)
; #pragma unroll
;                     for (int n2 = 0; n2 < 2; ++n2) acc[mt][n2] = __builtin_amdgcn_mfma_f32_16x16x32_bf16(F[q % 3][ks][n2], qf[mt], acc[mt][n2], 0, 0, 0); }
;         } else {
;             const LAS bf16_t* Pp = Pd + d * 128 * 136;
; #pragma unroll
;             for (int mt = 0; mt < 4; ++mt) { const float wv = winA[d * 128 + wt2 * 64 + mt * 16 + fr];
; #pragma unroll
;                 for (int n2 = 0; n2 < 2; ++n2) acc[mt][n2] *= wv; }
; #pragma unroll
;             for (int ks = 0; ks < 4; ++ks) { bf16x8 pf[4];
; #pragma unroll
;                 for (int mt = 0; mt < 4; ++mt) pf[mt] = *(const LAS bf16x8*)(Pp + (wt2 * 64 + mt * 16 + fr) * 136 + ks * 32 + fq * 8);
; #pragma unroll
;                 for (int mt = 0; mt < 4; ++mt)
; #pragma unroll
;                     for (int n2 = 0; n2 < 2; ++n2) acc[mt][n2] = __builtin_amdgcn_mfma_f32_16x16x32_bf16(F[q % 3][ks][n2], pf[mt], acc[mt][n2], 0, 0, 0); }
; #pragma unroll
;             for (int mt = 0; mt < 4; ++mt) { const float iv = invA[d * 128 + wt2 * 64 + mt * 16 + fr];
; #pragma unroll
;                 for (int n2 = 0; n2 < 2; ++n2) hsum[mt][nh * 2 + n2] += acc[mt][n2] * iv; }
	v_mfma_f32_16x16x32_bf16 v[88:91], v[72:75], v[88:91], v[96:99]
	s_nop 2
	ds_read_b128 v[96:99], v215 offset:8832
	ds_read_b128 v[124:127], v215 offset:8896
	s_waitcnt lgkmcnt(1)
	v_mfma_f32_16x16x32_bf16 v[108:111], v[68:71], v[96:99], v[108:111]
	v_mfma_f32_16x16x32_bf16 v[96:99], v[72:75], v[96:99], v[112:115]
	s_nop 2
	ds_read_b128 v[112:115], v215 offset:17280
	ds_read_b128 v[148:151], v215 offset:17344
	s_waitcnt lgkmcnt(1)
	v_mfma_f32_16x16x32_bf16 v[116:119], v[68:71], v[112:115], v[116:119]
	v_mfma_f32_16x16x32_bf16 v[112:115], v[72:75], v[112:115], v[120:123]
	s_nop 2
	ds_read_b128 v[120:123], v215 offset:25728
	ds_read_b128 v[228:231], v215 offset:25792
	s_waitcnt lgkmcnt(1)
	v_mfma_f32_16x16x32_bf16 v[60:63], v[68:71], v[120:123], v[60:63]
	v_mfma_f32_16x16x32_bf16 v[48:51], v[72:75], v[120:123], v[48:51]
	v_mfma_f32_16x16x32_bf16 v[68:71], v[64:67], v[100:103], v[104:107]
	s_waitcnt vmcnt(16)
	v_mfma_f32_16x16x32_bf16 v[72:75], v[56:59], v[100:103], v[88:91]
	v_mfma_f32_16x16x32_bf16 v[88:91], v[64:67], v[124:127], v[108:111]
	v_mfma_f32_16x16x32_bf16 v[232:235], v[56:59], v[124:127], v[96:99]
	v_mfma_f32_16x16x32_bf16 v[236:239], v[64:67], v[148:151], v[116:119]
	v_mfma_f32_16x16x32_bf16 v[148:151], v[56:59], v[148:151], v[112:115]
	global_load_dwordx4 v[120:123], v[204:205], off nt
	s_nop 1
	global_load_dwordx4 v[112:115], v[204:205], off offset:1024 nt
	global_load_dwordx4 v[124:127], v[248:249], off nt
	global_load_dwordx4 v[116:119], v[248:249], off offset:1024 nt
	global_load_dwordx4 v[104:107], v[204:205], off offset:2048 nt
	global_load_dwordx4 v[96:99], v[204:205], off offset:3072 nt
	global_load_dwordx4 v[108:111], v[248:249], off offset:2048 nt
	global_load_dwordx4 v[100:103], v[248:249], off offset:3072 nt
	s_waitcnt lgkmcnt(0)
	v_mfma_f32_16x16x32_bf16 v[60:63], v[64:67], v[228:231], v[60:63]
	v_mfma_f32_16x16x32_bf16 v[48:51], v[56:59], v[228:231], v[48:51]
	ds_read2_b32 v[204:205], v219 offset1:16
	ds_read_b128 v[56:59], v220
	ds_read_b128 v[240:243], v220 offset:4416
	ds_read_b128 v[244:247], v220 offset:8704
	ds_read_b128 v[228:231], v220 offset:4352
	s_waitcnt lgkmcnt(4)
	v_pk_mul_f32 v[64:65], v[68:69], v[204:205] op_sel_hi:[1,0]
	v_pk_mul_f32 v[66:67], v[70:71], v[204:205] op_sel_hi:[1,0]
	v_pk_mul_f32 v[68:69], v[72:73], v[204:205] op_sel_hi:[1,0]
	v_pk_mul_f32 v[70:71], v[74:75], v[204:205] op_sel_hi:[1,0]
	v_mov_b32_e32 v178, v205
	ds_read_b128 v[72:75], v220 offset:64
	ds_read2_b32 v[204:205], v219 offset0:32 offset1:48
	s_waitcnt vmcnt(23) lgkmcnt(5)
	v_mfma_f32_16x16x32_bf16 v[64:67], v[152:155], v[56:59], v[64:67]
	v_mul_f32_e64 v88, v88, v178
	v_mul_f32_e64 v89, v89, v178
	v_pk_mul_f32 v[90:91], v[90:91], v[178:179] op_sel_hi:[1,0]
	s_waitcnt lgkmcnt(0)
	v_pk_mul_f32 v[148:149], v[148:149], v[204:205] op_sel_hi:[1,0]
	s_waitcnt vmcnt(21)
	v_mfma_f32_16x16x32_bf16 v[56:59], v[164:167], v[56:59], v[68:71]
	v_mul_f32_e64 v150, v150, v204
	v_mul_f32_e64 v151, v151, v204
	s_nop 0
	v_pk_mul_f32 v[68:69], v[232:233], v[178:179] op_sel_hi:[1,0]
	v_pk_mul_f32 v[70:71], v[234:235], v[178:179] op_sel_hi:[1,0]
	v_mfma_f32_16x16x32_bf16 v[88:91], v[152:155], v[228:231], v[88:91]
	v_mul_f32_e64 v232, v236, v204
	v_mul_f32_e64 v233, v237, v204
	v_pk_mul_f32 v[234:235], v[238:239], v[204:205] op_sel_hi:[1,0]
	ds_read_b128 v[236:239], v220 offset:13056
	v_mfma_f32_16x16x32_bf16 v[68:71], v[164:167], v[228:231], v[68:71]
	ds_read_b128 v[228:231], v220 offset:8768
	v_mov_b32_e32 v178, v205
	v_pk_mul_f32 v[60:61], v[60:61], v[178:179] op_sel_hi:[1,0]
	v_mfma_f32_16x16x32_bf16 v[232:235], v[152:155], v[244:247], v[232:235]
	v_mul_f32_e64 v62, v62, v178
	v_mul_f32_e64 v63, v63, v178
	v_pk_mul_f32 v[48:49], v[48:49], v[178:179] op_sel_hi:[1,0]
	v_pk_mul_f32 v[50:51], v[50:51], v[178:179] op_sel_hi:[1,0]
	v_mfma_f32_16x16x32_bf16 v[148:151], v[164:167], v[244:247], v[148:151]
	ds_read_b128 v[244:247], v220 offset:13120
	s_waitcnt lgkmcnt(2)
	v_mfma_f32_16x16x32_bf16 v[60:63], v[152:155], v[236:239], v[60:63]
	v_mfma_f32_16x16x32_bf16 v[48:51], v[164:167], v[236:239], v[48:51]
	v_mfma_f32_16x16x32_bf16 v[64:67], v[132:135], v[72:75], v[64:67]
	s_waitcnt vmcnt(20)
	v_mfma_f32_16x16x32_bf16 v[56:59], v[144:147], v[72:75], v[56:59]
	v_mfma_f32_16x16x32_bf16 v[72:75], v[132:135], v[240:243], v[88:91]
	v_mfma_f32_16x16x32_bf16 v[68:71], v[144:147], v[240:243], v[68:71]
	s_waitcnt lgkmcnt(1)
	v_mfma_f32_16x16x32_bf16 v[88:91], v[132:135], v[228:231], v[232:235]
	v_mfma_f32_16x16x32_bf16 v[148:151], v[144:147], v[228:231], v[148:151]
	s_waitcnt lgkmcnt(0)
	v_mfma_f32_16x16x32_bf16 v[60:63], v[132:135], v[244:247], v[60:63]
	v_mfma_f32_16x16x32_bf16 v[48:51], v[144:147], v[244:247], v[48:51]
	ds_read_b128 v[132:135], v220 offset:128
	ds_read_b128 v[144:147], v220 offset:192
	s_waitcnt vmcnt(19) lgkmcnt(1)
	v_mfma_f32_16x16x32_bf16 v[64:67], v[76:79], v[132:135], v[64:67]
	s_waitcnt vmcnt(17)
	v_mfma_f32_16x16x32_bf16 v[56:59], v[92:95], v[132:135], v[56:59]
	ds_read_b128 v[132:135], v220 offset:4480
	ds_read_b128 v[152:155], v220 offset:4544
	s_waitcnt lgkmcnt(1)
	v_mfma_f32_16x16x32_bf16 v[72:75], v[76:79], v[132:135], v[72:75]
	v_mfma_f32_16x16x32_bf16 v[132:135], v[92:95], v[132:135], v[68:71]
	s_nop 2
	ds_read_b128 v[68:71], v220 offset:8832
	ds_read_b128 v[164:167], v220 offset:8896
	s_waitcnt lgkmcnt(1)
	v_mfma_f32_16x16x32_bf16 v[228:231], v[76:79], v[68:71], v[88:91]
	v_mfma_f32_16x16x32_bf16 v[232:235], v[92:95], v[68:71], v[148:151]
	ds_read_b128 v[68:71], v220 offset:13184
	ds_read_b128 v[236:239], v220 offset:13248
	s_waitcnt lgkmcnt(1)
; #define LAS __attribute__((address_space(3)))
; __device__ void passB_unit(const Params& p, LAS unsigned char* lds, int u, bool do_store = true) {
;     ...
;         if (kind < 2) {
; #pragma unroll
;             for (int ks = 0; ks < 4; ++ks) { bf16x8 qf[4];
; #pragma unroll
;                 for (int mt = 0; mt < 4; ++mt) qf[mt] = *(const LAS bf16x8*)(Qs + (wt2 * 64 + mt * 16 + fr) * 264 + (kind * 4 + ks) * 32 + fq * 8);
; #pragma unroll
;                 for (int mt = 0; mt < 4; ++mt)
; #pragma unroll
;                     for (int n2 = 0; n2 < 2; ++n2) acc[mt][n2] = __builtin_amdgcn_mfma_f32_16x16x32_bf16(F[q % 3][ks][n2], qf[mt], acc[mt][n2], 0, 0, 0); }
;     ...
;             for (int ks = 0; ks < 4; ++ks) { bf16x8 pf[4];
; #pragma unroll
;                 for (int mt = 0; mt < 4; ++mt) pf[mt] = *(const LAS bf16x8*)(Pp + (wt2 * 64 + mt * 16 + fr) * 136 + ks * 32 + fq * 8);
; #pragma unroll
;                 for (int mt = 0; mt < 4; ++mt)
; #pragma unroll
;                     for (int n2 = 0; n2 < 2; ++n2) acc[mt][n2] = __builtin_amdgcn_mfma_f32_16x16x32_bf16(F[q % 3][ks][n2], pf[mt], acc[mt][n2], 0, 0, 0); }
; #pragma unroll
;             for (int mt = 0; mt < 4; ++mt) { const float iv = invA[d * 128 + wt2 * 64 + mt * 16 + fr];
; #pragma unroll
;                 for (int n2 = 0; n2 < 2; ++n2) hsum[mt][nh * 2 + n2] += acc[mt][n2] * iv; }
	v_mfma_f32_16x16x32_bf16 v[240:243], v[76:79], v[68:71], v[60:63]
	v_mfma_f32_16x16x32_bf16 v[244:247], v[92:95], v[68:71], v[48:51]
	v_mfma_f32_16x16x32_bf16 v[248:251], v[128:131], v[144:147], v[64:67]
	s_waitcnt vmcnt(16)
	v_mfma_f32_16x16x32_bf16 v[204:207], v[52:55], v[144:147], v[56:59]
	v_mfma_f32_16x16x32_bf16 v[68:71], v[128:131], v[152:155], v[72:75]
	v_mfma_f32_16x16x32_bf16 v[64:67], v[52:55], v[152:155], v[132:135]
	global_load_dwordx4 v[152:155], v[194:195], off offset:-4096
	global_load_dwordx4 v[144:147], v[194:195], off
	s_nop 0
	global_load_dwordx4 v[132:135], v[194:195], off offset:1024
	global_load_dwordx4 v[88:91], v[194:195], off offset:2048
	global_load_dwordx4 v[92:95], v[188:189], off offset:2048
	global_load_dwordx4 v[76:79], v[188:189], off offset:3072
	global_load_dwordx4 v[148:151], v[188:189], off offset:1024
	global_load_dwordx4 v[72:75], v[194:195], off offset:3072
	v_mfma_f32_16x16x32_bf16 v[56:59], v[128:131], v[164:167], v[228:231]
	v_mfma_f32_16x16x32_bf16 v[60:63], v[52:55], v[164:167], v[232:235]
	ds_read2_b32 v[164:165], v218 offset1:16
	s_waitcnt lgkmcnt(0)
	v_pk_fma_f32 v[188:189], v[250:251], v[164:165], 0 op_sel_hi:[1,0,0]
	v_mfma_f32_16x16x32_bf16 v[48:51], v[128:131], v[236:239], v[240:243]
	ds_read2_b32 v[128:129], v218 offset0:32 offset1:48
	v_pk_fma_f32 v[194:195], v[248:249], v[164:165], 0 op_sel_hi:[1,0,0]
	v_pk_fma_f32 v[130:131], v[206:207], v[164:165], 0 op_sel_hi:[1,0,0]
	v_mfma_f32_16x16x32_bf16 v[52:55], v[52:55], v[236:239], v[244:247]
	v_fma_f32 v166, v204, v164, 0
	v_fma_f32 v167, v205, v164, 0
	ds_read_b128 v[204:207], v215
	ds_read_b128 v[232:235], v215 offset:8448
	ds_read_b128 v[240:243], v215 offset:16896
	ds_read_b128 v[248:251], v215 offset:25344
	s_waitcnt vmcnt(23) lgkmcnt(3)
	v_mfma_f32_16x16x32_bf16 v[228:231], v[168:171], v[204:207], 0
	s_waitcnt vmcnt(22)
	v_mfma_f32_16x16x32_bf16 v[204:207], v[172:175], v[204:207], 0
	s_waitcnt lgkmcnt(2)
	v_mfma_f32_16x16x32_bf16 v[236:239], v[168:171], v[232:235], 0
	v_mfma_f32_16x16x32_bf16 v[232:235], v[172:175], v[232:235], 0
	s_waitcnt lgkmcnt(1)
	v_mfma_f32_16x16x32_bf16 v[244:247], v[168:171], v[240:243], 0
	v_mfma_f32_16x16x32_bf16 v[240:243], v[172:175], v[240:243], 0
	s_waitcnt lgkmcnt(0)
	v_mfma_f32_16x16x32_bf16 v[168:171], v[168:171], v[248:251], 0
	v_mfma_f32_16x16x32_bf16 v[172:175], v[172:175], v[248:251], 0
	ds_read_b128 v[248:251], v215 offset:64
	s_waitcnt vmcnt(21) lgkmcnt(0)
	v_mfma_f32_16x16x32_bf16 v[228:231], v[156:159], v[248:251], v[228:231]
	s_waitcnt vmcnt(19)
	v_mfma_f32_16x16x32_bf16 v[204:207], v[160:163], v[248:251], v[204:207]
	ds_read_b128 v[248:251], v215 offset:8512
	s_waitcnt lgkmcnt(0)
	v_mfma_f32_16x16x32_bf16 v[236:239], v[156:159], v[248:251], v[236:239]
	v_mfma_f32_16x16x32_bf16 v[232:235], v[160:163], v[248:251], v[232:235]
	ds_read_b128 v[248:251], v215 offset:16960
	s_waitcnt lgkmcnt(0)
	v_mfma_f32_16x16x32_bf16 v[244:247], v[156:159], v[248:251], v[244:247]
	v_mfma_f32_16x16x32_bf16 v[240:243], v[160:163], v[248:251], v[240:243]
	ds_read_b128 v[248:251], v215 offset:25408
	s_waitcnt lgkmcnt(0)
	v_mfma_f32_16x16x32_bf16 v[156:159], v[156:159], v[248:251], v[168:171]
	s_nop 2
	ds_read_b128 v[168:171], v215 offset:128
	v_mfma_f32_16x16x32_bf16 v[160:163], v[160:163], v[248:251], v[172:175]
	s_waitcnt lgkmcnt(0)
	v_mfma_f32_16x16x32_bf16 v[172:175], v[136:139], v[168:171], v[228:231]
	s_waitcnt vmcnt(17)
	v_mfma_f32_16x16x32_bf16 v[168:171], v[140:143], v[168:171], v[204:207]
	s_nop 2
	ds_read_b128 v[204:207], v215 offset:8576
	s_waitcnt lgkmcnt(0)
	v_mfma_f32_16x16x32_bf16 v[228:231], v[136:139], v[204:207], v[236:239]
	v_mfma_f32_16x16x32_bf16 v[204:207], v[140:143], v[204:207], v[232:235]
	s_nop 2
	ds_read_b128 v[232:235], v215 offset:17024
	s_waitcnt lgkmcnt(0)
	v_mfma_f32_16x16x32_bf16 v[236:239], v[136:139], v[232:235], v[244:247]
	v_mfma_f32_16x16x32_bf16 v[232:235], v[140:143], v[232:235], v[240:243]
	s_nop 2
	ds_read_b128 v[240:243], v215 offset:25472
	s_waitcnt lgkmcnt(0)
	v_mfma_f32_16x16x32_bf16 v[136:139], v[136:139], v[240:243], v[156:159]
	s_nop 2
	ds_read_b128 v[156:159], v215 offset:192
	v_mfma_f32_16x16x32_bf16 v[140:143], v[140:143], v[240:243], v[160:163]
	s_waitcnt lgkmcnt(0)
	v_mfma_f32_16x16x32_bf16 v[160:163], v[80:83], v[156:159], v[172:175]
	s_waitcnt vmcnt(16)
	v_mfma_f32_16x16x32_bf16 v[156:159], v[84:87], v[156:159], v[168:171]
	s_nop 2
	ds_read_b128 v[168:171], v215 offset:8640
	s_waitcnt lgkmcnt(0)
	v_mfma_f32_16x16x32_bf16 v[172:175], v[80:83], v[168:171], v[228:231]
	v_mfma_f32_16x16x32_bf16 v[168:171], v[84:87], v[168:171], v[204:207]
	s_nop 2
	ds_read_b128 v[204:207], v215 offset:17088
	s_waitcnt lgkmcnt(0)
	v_mfma_f32_16x16x32_bf16 v[228:231], v[80:83], v[204:207], v[236:239]
	v_mfma_f32_16x16x32_bf16 v[204:207], v[84:87], v[204:207], v[232:235]
	s_nop 2
	ds_read_b128 v[232:235], v215 offset:25536
	s_waitcnt lgkmcnt(0)
	v_mfma_f32_16x16x32_bf16 v[80:83], v[80:83], v[232:235], v[136:139]
	v_mfma_f32_16x16x32_bf16 v[84:87], v[84:87], v[232:235], v[140:143]
	s_nop 1
	ds_read_b128 v[136:139], v215 offset:256
	ds_read_b128 v[140:143], v215 offset:320
	s_waitcnt vmcnt(15) lgkmcnt(1)
	v_mfma_f32_16x16x32_bf16 v[160:163], v[120:123], v[136:139], v[160:163]
	s_waitcnt vmcnt(13)
	v_mfma_f32_16x16x32_bf16 v[136:139], v[124:127], v[136:139], v[156:159]
	s_nop 2
	ds_read_b128 v[156:159], v215 offset:8704
	ds_read_b128 v[232:235], v215 offset:8768
	s_waitcnt lgkmcnt(1)
	v_mfma_f32_16x16x32_bf16 v[172:175], v[120:123], v[156:159], v[172:175]
	v_mfma_f32_16x16x32_bf16 v[156:159], v[124:127], v[156:159], v[168:171]
	s_nop 2
	ds_read_b128 v[168:171], v215 offset:17152
	ds_read_b128 v[236:239], v215 offset:17216
	s_waitcnt lgkmcnt(1)
; #define LAS __attribute__((address_space(3)))
; __device__ void passB_unit(const Params& p, LAS unsigned char* lds, int u, bool do_store = true) {
;     ...
;         if (kind < 2) {
; #pragma unroll
;             for (int ks = 0; ks < 4; ++ks) { bf16x8 qf[4];
; #pragma unroll
;                 for (int mt = 0; mt < 4; ++mt) qf[mt] = *(const LAS bf16x8*)(Qs + (wt2 * 64 + mt * 16 + fr) * 264 + (kind * 4 + ks) * 32 + fq * 8);
; #pragma unroll
;                 for (int mt = 0; mt < 4; ++mt)
; #pragma unroll
;                     for (int n2 = 0; n2 < 2; ++n2) acc[mt][n2] = __builtin_amdgcn_mfma_f32_16x16x32_bf16(F[q % 3][ks][n2], qf[mt], acc[mt][n2], 0, 0, 0); }
;         } else {
;             const LAS bf16_t* Pp = Pd + d * 128 * 136;
; #pragma unroll
;             for (int mt = 0; mt < 4; ++mt) { const float wv = winA[d * 128 + wt2 * 64 + mt * 16 + fr];
; #pragma unroll
;                 for (int n2 = 0; n2 < 2; ++n2) acc[mt][n2] *= wv; }
; #pragma unroll
;             for (int ks = 0; ks < 4; ++ks) { bf16x8 pf[4];
; #pragma unroll
;                 for (int mt = 0; mt < 4; ++mt) pf[mt] = *(const LAS bf16x8*)(Pp + (wt2 * 64 + mt * 16 + fr) * 136 + ks * 32 + fq * 8);
; #pragma unroll
;                 for (int mt = 0; mt < 4; ++mt)
; #pragma unroll
;                     for (int n2 = 0; n2 < 2; ++n2) acc[mt][n2] = __builtin_amdgcn_mfma_f32_16x16x32_bf16(F[q % 3][ks][n2], pf[mt], acc[mt][n2], 0, 0, 0); }
; #pragma unroll
;             for (int mt = 0; mt < 4; ++mt) { const float iv = invA[d * 128 + wt2 * 64 + mt * 16 + fr];
; #pragma unroll
;                 for (int n2 = 0; n2 < 2; ++n2) hsum[mt][nh * 2 + n2] += acc[mt][n2] * iv; }
	v_mfma_f32_16x16x32_bf16 v[228:231], v[120:123], v[168:171], v[228:231]
	v_mfma_f32_16x16x32_bf16 v[168:171], v[124:127], v[168:171], v[204:207]
	s_nop 2
	ds_read_b128 v[204:207], v215 offset:25600
	ds_read_b128 v[240:243], v215 offset:25664
	s_waitcnt lgkmcnt(1)
	v_mfma_f32_16x16x32_bf16 v[80:83], v[120:123], v[204:207], v[80:83]
	v_mfma_f32_16x16x32_bf16 v[84:87], v[124:127], v[204:207], v[84:87]
	v_mfma_f32_16x16x32_bf16 v[120:123], v[112:115], v[140:143], v[160:163]
	s_waitcnt vmcnt(12)
	v_mfma_f32_16x16x32_bf16 v[124:127], v[116:119], v[140:143], v[136:139]
	v_mfma_f32_16x16x32_bf16 v[136:139], v[112:115], v[232:235], v[172:175]
	v_mfma_f32_16x16x32_bf16 v[140:143], v[116:119], v[232:235], v[156:159]
	v_mfma_f32_16x16x32_bf16 v[156:159], v[112:115], v[236:239], v[228:231]
	v_mfma_f32_16x16x32_bf16 v[160:163], v[116:119], v[236:239], v[168:171]
	s_waitcnt lgkmcnt(0)
	v_mfma_f32_16x16x32_bf16 v[80:83], v[112:115], v[240:243], v[80:83]
	v_mfma_f32_16x16x32_bf16 v[84:87], v[116:119], v[240:243], v[84:87]
	ds_read_b128 v[112:115], v215 offset:384
	ds_read_b128 v[116:119], v215 offset:448
	s_waitcnt vmcnt(11) lgkmcnt(1)
	v_mfma_f32_16x16x32_bf16 v[120:123], v[104:107], v[112:115], v[120:123]
	s_waitcnt vmcnt(9)
	v_mfma_f32_16x16x32_bf16 v[112:115], v[108:111], v[112:115], v[124:127]
	s_nop 2
	ds_read_b128 v[124:127], v215 offset:8832
	ds_read_b128 v[168:171], v215 offset:8896
	s_waitcnt lgkmcnt(1)
	v_mfma_f32_16x16x32_bf16 v[136:139], v[104:107], v[124:127], v[136:139]
	v_mfma_f32_16x16x32_bf16 v[124:127], v[108:111], v[124:127], v[140:143]
	s_nop 2
	ds_read_b128 v[140:143], v215 offset:17280
	ds_read_b128 v[172:175], v215 offset:17344
	s_waitcnt lgkmcnt(1)
	v_mfma_f32_16x16x32_bf16 v[156:159], v[104:107], v[140:143], v[156:159]
	v_mfma_f32_16x16x32_bf16 v[140:143], v[108:111], v[140:143], v[160:163]
	s_nop 2
	ds_read_b128 v[160:163], v215 offset:25728
	ds_read_b128 v[204:207], v215 offset:25792
	s_waitcnt lgkmcnt(1)
	v_mfma_f32_16x16x32_bf16 v[80:83], v[104:107], v[160:163], v[80:83]
	v_mfma_f32_16x16x32_bf16 v[84:87], v[108:111], v[160:163], v[84:87]
	v_mfma_f32_16x16x32_bf16 v[104:107], v[96:99], v[116:119], v[120:123]
	s_waitcnt vmcnt(8)
	v_mfma_f32_16x16x32_bf16 v[108:111], v[100:103], v[116:119], v[112:115]
	v_mfma_f32_16x16x32_bf16 v[112:115], v[96:99], v[168:171], v[136:139]
	s_waitcnt lgkmcnt(0)
	v_mfma_f32_16x16x32_bf16 v[80:83], v[96:99], v[204:207], v[80:83]
	v_mfma_f32_16x16x32_bf16 v[84:87], v[100:103], v[204:207], v[84:87]
	v_mfma_f32_16x16x32_bf16 v[116:119], v[100:103], v[168:171], v[124:127]
	v_mfma_f32_16x16x32_bf16 v[120:123], v[96:99], v[172:175], v[156:159]
	v_mfma_f32_16x16x32_bf16 v[124:127], v[100:103], v[172:175], v[140:143]
	ds_read2_b32 v[136:137], v219 offset0:128 offset1:144
	ds_read_b128 v[96:99], v220 offset:34816
	ds_read2_b32 v[168:169], v219 offset0:160 offset1:176
	ds_read_b128 v[140:143], v220 offset:39232
	s_waitcnt lgkmcnt(3)
	v_pk_mul_f32 v[102:103], v[106:107], v[136:137] op_sel_hi:[1,0]
	v_pk_mul_f32 v[100:101], v[104:105], v[136:137] op_sel_hi:[1,0]
	v_pk_mul_f32 v[106:107], v[110:111], v[136:137] op_sel_hi:[1,0]
	v_pk_mul_f32 v[104:105], v[108:109], v[136:137] op_sel_hi:[1,0]
	v_mov_b32_e32 v156, v137
	ds_read_b128 v[108:111], v220 offset:34880
	ds_read_b128 v[136:139], v220 offset:39168
	s_waitcnt vmcnt(7) lgkmcnt(4)
	v_mfma_f32_16x16x32_bf16 v[100:103], v[152:155], v[96:99], v[100:103]
	v_mul_f32_e64 v114, v114, v156
	v_mul_f32_e64 v115, v115, v156
	v_pk_mul_f32 v[112:113], v[112:113], v[156:157] op_sel_hi:[1,0]
	s_waitcnt vmcnt(6)
	v_mfma_f32_16x16x32_bf16 v[96:99], v[144:147], v[96:99], v[104:107]
	s_nop 2
	v_mul_f32_e64 v106, v118, v156
	v_mul_f32_e64 v107, v119, v156
	v_pk_mul_f32 v[104:105], v[116:117], v[156:157] op_sel_hi:[1,0]
	ds_read_b128 v[156:159], v220 offset:43520
	s_waitcnt lgkmcnt(4)
	v_pk_mul_f32 v[118:119], v[122:123], v[168:169] op_sel_hi:[1,0]
	v_pk_mul_f32 v[116:117], v[120:121], v[168:169] op_sel_hi:[1,0]
	s_waitcnt lgkmcnt(1)
	v_mfma_f32_16x16x32_bf16 v[112:115], v[152:155], v[136:139], v[112:115]
	v_mul_f32_e64 v120, v126, v168
	v_mul_f32_e64 v121, v127, v168
	v_mov_b32_e32 v126, v169
	v_pk_mul_f32 v[82:83], v[82:83], v[126:127] op_sel_hi:[1,0]
	v_mfma_f32_16x16x32_bf16 v[104:107], v[144:147], v[136:139], v[104:107]
	ds_read_b128 v[136:139], v220 offset:43584
	v_pk_mul_f32 v[80:81], v[80:81], v[126:127] op_sel_hi:[1,0]
	v_pk_mul_f32 v[86:87], v[86:87], v[126:127] op_sel_hi:[1,0]
	s_waitcnt lgkmcnt(1)
	v_mfma_f32_16x16x32_bf16 v[160:163], v[152:155], v[156:159], v[116:119]
	v_mul_f32_e64 v84, v84, v126
	v_mul_f32_e64 v85, v85, v126
	s_nop 0
	v_pk_mul_f32 v[118:119], v[124:125], v[168:169] op_sel_hi:[1,0]
	ds_read_b128 v[122:125], v220 offset:47872
	s_waitcnt lgkmcnt(0)
	v_mfma_f32_16x16x32_bf16 v[80:83], v[152:155], v[122:125], v[80:83]
	v_mfma_f32_16x16x32_bf16 v[116:119], v[144:147], v[156:159], v[118:121]
	ds_read_b128 v[156:159], v220 offset:47936
	v_mfma_f32_16x16x32_bf16 v[84:87], v[144:147], v[122:125], v[84:87]
	s_waitcnt vmcnt(1)
	v_mfma_f32_16x16x32_bf16 v[100:103], v[148:151], v[108:111], v[100:103]
	v_mfma_f32_16x16x32_bf16 v[96:99], v[132:135], v[108:111], v[96:99]
	v_mfma_f32_16x16x32_bf16 v[108:111], v[148:151], v[140:143], v[112:115]
	s_nop 2
	ds_read_b128 v[112:115], v220 offset:34944
	ds_read_b128 v[124:127], v220 offset:35008
	v_mfma_f32_16x16x32_bf16 v[104:107], v[132:135], v[140:143], v[104:107]
	v_mfma_f32_16x16x32_bf16 v[116:119], v[132:135], v[136:139], v[116:119]
	s_waitcnt lgkmcnt(2)
; __device__ void passB_unit(const Params& p, LAS unsigned char* lds, int u, bool do_store = true) {
;     ...
;                     for (int n2 = 0; n2 < 2; ++n2) acc[mt][n2] = __builtin_amdgcn_mfma_f32_16x16x32_bf16(F[q % 3][ks][n2], pf[mt], acc[mt][n2], 0, 0, 0); }
; #pragma unroll
;             for (int mt = 0; mt < 4; ++mt) { const float iv = invA[d * 128 + wt2 * 64 + mt * 16 + fr];
; #pragma unroll
;                 for (int n2 = 0; n2 < 2; ++n2) hsum[mt][nh * 2 + n2] += acc[mt][n2] * iv; }
;         }
;     }
;     ...
; #pragma unroll
;     for (int mt = 0; mt < 4; ++mt) { float sv = 0.f;
; #pragma unroll
;         for (int nt = 0; nt < 4; ++nt) { const f32x4 hv = hsum[mt][nt]; sv += (hv[0] * hv[0] + hv[1] * hv[1]) + (hv[2] * hv[2] + hv[3] * hv[3]); }
;         sv += __shfl_xor(sv, 16); sv += __shfl_xor(sv, 32);
;         if (fq == 0) ssP[w4 * 128 + wt2 * 64 + mt * 16 + fr] = sv; }
	v_mfma_f32_16x16x32_bf16 v[84:87], v[132:135], v[156:159], v[84:87]
	s_waitcnt lgkmcnt(1)
	v_mfma_f32_16x16x32_bf16 v[100:103], v[92:95], v[112:115], v[100:103]
	v_mfma_f32_16x16x32_bf16 v[96:99], v[88:91], v[112:115], v[96:99]
	ds_read_b128 v[112:115], v220 offset:39296
	ds_read_b128 v[132:135], v220 offset:39360
	v_mfma_f32_16x16x32_bf16 v[120:123], v[148:151], v[136:139], v[160:163]
	s_waitcnt lgkmcnt(1)
	v_mfma_f32_16x16x32_bf16 v[108:111], v[92:95], v[112:115], v[108:111]
	v_mfma_f32_16x16x32_bf16 v[136:139], v[88:91], v[112:115], v[104:107]
	ds_read_b128 v[140:143], v220 offset:43648
	ds_read_b128 v[144:147], v220 offset:43712
	ds_read2_b32 v[114:115], v218 offset0:128 offset1:144
	v_mfma_f32_16x16x32_bf16 v[100:103], v[76:79], v[124:127], v[100:103]
	v_mfma_f32_16x16x32_bf16 v[80:83], v[148:151], v[156:159], v[80:83]
	ds_read_b128 v[148:151], v220 offset:48000
	ds_read_b128 v[152:155], v220 offset:48064
	s_waitcnt lgkmcnt(2)
	s_nop 3
	v_pk_fma_f32 v[106:107], v[100:101], v[114:115], v[194:195] op_sel_hi:[1,0,1]
	v_pk_fma_f32 v[104:105], v[102:103], v[114:115], v[188:189] op_sel_hi:[1,0,1]
	s_waitcnt vmcnt(0)
	v_mfma_f32_16x16x32_bf16 v[98:101], v[72:75], v[124:127], v[96:99]
	ds_read2_b32 v[112:113], v218 offset0:160 offset1:176
	v_add_u32_e32 v102, s49, v214
	s_waitcnt lgkmcnt(2)
	v_mfma_f32_16x16x32_bf16 v[124:127], v[92:95], v[148:151], v[80:83]
	s_nop 2
	v_mul_f32_e32 v80, v181, v181
	v_pk_fma_f32 v[96:97], v[100:101], v[114:115], v[130:131] op_sel_hi:[1,0,1]
	v_pk_fma_f32 v[100:101], v[98:99], v[114:115], v[166:167] op_sel_hi:[1,0,1]
	v_mul_f32_e32 v98, v187, v187
	v_mul_f32_e32 v99, v185, v185
	v_fmac_f32_e32 v98, v186, v186
	v_fmac_f32_e32 v99, v184, v184
	v_add_f32_e32 v98, v98, v99
	v_mul_f32_e32 v99, v183, v183
	v_fmac_f32_e32 v99, v182, v182
	v_fmac_f32_e32 v80, v180, v180
	v_mul_f32_e32 v81, v107, v107
	v_mul_f32_e32 v82, v105, v105
	v_mfma_f32_16x16x32_bf16 v[120:123], v[92:95], v[140:143], v[120:123]
	v_add_f32_e32 v80, v99, v80
	v_fmac_f32_e32 v81, v106, v106
	v_fmac_f32_e32 v82, v104, v104
	v_mfma_f32_16x16x32_bf16 v[116:119], v[88:91], v[140:143], v[116:119]
	v_add_f32_e32 v80, v98, v80
	v_add_f32_e32 v81, v81, v82
	v_add_f32_e32 v98, v80, v81
	v_mfma_f32_16x16x32_bf16 v[140:143], v[88:91], v[148:151], v[84:87]
	v_add3_u32 v114, v102, v216, v217
	s_nop 1
	v_mul_f32_e32 v84, v101, v101
	v_mul_f32_e32 v85, v97, v97
	v_fmac_f32_e32 v84, v100, v100
	v_fmac_f32_e32 v85, v96, v96
	v_add_f32_e32 v99, v84, v85
	v_add_f32_e32 v98, v99, v98
	v_mfma_f32_16x16x32_bf16 v[88:91], v[76:79], v[132:135], v[108:111]
	s_waitcnt lgkmcnt(0)
	v_mov_b32_e32 v99, v98
	s_nop 1
	v_permlane16_swap_b32_e32 v99, v98
	v_add_f32_e32 v98, v98, v99
	v_mov_b32_e32 v99, v98
	s_nop 1
	v_permlane32_swap_b32_e32 v99, v98
	v_mfma_f32_16x16x32_bf16 v[92:95], v[72:75], v[132:135], v[136:139]
	v_mfma_f32_16x16x32_bf16 v[80:83], v[76:79], v[144:147], v[120:123]
	v_mfma_f32_16x16x32_bf16 v[84:87], v[72:75], v[144:147], v[116:119]
	v_mfma_f32_16x16x32_bf16 v[76:79], v[76:79], v[152:155], v[124:127]
	v_mfma_f32_16x16x32_bf16 v[72:75], v[72:75], v[152:155], v[140:143]
	s_and_saveexec_b64 s[0:1], s[4:5]
	s_cbranch_execz .LBB0_597
	s_waitcnt lgkmcnt(0)
	v_add_f32_e32 v98, v98, v99
	ds_write_b32 v114, v98
.LBB0_597:
	s_or_b64 exec, exec, s[0:1]
	v_mov_b32_e32 v98, v179
	s_waitcnt lgkmcnt(0)
	v_pk_fma_f32 v[22:23], v[22:23], v[98:99], 0 op_sel_hi:[1,0,0]
	v_pk_fma_f32 v[20:21], v[20:21], v[98:99], 0 op_sel_hi:[1,0,0]
	v_pk_fma_f32 v[18:19], v[18:19], v[98:99], 0 op_sel_hi:[1,0,0]
	v_pk_fma_f32 v[16:17], v[16:17], v[98:99], 0 op_sel_hi:[1,0,0]
	v_mov_b32_e32 v102, v193
	v_pk_fma_f32 v[108:109], v[42:43], v[102:103], v[22:23] op_sel_hi:[1,0,1]
	v_pk_fma_f32 v[110:111], v[40:41], v[102:103], v[20:21] op_sel_hi:[1,0,1]
	v_pk_fma_f32 v[98:99], v[46:47], v[102:103], v[18:19] op_sel_hi:[1,0,1]
	v_pk_fma_f32 v[102:103], v[44:45], v[102:103], v[16:17] op_sel_hi:[1,0,1]
	v_mov_b32_e32 v16, v165
	v_pk_fma_f32 v[18:19], v[70:71], v[16:17], 0 op_sel_hi:[1,0,0]
	v_pk_fma_f32 v[20:21], v[68:69], v[16:17], 0 op_sel_hi:[1,0,0]
	v_pk_fma_f32 v[22:23], v[66:67], v[16:17], 0 op_sel_hi:[1,0,0]
	v_pk_fma_f32 v[16:17], v[64:65], v[16:17], 0 op_sel_hi:[1,0,0]
	v_mov_b32_e32 v42, v115
	v_pk_fma_f32 v[44:45], v[90:91], v[42:43], v[18:19] op_sel_hi:[1,0,1]
	v_pk_fma_f32 v[46:47], v[88:89], v[42:43], v[20:21] op_sel_hi:[1,0,1]
	v_pk_fma_f32 v[40:41], v[94:95], v[42:43], v[22:23] op_sel_hi:[1,0,1]
	v_pk_fma_f32 v[42:43], v[92:93], v[42:43], v[16:17] op_sel_hi:[1,0,1]
	v_mul_f32_e32 v16, v111, v111
	v_mul_f32_e32 v17, v109, v109
	v_fmac_f32_e32 v16, v110, v110
	v_fmac_f32_e32 v17, v108, v108
	v_add_f32_e32 v16, v16, v17
	v_mul_f32_e32 v17, v103, v103
	v_mul_f32_e32 v18, v99, v99
	v_fmac_f32_e32 v17, v102, v102
	v_fmac_f32_e32 v18, v98, v98
	v_add_f32_e32 v17, v17, v18
	v_add_f32_e32 v16, v16, v17
	v_mul_f32_e32 v17, v47, v47
	v_mul_f32_e32 v18, v45, v45
	v_fmac_f32_e32 v17, v46, v46
	v_fmac_f32_e32 v18, v44, v44
	v_add_f32_e32 v17, v17, v18
	v_add_f32_e32 v16, v16, v17
	v_mul_f32_e32 v17, v43, v43
	v_mul_f32_e32 v18, v41, v41
	v_fmac_f32_e32 v17, v42, v42
	v_fmac_f32_e32 v18, v40, v40
	v_add_f32_e32 v17, v17, v18
	v_add_f32_e32 v16, v17, v16
	s_waitcnt lgkmcnt(0)
	v_mov_b32_e32 v17, v16
	s_nop 1
	v_permlane16_swap_b32_e32 v17, v16
	v_add_f32_e32 v16, v16, v17
	v_mov_b32_e32 v17, v16
	s_nop 1
	v_permlane32_swap_b32_e32 v17, v16
	s_and_saveexec_b64 s[0:1], s[4:5]
	s_cbranch_execz .LBB0_599
	s_waitcnt lgkmcnt(0)
	v_add_f32_e32 v16, v16, v17
	ds_write_b32 v114, v16 offset:64

; #define EO_LOAD(k) do { _Pragma("unroll") for (int m2 = 0; m2 < 2; ++m2) _Pragma("unroll") for (int bj = 0; bj < 2; ++bj) _Pragma("unroll") for (int n = 0; n < 2; ++n) \
;             xb[(k) & 1][m2][bj][n] = __builtin_nontemporal_load((const f32x4*)(x + (size_t)(row0 + ((k) >> 1) * 128 + (((k) & 1) * 2 + m2) * 16) * 1024 + u.pn * 256 + col0 + bj * 128 + 4 * n)); } while (0)
;     __device__ __forceinline__ void fused(f32x4 (&acc)[2][2][4][2], const Unit& u, int wr, int wc, int fr, int fq, LAS unsigned char* lds) const {
;         const int b = u.pm >> 3;
;         const float* gv = (const float*)(ws + OFF_GATEV) + b * 1024 + u.pn * 256;
;         float* ssq = (float*)(ws + OFF_SSQ);
;         unsigned* cnt = (unsigned*)(ws + OFF_PCNT) + 64 * u.pm;
;         const int row0 = u.pm * 256 + wr * 64 + fr, col0 = wc * 32 + 8 * fq;
;         f32x4 gg[2][2];
; #pragma unroll
;         for (int bj = 0; bj < 2; ++bj)
; #pragma unroll
;             for (int n = 0; n < 2; ++n) gg[bj][n] = *(const f32x4*)(gv + col0 + bj * 128 + 4 * n);
;         f32x4 xb[2][2][2][2];
;     ...
;         EO_LOAD(0);
; #pragma unroll
;         for (int k = 0; k < 4; ++k) { const int ai = k >> 1;
;             if (k + 1 < 4) EO_LOAD(k + 1);
; #pragma unroll
;             for (int m2 = 0; m2 < 2; ++m2) { const int m = (k & 1) * 2 + m2; const size_t row = (size_t)(row0 + ai * 128 + m * 16); float s = 0.f;
; #pragma unroll
;                 for (int bj = 0; bj < 2; ++bj)
; #pragma unroll
;                     for (int n = 0; n < 2; ++n) { const f32x4 o = xb[k & 1][m2][bj][n] + gg[bj][n] * acc[ai][bj][m][n];
;                         acc[ai][bj][m][n] = o; s += (o[0] * o[0] + o[1] * o[1]) + (o[2] * o[2] + o[3] * o[3]); }
;                 s += __shfl_xor(s, 16); s += __shfl_xor(s, 32);
;                 if (fq == 0) __hip_atomic_store(ssq + row * 16 + u.pn * 4 + wc, s, __ATOMIC_RELAXED, __HIP_MEMORY_SCOPE_AGENT); } }
.LBB0_1040:
	s_lshl_b32 s0, s18, 7
	s_and_b32 s0, s0, 0xfffffc00
	s_ashr_i32 s1, s0, 31
	s_lshl_b64 s[0:1], s[0:1], 2
	s_add_u32 s0, s70, s0
	s_addc_u32 s1, s71, s1
	s_lshl_b32 s2, s54, 2
	v_lshlrev_b32_e32 v128, 3, v210
	s_add_u32 s0, s0, s2
	s_addc_u32 s1, s1, 0
	v_lshl_or_b32 v128, s13, 5, v128
	s_add_u32 s4, s70, 0xfc00000
	v_mov_b32_e32 v193, 0
	v_lshlrev_b32_e32 v192, 2, v128
	s_addc_u32 s5, s71, 0
	s_add_i32 s17, s17, s78
	v_lshl_add_u64 v[128:129], s[0:1], 0, v[192:193]
	s_mov_b32 s3, 0xfef9000
	v_add_co_u32_e32 v130, vcc, s3, v128
	v_or_b32_e32 v214, s17, v140
	s_add_u32 s6, s36, s2
	v_addc_co_u32_e32 v131, vcc, 0, v129, vcc
	s_addc_u32 s7, s37, 0
	v_ashrrev_i32_e32 v215, 31, v214
	s_barrier
	global_load_dwordx4 v[136:139], v[130:131], off
	v_lshl_add_u64 v[212:213], s[6:7], 0, v[192:193]
	v_lshlrev_b64 v[130:131], 12, v[214:215]
	s_mov_b64 s[0:1], 0xfef9000
	v_lshl_add_u64 v[130:131], v[212:213], 0, v[130:131]
	global_load_dwordx4 v[200:203], v[130:131], off offset:16 nt
	global_load_dwordx4 v[196:199], v[130:131], off nt
	v_lshl_add_u64 v[128:129], v[128:129], 0, s[0:1]
	global_load_dwordx4 v[140:143], v[128:129], off offset:16
	global_load_dwordx4 v[132:135], v[128:129], off offset:512
	global_load_dwordx4 v[204:207], v[130:131], off offset:512 nt
	global_load_dwordx4 v[228:231], v[130:131], off offset:528 nt
	s_nop 0
	global_load_dwordx4 v[128:131], v[128:129], off offset:528
	v_or_b32_e32 v218, 16, v214
	v_ashrrev_i32_e32 v219, 31, v218
	v_lshlrev_b64 v[144:145], 12, v[218:219]
	v_or_b32_e32 v220, 32, v214
	v_lshl_add_u64 v[144:145], v[212:213], 0, v[144:145]
	v_ashrrev_i32_e32 v221, 31, v220
	global_load_dwordx4 v[184:187], v[144:145], off offset:16 nt
	global_load_dwordx4 v[188:191], v[144:145], off nt
	global_load_dwordx4 v[176:179], v[144:145], off offset:528 nt
	global_load_dwordx4 v[180:183], v[144:145], off offset:512 nt
	v_lshlrev_b64 v[144:145], 12, v[220:221]
	v_or_b32_e32 v216, 48, v214
	v_lshl_add_u64 v[144:145], v[212:213], 0, v[144:145]
	v_ashrrev_i32_e32 v217, 31, v216
	global_load_dwordx4 v[168:171], v[144:145], off offset:16 nt
	global_load_dwordx4 v[172:175], v[144:145], off nt
	global_load_dwordx4 v[160:163], v[144:145], off offset:528 nt
	global_load_dwordx4 v[164:167], v[144:145], off offset:512 nt
	v_lshlrev_b64 v[144:145], 12, v[216:217]
	v_lshl_add_u64 v[148:149], v[212:213], 0, v[144:145]
	global_load_dwordx4 v[152:155], v[148:149], off offset:16 nt
	global_load_dwordx4 v[156:159], v[148:149], off nt
	global_load_dwordx4 v[144:147], v[148:149], off offset:528 nt
	s_nop 0
	global_load_dwordx4 v[148:151], v[148:149], off offset:512 nt
	s_lshl_b32 s3, s34, 4
	s_add_u32 s3, s4, s3
	s_addc_u32 s7, s5, 0
	s_lshl_b32 s6, s13, 2
	s_add_u32 s6, s3, s6
	v_cmp_eq_u32_e64 s[0:1], 0, v210
	s_addc_u32 s7, s7, 0
	v_lshlrev_b64 v[210:211], 6, v[214:215]
	s_waitcnt vmcnt(0)
	v_pk_fma_f32 v[200:201], v[120:121], v[140:141], v[200:201]
	v_pk_fma_f32 v[194:195], v[126:127], v[138:139], v[198:199]
	v_pk_fma_f32 v[196:197], v[124:125], v[136:137], v[196:197]
	v_pk_fma_f32 v[198:199], v[122:123], v[142:143], v[202:203]
	v_pk_fma_f32 v[202:203], v[118:119], v[134:135], v[206:207]
	v_pk_fma_f32 v[204:205], v[116:117], v[132:133], v[204:205]
	v_pk_fma_f32 v[206:207], v[114:115], v[130:131], v[230:231]
	v_pk_fma_f32 v[208:209], v[112:113], v[128:129], v[228:229]
	v_mul_f32_e32 v112, v197, v197
	v_mul_f32_e32 v113, v195, v195
	v_mul_f32_e32 v114, v201, v201
	v_mul_f32_e32 v115, v199, v199
	v_mul_f32_e32 v116, v205, v205
	v_mul_f32_e32 v117, v203, v203
	v_fmac_f32_e32 v112, v196, v196
	v_fmac_f32_e32 v113, v194, v194
	v_fmac_f32_e32 v114, v200, v200
	v_fmac_f32_e32 v115, v198, v198
	v_mul_f32_e32 v118, v209, v209
	v_mul_f32_e32 v119, v207, v207
	v_fmac_f32_e32 v116, v204, v204
	v_fmac_f32_e32 v117, v202, v202
	v_add_f32_e32 v112, v112, v113
	v_add_f32_e32 v113, v114, v115
	v_fmac_f32_e32 v118, v208, v208
	v_fmac_f32_e32 v119, v206, v206
	v_add_f32_e32 v114, v116, v117
	v_add_f32_e32 v112, v112, v113
	v_add_f32_e32 v112, v112, v114
	v_add_f32_e32 v113, v118, v119
	v_add_f32_e32 v112, v112, v113
	s_waitcnt lgkmcnt(0)
	v_mov_b32_e32 v113, v112
	s_nop 1
	v_permlane16_swap_b32_e32 v113, v112
	v_add_f32_e32 v112, v112, v113
	v_mov_b32_e32 v113, v112
	s_nop 1
	v_permlane32_swap_b32_e32 v113, v112
	s_and_saveexec_b64 s[8:9], s[0:1]
	s_cbranch_execz .LBB0_1042
	v_lshl_add_u64 v[114:115], s[6:7], 0, v[210:211]
	s_waitcnt lgkmcnt(0)
	v_add_f32_e32 v112, v112, v113
	global_store_dword v[114:115], v112, off sc1
.LBB0_1042:
	s_or_b64 exec, exec, s[8:9]
	v_pk_fma_f32 v[190:191], v[110:111], v[138:139], v[190:191]
	v_pk_fma_f32 v[188:189], v[108:109], v[136:137], v[188:189]
	v_pk_fma_f32 v[186:187], v[106:107], v[142:143], v[186:187]
	v_pk_fma_f32 v[184:185], v[104:105], v[140:141], v[184:185]
	v_mul_f32_e32 v108, v189, v189
	v_mul_f32_e32 v109, v191, v191
	v_mul_f32_e32 v104, v185, v185
	v_mul_f32_e32 v105, v187, v187
	v_pk_fma_f32 v[182:183], v[102:103], v[134:135], v[182:183]
	v_pk_fma_f32 v[180:181], v[100:101], v[132:133], v[180:181]
	v_fmac_f32_e32 v108, v188, v188
	v_fmac_f32_e32 v109, v190, v190
	v_fmac_f32_e32 v104, v184, v184
	v_fmac_f32_e32 v105, v186, v186
	v_mul_f32_e32 v100, v181, v181
	v_mul_f32_e32 v101, v183, v183
	v_pk_fma_f32 v[178:179], v[98:99], v[130:131], v[178:179]
	v_pk_fma_f32 v[176:177], v[96:97], v[128:129], v[176:177]
	v_add_f32_e32 v108, v108, v109
	v_add_f32_e32 v104, v104, v105
	v_fmac_f32_e32 v100, v180, v180
	v_fmac_f32_e32 v101, v182, v182
	v_mul_f32_e32 v96, v177, v177
	v_mul_f32_e32 v97, v179, v179
	v_add_f32_e32 v104, v108, v104
	v_add_f32_e32 v100, v100, v101
	v_fmac_f32_e32 v96, v176, v176
	v_fmac_f32_e32 v97, v178, v178
	v_add_f32_e32 v100, v104, v100
	v_add_f32_e32 v96, v96, v97
	v_add_f32_e32 v96, v100, v96
	s_waitcnt lgkmcnt(0)
	v_mov_b32_e32 v97, v96
	s_nop 1
	v_permlane16_swap_b32_e32 v97, v96
	v_add_f32_e32 v96, v96, v97
	v_mov_b32_e32 v97, v96
	s_nop 1
	v_permlane32_swap_b32_e32 v97, v96
	s_and_saveexec_b64 s[8:9], s[0:1]
	s_cbranch_execz .LBB0_1044
	v_lshlrev_b64 v[98:99], 6, v[218:219]
	v_lshl_add_u64 v[98:99], s[6:7], 0, v[98:99]
	s_waitcnt lgkmcnt(0)
	v_add_f32_e32 v96, v96, v97
	global_store_dword v[98:99], v96, off sc1
; #define EO_LOAD(k) do { _Pragma("unroll") for (int m2 = 0; m2 < 2; ++m2) _Pragma("unroll") for (int bj = 0; bj < 2; ++bj) _Pragma("unroll") for (int n = 0; n < 2; ++n) \
;             xb[(k) & 1][m2][bj][n] = __builtin_nontemporal_load((const f32x4*)(x + (size_t)(row0 + ((k) >> 1) * 128 + (((k) & 1) * 2 + m2) * 16) * 1024 + u.pn * 256 + col0 + bj * 128 + 4 * n)); } while (0)
;     __device__ __forceinline__ void fused(f32x4 (&acc)[2][2][4][2], const Unit& u, int wr, int wc, int fr, int fq, LAS unsigned char* lds) const {
;     ...
;         for (int k = 0; k < 4; ++k) { const int ai = k >> 1;
;             if (k + 1 < 4) EO_LOAD(k + 1);
; #pragma unroll
;             for (int m2 = 0; m2 < 2; ++m2) { const int m = (k & 1) * 2 + m2; const size_t row = (size_t)(row0 + ai * 128 + m * 16); float s = 0.f;
; #pragma unroll
;                 for (int bj = 0; bj < 2; ++bj)
; #pragma unroll
;                     for (int n = 0; n < 2; ++n) { const f32x4 o = xb[k & 1][m2][bj][n] + gg[bj][n] * acc[ai][bj][m][n];
;                         acc[ai][bj][m][n] = o; s += (o[0] * o[0] + o[1] * o[1]) + (o[2] * o[2] + o[3] * o[3]); }
;                 s += __shfl_xor(s, 16); s += __shfl_xor(s, 32);
;                 if (fq == 0) __hip_atomic_store(ssq + row * 16 + u.pn * 4 + wc, s, __ATOMIC_RELAXED, __HIP_MEMORY_SCOPE_AGENT); } }
.LBB0_1044:
	s_or_b64 exec, exec, s[8:9]
	v_add_u32_e32 v222, 0x80, v214
	v_ashrrev_i32_e32 v223, 31, v222
	s_waitcnt lgkmcnt(0)
	v_lshlrev_b64 v[96:97], 12, v[222:223]
	v_add_u32_e32 v218, 0x90, v214
	v_lshl_add_u64 v[96:97], v[212:213], 0, v[96:97]
	v_ashrrev_i32_e32 v219, 31, v218
	global_load_dwordx4 v[120:123], v[96:97], off offset:16 nt
	global_load_dwordx4 v[124:127], v[96:97], off nt
	global_load_dwordx4 v[112:115], v[96:97], off offset:528 nt
	global_load_dwordx4 v[116:119], v[96:97], off offset:512 nt
	v_lshlrev_b64 v[96:97], 12, v[218:219]
	v_lshl_add_u64 v[100:101], v[212:213], 0, v[96:97]
	global_load_dwordx4 v[104:107], v[100:101], off offset:16 nt
	global_load_dwordx4 v[108:111], v[100:101], off nt
	global_load_dwordx4 v[96:99], v[100:101], off offset:528 nt
	s_nop 0
	global_load_dwordx4 v[100:103], v[100:101], off offset:512 nt
	v_pk_fma_f32 v[174:175], v[94:95], v[138:139], v[174:175]
	v_pk_fma_f32 v[172:173], v[92:93], v[136:137], v[172:173]
	v_pk_fma_f32 v[170:171], v[90:91], v[142:143], v[170:171]
	v_pk_fma_f32 v[168:169], v[88:89], v[140:141], v[168:169]
	v_mul_f32_e32 v92, v173, v173
	v_mul_f32_e32 v93, v175, v175
	v_mul_f32_e32 v88, v169, v169
	v_mul_f32_e32 v89, v171, v171
	v_pk_fma_f32 v[166:167], v[86:87], v[134:135], v[166:167]
	v_pk_fma_f32 v[164:165], v[84:85], v[132:133], v[164:165]
	v_fmac_f32_e32 v92, v172, v172
	v_fmac_f32_e32 v93, v174, v174
	v_fmac_f32_e32 v88, v168, v168
	v_fmac_f32_e32 v89, v170, v170
	v_mul_f32_e32 v84, v165, v165
	v_mul_f32_e32 v85, v167, v167
	v_pk_fma_f32 v[162:163], v[82:83], v[130:131], v[162:163]
	v_pk_fma_f32 v[160:161], v[80:81], v[128:129], v[160:161]
	v_add_f32_e32 v92, v92, v93
	v_add_f32_e32 v88, v88, v89
	v_fmac_f32_e32 v84, v164, v164
	v_fmac_f32_e32 v85, v166, v166
	v_mul_f32_e32 v80, v161, v161
	v_mul_f32_e32 v81, v163, v163
	v_add_f32_e32 v88, v92, v88
	v_add_f32_e32 v84, v84, v85
	v_fmac_f32_e32 v80, v160, v160
	v_fmac_f32_e32 v81, v162, v162
	v_add_f32_e32 v84, v88, v84
	v_add_f32_e32 v80, v80, v81
	v_add_f32_e32 v80, v84, v80
	s_waitcnt lgkmcnt(0)
	v_mov_b32_e32 v81, v80
	s_nop 1
	v_permlane16_swap_b32_e32 v81, v80
	v_add_f32_e32 v80, v80, v81
	v_mov_b32_e32 v81, v80
	s_nop 1
	v_permlane32_swap_b32_e32 v81, v80
	s_and_saveexec_b64 s[8:9], s[0:1]
	s_cbranch_execz .LBB0_1046
	v_lshlrev_b64 v[82:83], 6, v[220:221]
	v_lshl_add_u64 v[82:83], s[6:7], 0, v[82:83]
	s_waitcnt lgkmcnt(0)
	v_add_f32_e32 v80, v80, v81
	global_store_dword v[82:83], v80, off sc1
.LBB0_1046:
	s_or_b64 exec, exec, s[8:9]
	v_pk_fma_f32 v[158:159], v[78:79], v[138:139], v[158:159]
	v_pk_fma_f32 v[156:157], v[76:77], v[136:137], v[156:157]
	v_pk_fma_f32 v[154:155], v[74:75], v[142:143], v[154:155]
	v_pk_fma_f32 v[152:153], v[72:73], v[140:141], v[152:153]
	v_mul_f32_e32 v76, v157, v157
	v_mul_f32_e32 v77, v159, v159
	v_mul_f32_e32 v72, v153, v153
	v_mul_f32_e32 v73, v155, v155
	v_pk_fma_f32 v[150:151], v[70:71], v[134:135], v[150:151]
	v_pk_fma_f32 v[148:149], v[68:69], v[132:133], v[148:149]
	v_fmac_f32_e32 v76, v156, v156
	v_fmac_f32_e32 v77, v158, v158
	v_fmac_f32_e32 v72, v152, v152
	v_fmac_f32_e32 v73, v154, v154
	v_mul_f32_e32 v68, v149, v149
	v_mul_f32_e32 v69, v151, v151
	v_pk_fma_f32 v[146:147], v[66:67], v[130:131], v[146:147]
	v_pk_fma_f32 v[144:145], v[64:65], v[128:129], v[144:145]
	v_add_f32_e32 v76, v76, v77
	v_add_f32_e32 v72, v72, v73
	v_fmac_f32_e32 v68, v148, v148
	v_fmac_f32_e32 v69, v150, v150
	v_mul_f32_e32 v64, v145, v145
	v_mul_f32_e32 v65, v147, v147
	v_add_f32_e32 v72, v76, v72
	v_add_f32_e32 v68, v68, v69
	v_fmac_f32_e32 v64, v144, v144
	v_fmac_f32_e32 v65, v146, v146
	v_add_f32_e32 v68, v72, v68
	v_add_f32_e32 v64, v64, v65
	v_add_f32_e32 v64, v68, v64
	s_waitcnt lgkmcnt(0)
	v_mov_b32_e32 v65, v64
	s_nop 1
	v_permlane16_swap_b32_e32 v65, v64
	v_add_f32_e32 v64, v64, v65
	v_mov_b32_e32 v65, v64
	s_nop 1
	v_permlane32_swap_b32_e32 v65, v64
	s_and_saveexec_b64 s[8:9], s[0:1]
	s_cbranch_execz .LBB0_1048
	v_lshlrev_b64 v[66:67], 6, v[216:217]
	v_lshl_add_u64 v[66:67], s[6:7], 0, v[66:67]
	s_waitcnt lgkmcnt(0)
	v_add_f32_e32 v64, v64, v65
	global_store_dword v[66:67], v64, off sc1
.LBB0_1048:
	s_or_b64 exec, exec, s[8:9]
	v_or_b32_e32 v64, 32, v222
	s_waitcnt lgkmcnt(0)
	v_ashrrev_i32_e32 v65, 31, v64
	v_lshlrev_b64 v[64:65], 12, v[64:65]
	v_add_u32_e32 v214, 0xb0, v214
	v_lshl_add_u64 v[64:65], v[212:213], 0, v[64:65]
	v_ashrrev_i32_e32 v215, 31, v214
	global_load_dwordx4 v[88:91], v[64:65], off offset:16 nt
	global_load_dwordx4 v[92:95], v[64:65], off nt
	global_load_dwordx4 v[80:83], v[64:65], off offset:528 nt
	global_load_dwordx4 v[84:87], v[64:65], off offset:512 nt
	v_lshlrev_b64 v[64:65], 12, v[214:215]
	v_lshl_add_u64 v[68:69], v[212:213], 0, v[64:65]
	global_load_dwordx4 v[72:75], v[68:69], off offset:16 nt
	global_load_dwordx4 v[76:79], v[68:69], off nt
	global_load_dwordx4 v[64:67], v[68:69], off offset:528 nt
	s_nop 0
	global_load_dwordx4 v[68:71], v[68:69], off offset:512 nt
	s_waitcnt vmcnt(14)
	v_pk_fma_f32 v[62:63], v[62:63], v[138:139], v[126:127]
	v_pk_fma_f32 v[60:61], v[60:61], v[136:137], v[124:125]
	v_pk_fma_f32 v[58:59], v[58:59], v[142:143], v[122:123]
	v_pk_fma_f32 v[56:57], v[56:57], v[140:141], v[120:121]
	v_mul_f32_e32 v124, v61, v61
	v_mul_f32_e32 v125, v63, v63
	v_mul_f32_e32 v120, v57, v57
	v_mul_f32_e32 v121, v59, v59
	s_waitcnt vmcnt(12)
	v_pk_fma_f32 v[54:55], v[54:55], v[134:135], v[118:119]
	v_pk_fma_f32 v[52:53], v[52:53], v[132:133], v[116:117]
	v_fmac_f32_e32 v124, v60, v60
	v_fmac_f32_e32 v125, v62, v62
	v_fmac_f32_e32 v120, v56, v56
	v_fmac_f32_e32 v121, v58, v58
	v_mul_f32_e32 v116, v53, v53
	v_mul_f32_e32 v117, v55, v55
	v_pk_fma_f32 v[50:51], v[50:51], v[130:131], v[114:115]
	v_pk_fma_f32 v[48:49], v[48:49], v[128:129], v[112:113]
	v_add_f32_e32 v124, v124, v125
	v_add_f32_e32 v120, v120, v121
	v_fmac_f32_e32 v116, v52, v52
	v_fmac_f32_e32 v117, v54, v54
	v_mul_f32_e32 v112, v49, v49
	v_mul_f32_e32 v113, v51, v51
	v_add_f32_e32 v120, v124, v120
	v_add_f32_e32 v116, v116, v117
	v_fmac_f32_e32 v112, v48, v48
	v_fmac_f32_e32 v113, v50, v50
	v_add_f32_e32 v116, v120, v116
	v_add_f32_e32 v112, v112, v113
	v_add_f32_e32 v112, v116, v112
	s_waitcnt lgkmcnt(0)
	v_mov_b32_e32 v113, v112
	s_nop 1
	v_permlane16_swap_b32_e32 v113, v112
	v_add_f32_e32 v112, v112, v113
	v_mov_b32_e32 v113, v112
	s_nop 1
	v_permlane32_swap_b32_e32 v113, v112
	s_and_saveexec_b64 s[8:9], s[0:1]
	s_cbranch_execz .LBB0_1050
	v_lshlrev_b64 v[114:115], 6, v[222:223]
	v_lshl_add_u64 v[114:115], s[6:7], 0, v[114:115]
	s_waitcnt lgkmcnt(0)
	v_add_f32_e32 v112, v112, v113
	global_store_dword v[114:115], v112, off sc1
; #define EO_LOAD(k) do { _Pragma("unroll") for (int m2 = 0; m2 < 2; ++m2) _Pragma("unroll") for (int bj = 0; bj < 2; ++bj) _Pragma("unroll") for (int n = 0; n < 2; ++n) \
;             xb[(k) & 1][m2][bj][n] = __builtin_nontemporal_load((const f32x4*)(x + (size_t)(row0 + ((k) >> 1) * 128 + (((k) & 1) * 2 + m2) * 16) * 1024 + u.pn * 256 + col0 + bj * 128 + 4 * n)); } while (0)
;     __device__ __forceinline__ void fused(f32x4 (&acc)[2][2][4][2], const Unit& u, int wr, int wc, int fr, int fq, LAS unsigned char* lds) const {
;     ...
;         for (int k = 0; k < 4; ++k) { const int ai = k >> 1;
;             if (k + 1 < 4) EO_LOAD(k + 1);
; #pragma unroll
;             for (int m2 = 0; m2 < 2; ++m2) { const int m = (k & 1) * 2 + m2; const size_t row = (size_t)(row0 + ai * 128 + m * 16); float s = 0.f;
; #pragma unroll
;                 for (int bj = 0; bj < 2; ++bj)
; #pragma unroll
;                     for (int n = 0; n < 2; ++n) { const f32x4 o = xb[k & 1][m2][bj][n] + gg[bj][n] * acc[ai][bj][m][n];
;                         acc[ai][bj][m][n] = o; s += (o[0] * o[0] + o[1] * o[1]) + (o[2] * o[2] + o[3] * o[3]); }
;                 s += __shfl_xor(s, 16); s += __shfl_xor(s, 32);
;                 if (fq == 0) __hip_atomic_store(ssq + row * 16 + u.pn * 4 + wc, s, __ATOMIC_RELAXED, __HIP_MEMORY_SCOPE_AGENT); } }
.LBB0_1050:
	s_or_b64 exec, exec, s[8:9]
	s_waitcnt vmcnt(10)
	v_pk_fma_f32 v[46:47], v[46:47], v[138:139], v[110:111]
	v_pk_fma_f32 v[44:45], v[44:45], v[136:137], v[108:109]
	v_pk_fma_f32 v[42:43], v[42:43], v[142:143], v[106:107]
	v_pk_fma_f32 v[40:41], v[40:41], v[140:141], v[104:105]
	v_mul_f32_e32 v108, v45, v45
	v_mul_f32_e32 v109, v47, v47
	v_mul_f32_e32 v104, v41, v41
	v_mul_f32_e32 v105, v43, v43
	s_waitcnt vmcnt(8)
	v_pk_fma_f32 v[38:39], v[38:39], v[134:135], v[102:103]
	v_pk_fma_f32 v[36:37], v[36:37], v[132:133], v[100:101]
	v_fmac_f32_e32 v108, v44, v44
	v_fmac_f32_e32 v109, v46, v46
	v_fmac_f32_e32 v104, v40, v40
	v_fmac_f32_e32 v105, v42, v42
	v_mul_f32_e32 v100, v37, v37
	v_mul_f32_e32 v101, v39, v39
	v_pk_fma_f32 v[34:35], v[34:35], v[130:131], v[98:99]
	v_pk_fma_f32 v[32:33], v[32:33], v[128:129], v[96:97]
	v_add_f32_e32 v108, v108, v109
	v_add_f32_e32 v104, v104, v105
	v_fmac_f32_e32 v100, v36, v36
	v_fmac_f32_e32 v101, v38, v38
	v_mul_f32_e32 v96, v33, v33
	v_mul_f32_e32 v97, v35, v35
	v_add_f32_e32 v104, v108, v104
	v_add_f32_e32 v100, v100, v101
	v_fmac_f32_e32 v96, v32, v32
	v_fmac_f32_e32 v97, v34, v34
	v_add_f32_e32 v100, v104, v100
	v_add_f32_e32 v96, v96, v97
	v_add_f32_e32 v96, v100, v96
	s_waitcnt lgkmcnt(0)
	v_mov_b32_e32 v97, v96
	s_nop 1
	v_permlane16_swap_b32_e32 v97, v96
	v_add_f32_e32 v96, v96, v97
	v_mov_b32_e32 v97, v96
	s_nop 1
	v_permlane32_swap_b32_e32 v97, v96
	s_and_saveexec_b64 s[8:9], s[0:1]
	s_cbranch_execz .LBB0_1052
	v_lshlrev_b64 v[98:99], 6, v[218:219]
	v_lshl_add_u64 v[98:99], s[6:7], 0, v[98:99]
	s_waitcnt lgkmcnt(0)
	v_add_f32_e32 v96, v96, v97
	global_store_dword v[98:99], v96, off sc1
.LBB0_1052:
	s_or_b64 exec, exec, s[8:9]
	s_waitcnt vmcnt(6)
	v_pk_fma_f32 v[30:31], v[30:31], v[138:139], v[94:95]
	v_pk_fma_f32 v[28:29], v[28:29], v[136:137], v[92:93]
	v_pk_fma_f32 v[26:27], v[26:27], v[142:143], v[90:91]
	v_pk_fma_f32 v[24:25], v[24:25], v[140:141], v[88:89]
	v_mul_f32_e32 v92, v29, v29
	v_mul_f32_e32 v93, v31, v31
	v_mul_f32_e32 v88, v25, v25
	v_mul_f32_e32 v89, v27, v27
	s_waitcnt vmcnt(4)
	v_pk_fma_f32 v[22:23], v[22:23], v[134:135], v[86:87]
	v_pk_fma_f32 v[20:21], v[20:21], v[132:133], v[84:85]
	v_fmac_f32_e32 v92, v28, v28
	v_fmac_f32_e32 v93, v30, v30
	v_fmac_f32_e32 v88, v24, v24
	v_fmac_f32_e32 v89, v26, v26
	v_mul_f32_e32 v84, v21, v21
	v_mul_f32_e32 v85, v23, v23
	v_pk_fma_f32 v[18:19], v[18:19], v[130:131], v[82:83]
	v_pk_fma_f32 v[16:17], v[16:17], v[128:129], v[80:81]
	v_add_f32_e32 v92, v92, v93
	v_add_f32_e32 v88, v88, v89
	v_fmac_f32_e32 v84, v20, v20
	v_fmac_f32_e32 v85, v22, v22
	v_mul_f32_e32 v80, v17, v17
	v_mul_f32_e32 v81, v19, v19
	v_add_f32_e32 v88, v92, v88
	v_add_f32_e32 v84, v84, v85
	v_fmac_f32_e32 v80, v16, v16
	v_fmac_f32_e32 v81, v18, v18
	v_add_f32_e32 v84, v88, v84
	v_add_f32_e32 v80, v80, v81
	v_add_f32_e32 v80, v84, v80
	s_waitcnt lgkmcnt(0)
	v_mov_b32_e32 v81, v80
	s_nop 1
	v_permlane16_swap_b32_e32 v81, v80
	v_add_f32_e32 v80, v80, v81
	v_mov_b32_e32 v81, v80
	s_nop 1
	v_permlane32_swap_b32_e32 v81, v80
	s_and_saveexec_b64 s[8:9], s[0:1]
	s_cbranch_execz .LBB0_1054
	v_lshl_add_u64 v[82:83], s[6:7], 0, v[210:211]
	s_waitcnt lgkmcnt(0)
	v_add_f32_e32 v84, v80, v81
	v_add_co_u32_e32 v80, vcc, 0x2000, v82
	s_nop 1
	v_addc_co_u32_e32 v81, vcc, 0, v83, vcc
	global_store_dword v[80:81], v84, off offset:2048 sc1
.LBB0_1054:
	s_or_b64 exec, exec, s[8:9]
	s_waitcnt vmcnt(2)
	v_pk_fma_f32 v[78:79], v[14:15], v[138:139], v[78:79]
	v_pk_fma_f32 v[76:77], v[12:13], v[136:137], v[76:77]
	v_pk_fma_f32 v[74:75], v[10:11], v[142:143], v[74:75]
	v_pk_fma_f32 v[72:73], v[8:9], v[140:141], v[72:73]
	v_mul_f32_e32 v12, v77, v77
	v_mul_f32_e32 v13, v79, v79
	v_mul_f32_e32 v8, v73, v73
	v_mul_f32_e32 v9, v75, v75
	s_waitcnt vmcnt(0)
	v_pk_fma_f32 v[70:71], v[6:7], v[134:135], v[70:71]
	v_pk_fma_f32 v[68:69], v[4:5], v[132:133], v[68:69]
	v_fmac_f32_e32 v12, v76, v76
	v_fmac_f32_e32 v13, v78, v78
	v_fmac_f32_e32 v8, v72, v72
	v_fmac_f32_e32 v9, v74, v74
	v_mul_f32_e32 v4, v69, v69
	v_mul_f32_e32 v5, v71, v71
	v_pk_fma_f32 v[66:67], v[2:3], v[130:131], v[66:67]
	v_pk_fma_f32 v[64:65], v[0:1], v[128:129], v[64:65]
	v_add_f32_e32 v12, v12, v13
	v_add_f32_e32 v8, v8, v9
	v_fmac_f32_e32 v4, v68, v68
	v_fmac_f32_e32 v5, v70, v70
	v_mul_f32_e32 v0, v65, v65
	v_mul_f32_e32 v1, v67, v67
	v_add_f32_e32 v8, v12, v8
	v_add_f32_e32 v4, v4, v5
	v_fmac_f32_e32 v0, v64, v64
	v_fmac_f32_e32 v1, v66, v66
	v_add_f32_e32 v4, v8, v4
	v_add_f32_e32 v0, v0, v1
	v_add_f32_e32 v0, v4, v0
	s_waitcnt lgkmcnt(0)
	v_mov_b32_e32 v1, v0
	s_nop 1
	v_permlane16_swap_b32_e32 v1, v0
	v_add_f32_e32 v0, v0, v1
	v_mov_b32_e32 v1, v0
	s_nop 1
	v_permlane32_swap_b32_e32 v1, v0
	s_and_saveexec_b64 s[8:9], s[0:1]
	s_cbranch_execz .LBB0_1056
	v_lshlrev_b64 v[2:3], 6, v[214:215]
	v_lshl_add_u64 v[2:3], s[6:7], 0, v[2:3]
	s_waitcnt lgkmcnt(0)
	v_add_f32_e32 v0, v0, v1
	global_store_dword v[2:3], v0, off sc1
